# GEMM k-steps of up and gemm_in: the stage's whole last sub-step (4 MFMAs) runs after the stage barrier in the shadow of the LDS-DMA issue block, second A fragment in its own registers
# speedup vs baseline: 1.0058x; 1.0052x over previous
; #define WAIT_V0() asm volatile("s_waitcnt vmcnt(0)" ::: "memory")
; DI int glds_row(int i) { const int tid = ltid(); return ((tid >> 6) * 4 + i) * 8 + ((tid & 63) >> 3); }
; DI int glds_chunk(int row) { return (ltid() & 7) ^ ((row >> 1) & 7); }
; DI void gemm_core(char* smem, int nk, const char* Ab, const char* Bb, const unsigned (&aoff)[4], const unsigned (&boff)[4],
;                   f32x16 (&acc)[2][2]) {
;     ...
;   auto stage = [&](int buf, int kt) __attribute__((always_inline)) {
;     const char* ak = Ab + kt * 128;
;     const char* bk = Bb + kt * 128;
;     char* sa = smem + buf * STAGE_B + w * 4096;
; #pragma unroll
;     for (int i = 0; i < 4; ++i) {
;       __builtin_amdgcn_global_load_lds((const unsigned*)(ak + aoff[i]), (unsigned*)(sa + i * 1024), 16, 0, 0);
;       __builtin_amdgcn_global_load_lds((const unsigned*)(bk + boff[i]), (unsigned*)(sa + 16384 + i * 1024), 16, 0, 0);
;     }
;   };
;   stage(0, 0);
;   WAIT_V0();
;   __syncthreads();
; DI void phase_up(const Params& P, int layer, char* smem) {
;     ...
;   for (int t0 = blockIdx.x; t0 < MT * NT; t0 += gridDim.x) {
;     const int tl = xcd_tile(t0, MT * NT) - (t0 & 7) * ((MT * NT) >> 3);
;     const int mt = (t0 & 1) * 131 + tl / 11, nt = ((t0 & 7) >> 1) * 11 + tl % 11;
;     const int b = mt / 131, i = mt % 131;
;     const int tb0 = i * 126 - 2;
;     unsigned aoff[4], boff[4];
;     const char* Abase = (const char*)(hn + (size_t)b * S_ * 1024);
;     const unsigned zoff = (unsigned)((P.ws + OFF_ZPAGE) - Abase);
; #pragma unroll
;     for (int q = 0; q < 4; ++q) {
;       const int r = glds_row(q), ch = glds_chunk(r);
;       const int tb = tb0 + r;
;       const bool ok = (tb >= 0) && (tb < S_);
;       aoff[q] = ok ? (unsigned)((tb * 1024 + ch * 8) * 2) : zoff;
;       const int wr = (r < 64) ? (nt * 64 + r) : (DFF + nt * 64 + r - 64);
;       boff[q] = (unsigned)((wr * 1024 + ch * 8) * 2);
;     }
.LBB0_25:
	s_ashr_i32 s18, s2, 3
	s_and_b32 s19, s18, 0xffffffc0
	s_lshl_b32 s20, s18, 1
	s_bfe_u32 s21, s18, 0x10005
	s_and_b32 s20, s20, 62
	s_or_b32 s19, s21, s19
	s_or_b32 s19, s19, s20
	s_or_b32 s20, s18, 63
	s_cmpk_lt_i32 s20, 0x5a1
	s_cselect_b32 s18, s19, s18
	s_bitcmp1_b32 s2, 0
	s_mul_hi_i32 s20, s18, 0x2e8ba2e9
	s_cselect_b32 s19, 0x83, 0
	s_lshr_b32 s21, s20, 31
	s_ashr_i32 s20, s20, 1
	s_add_i32 s21, s20, s21
	s_add_i32 s20, s21, s19
	s_bfe_u32 s19, s2, 0x20001
	s_mul_i32 s21, s21, 11
	s_mul_i32 s19, s19, 11
	s_sub_i32 s18, s18, s21
	s_add_i32 s21, s18, s19
	s_mul_hi_i32 s18, s20, 0x3e88cb3d
	s_lshr_b32 s19, s18, 31
	s_ashr_i32 s18, s18, 5
	v_mov_b32_e32 v0, v161
	s_add_i32 s68, s18, s19
	s_mul_i32 s18, s68, 0x83
	v_ashrrev_i32_e32 v1, 1, v0
	v_lshrrev_b32_e32 v2, 3, v0
	v_bfe_u32 v0, v0, 3, 3
	s_movk_i32 s3, 0xffe0
	s_sub_i32 s28, s20, s18
	v_and_or_b32 v0, v1, s3, v0
	v_mov_b32_e32 v1, v161
	s_mulk_i32 s28, 0x7e
	s_ashr_i32 s69, s68, 31
	v_bfe_u32 v2, v2, 1, 2
	s_add_i32 s29, s28, -2
	s_lshl_b64 s[22:23], s[68:69], 25
	v_xor_b32_e32 v1, v2, v1
	s_add_u32 s18, s84, s22
	v_lshlrev_b32_e32 v1, 4, v1
	s_addc_u32 s19, s85, s23
	s_sub_i32 s22, 0x1b508000, s22
	s_lshl_b32 s21, s21, 6
	v_add_u32_e32 v2, s29, v0
	v_and_b32_e32 v1, 0x70, v1
	s_movk_i32 s3, 0x4000
	s_add_i32 s23, s21, 0xac0
	v_lshl_or_b32 v3, v2, 11, v1
	v_mov_b32_e32 v4, s22
	v_cmp_gt_u32_e32 vcc, s3, v2
	v_mov_b32_e32 v5, s21
	v_mov_b32_e32 v12, v161
	v_cndmask_b32_e32 v136, v4, v3, vcc
	v_mov_b32_e32 v3, s23
	v_cmp_gt_i32_e32 vcc, 64, v0
	v_lshl_add_u64 v[64:65], s[18:19], 0, v[136:137]
	s_mov_b64 s[4:5], 0x100
	v_cndmask_b32_e32 v2, v3, v5, vcc
	v_add_u32_e32 v0, v2, v0
	v_lshl_or_b32 v76, v0, 11, v1
	v_mov_b32_e32 v0, v161
	s_mov_b64 s[6:7], 0x780
	v_ashrrev_i32_e32 v1, 1, v0
	v_and_b32_e32 v1, 0xffffffe0, v1
	v_bfe_u32 v0, v0, 3, 3
	v_or3_b32 v1, v1, v0, 8
	v_mov_b32_e32 v0, v161
	v_lshrrev_b32_e32 v2, 1, v1
	v_xor_b32_e32 v0, v2, v0
	v_lshlrev_b32_e32 v0, 4, v0
	v_add_u32_e32 v2, s29, v1
	v_and_b32_e32 v6, 0x70, v0
	v_lshl_or_b32 v0, v2, 11, v6
	v_cmp_gt_u32_e32 vcc, s3, v2
	s_nop 1
	v_cndmask_b32_e32 v0, v4, v0, vcc
	v_cmp_gt_i32_e32 vcc, 64, v1
	s_nop 1
	v_cndmask_b32_e32 v2, v3, v5, vcc
	v_add_u32_e32 v1, v2, v1
	v_lshl_or_b32 v77, v1, 11, v6
	v_mov_b32_e32 v1, v161
	s_nop 0
	v_ashrrev_i32_e32 v2, 1, v1
	v_and_b32_e32 v2, 0xffffffe0, v2
	v_lshrrev_b32_e32 v6, 3, v1
	v_bfe_u32 v1, v1, 3, 3
	v_or3_b32 v1, v2, v1, 16
	v_mov_b32_e32 v2, v161
	v_bfe_u32 v6, v6, 1, 2
	v_xor_b32_e32 v2, v6, v2
	v_lshlrev_b32_e32 v2, 4, v2
	v_add_u32_e32 v6, s29, v1
	v_and_b32_e32 v7, 0x70, v2
	v_lshl_or_b32 v2, v6, 11, v7
	v_cmp_gt_u32_e32 vcc, s3, v6
	s_nop 1
	v_cndmask_b32_e32 v2, v4, v2, vcc
	v_cmp_gt_i32_e32 vcc, 64, v1
	s_nop 1
	v_cndmask_b32_e32 v6, v3, v5, vcc
	v_add_u32_e32 v1, v6, v1
	v_lshl_or_b32 v78, v1, 11, v7
	v_mov_b32_e32 v1, v161
	s_nop 0
	v_ashrrev_i32_e32 v6, 1, v1
	v_and_b32_e32 v6, 0xffffffe0, v6
	v_bfe_u32 v1, v1, 3, 3
	v_or3_b32 v1, v6, v1, 24
	v_mov_b32_e32 v6, v161
	v_lshrrev_b32_e32 v7, 1, v1
	v_xor_b32_e32 v6, v7, v6
	v_lshlrev_b32_e32 v6, 4, v6
	v_add_u32_e32 v7, s29, v1
	v_and_b32_e32 v6, 0x70, v6
	v_lshl_or_b32 v8, v7, 11, v6
	v_cmp_gt_u32_e32 vcc, s3, v7
	s_mov_b32 s3, 0x1ffffc0
	v_bfe_u32 v86, v12, 1, 3
	v_cndmask_b32_e32 v4, v4, v8, vcc
	v_cmp_gt_i32_e32 vcc, 64, v1
	v_bfe_u32 v117, v12, 5, 1
	s_nop 0
	v_cndmask_b32_e32 v3, v3, v5, vcc
	v_add_u32_e32 v1, v3, v1
	v_lshl_or_b32 v84, v1, 11, v6
	v_and_b32_e32 v1, 31, v12
	v_lshrrev_b32_e32 v5, 1, v12
	v_and_or_b32 v1, v5, s3, v1
	v_lshlrev_b32_e32 v87, 7, v1
	v_lshlrev_b32_e32 v1, 6, v12
	v_and_b32_e32 v97, 0xfffff000, v1
	v_add_u32_e32 v96, 0x4000, v97
	v_readfirstlane_b32 s84, v97
	s_mov_b32 m0, s84
	v_readfirstlane_b32 s85, v96
	v_or_b32_e32 v98, 0x400, v97
	global_load_lds_dwordx4 v136, s[18:19]
	s_mov_b32 m0, s85
	v_readfirstlane_b32 s86, v98
	v_add_u32_e32 v99, 0x4400, v97
	global_load_lds_dwordx4 v76, s[0:1]
	s_mov_b32 m0, s86
	v_readfirstlane_b32 s87, v99
	v_or_b32_e32 v100, 0x800, v97
	global_load_lds_dwordx4 v0, s[18:19]
	s_mov_b32 m0, s87
	v_readfirstlane_b32 s88, v100
	v_add_u32_e32 v101, 0x4800, v97
	v_lshrrev_b32_e32 v3, 5, v12
	global_load_lds_dwordx4 v77, s[0:1]
	s_mov_b32 m0, s88
	v_readfirstlane_b32 s89, v101
	v_or_b32_e32 v102, 0xc00, v97
	v_bitop3_b32 v3, v3, v86, 1 bitop3:0x6c
	global_load_lds_dwordx4 v2, s[18:19]
	s_mov_b32 m0, s89
	v_readfirstlane_b32 s90, v102
	v_add_u32_e32 v103, 0x4c00, v97
	v_lshlrev_b32_e32 v6, 4, v3
	v_mov_b32_e32 v1, v137
	v_mov_b32_e32 v3, v137
	global_load_lds_dwordx4 v78, s[0:1]
	v_mov_b32_e32 v5, v137
	s_mov_b32 m0, s90
	v_readfirstlane_b32 s91, v103
	v_add_u32_e32 v89, 0x8000, v97
	v_lshl_add_u64 v[66:67], s[18:19], 0, v[0:1]
	v_lshl_add_u64 v[68:69], s[18:19], 0, v[2:3]
	v_lshl_add_u64 v[70:71], s[18:19], 0, v[4:5]
	global_load_lds_dwordx4 v4, s[18:19]
	s_mov_b32 m0, s91
	v_add_u32_e32 v88, 0xc000, v97
	v_readfirstlane_b32 s18, v89
	global_load_lds_dwordx4 v84, s[0:1]
	v_lshl_add_u64 v[0:1], v[64:65], 0, s[94:95]
	s_mov_b32 m0, s18
	v_readfirstlane_b32 s19, v88
	v_add_u32_e32 v90, 0x8400, v97
	global_load_lds_dwordx4 v[0:1], off
	s_mov_b32 m0, s19
	v_readfirstlane_b32 s22, v90
	v_add_u32_e32 v91, 0xc400, v97
	global_load_lds_dwordx4 v76, s[14:15]
	v_lshl_add_u64 v[0:1], v[66:67], 0, s[94:95]
	s_mov_b32 m0, s22
	v_readfirstlane_b32 s23, v91
	v_add_u32_e32 v92, 0x8800, v97
	global_load_lds_dwordx4 v[0:1], off
	s_mov_b32 m0, s23
	v_readfirstlane_b32 s29, v92
	v_add_u32_e32 v93, 0xc800, v97
	global_load_lds_dwordx4 v77, s[14:15]
	v_lshl_add_u64 v[0:1], v[68:69], 0, s[94:95]
	s_mov_b32 m0, s29
	v_readfirstlane_b32 s69, v93
	v_add_u32_e32 v94, 0x8c00, v97
	global_load_lds_dwordx4 v[0:1], off
	s_mov_b32 m0, s69
	v_readfirstlane_b32 s70, v94
	v_add_u32_e32 v95, 0xcc00, v97
	global_load_lds_dwordx4 v78, s[14:15]
	v_lshl_add_u64 v[0:1], v[70:71], 0, s[94:95]
	s_mov_b32 m0, s70
	v_readfirstlane_b32 s71, v95
	global_load_lds_dwordx4 v[0:1], off
	s_mov_b32 m0, s71
	v_or_b32_e32 v79, v87, v6
	global_load_lds_dwordx4 v84, s[14:15]
	s_waitcnt vmcnt(8)
	s_waitcnt vmcnt(8) lgkmcnt(0)
	s_barrier
; #define WAIT_V0() asm volatile("s_waitcnt vmcnt(0)" ::: "memory")
; DI void gemm_core(char* smem, int nk, const char* Ab, const char* Bb, const unsigned (&aoff)[4], const unsigned (&boff)[4],
;                   f32x16 (&acc)[2][2]) {
;     ...
;   for (int kt = 0; kt < nk; ++kt) {
;     const int cur = kt & 1;
;     if (kt + 1 < nk) stage(cur ^ 1, kt + 1);
;     const char* sb = smem + cur * STAGE_B;
; #pragma unroll
;     for (int ks = 0; ks < 4; ++ks) {
;       bf16x8 af[2], bfr[2];
; #pragma unroll
;       for (int mb = 0; mb < 2; ++mb) af[mb] = *(const bf16x8*)(sb + a_base + mb * 4096 + xo[ks]);
; #pragma unroll
;       for (int nb = 0; nb < 2; ++nb) bfr[nb] = *(const bf16x8*)(sb + b_base + nb * 4096 + xo[ks]);
; #pragma unroll
;       for (int mb = 0; mb < 2; ++mb)
; #pragma unroll
;         for (int nb = 0; nb < 2; ++nb)
;           acc[mb][nb] = __builtin_amdgcn_mfma_f32_32x32x16_bf16(af[mb], bfr[nb], acc[mb][nb], 0, 0, 0);
;     }
;     WAIT_V0();
;     __syncthreads();
;   }
	ds_read_b128 v[0:3], v79
	v_lshlrev_b32_e32 v4, 7, v12
	v_and_b32_e32 v116, 0x2f80, v4
	v_or_b32_e32 v81, v116, v6
	ds_read_b128 v[4:7], v81 offset:16384
	ds_read_b128 v[8:11], v81 offset:20480
	s_waitcnt lgkmcnt(0)
	v_mfma_f32_32x32x16_bf16 v[48:63], v[0:3], v[4:7], 0
	s_mov_b32 m0, s84
	s_mov_b32 s3, 0xfffffc0
	v_mfma_f32_32x32x16_bf16 v[32:47], v[0:3], v[8:11], 0
	ds_read_b128 v[0:3], v79 offset:4096
	s_waitcnt lgkmcnt(0)
	v_mfma_f32_32x32x16_bf16 v[16:31], v[0:3], v[4:7], 0
	v_bitop3_b32 v4, v117, v86, 2 bitop3:0x36
	v_lshlrev_b32_e32 v82, 4, v4
	v_or_b32_e32 v80, v87, v82
	ds_read_b128 v[104:107], v80
	v_or_b32_e32 v83, v116, v82
	ds_read_b128 v[108:111], v83 offset:16384
	ds_read_b128 v[112:115], v83 offset:20480
	s_waitcnt lgkmcnt(0)
	v_mfma_f32_32x32x16_bf16 v[48:63], v[104:107], v[108:111], v[48:63]
	v_bitop3_b32 v82, v117, v86, 4 bitop3:0x36
	v_lshlrev_b32_e32 v85, 4, v82
	v_or_b32_e32 v82, v87, v85
	v_or_b32_e32 v85, v116, v85
	v_bitop3_b32 v86, v117, v86, 6 bitop3:0x36
	v_mfma_f32_32x32x16_bf16 v[32:47], v[104:107], v[112:115], v[32:47]
	ds_read_b128 v[104:107], v80 offset:4096
	v_mfma_f32_32x32x16_bf16 v[0:15], v[0:3], v[8:11], 0
	s_waitcnt lgkmcnt(0)
	v_mfma_f32_32x32x16_bf16 v[16:31], v[104:107], v[108:111], v[16:31]
	ds_read_b128 v[108:111], v85 offset:16384
	v_mfma_f32_32x32x16_bf16 v[0:15], v[104:107], v[112:115], v[0:15]
	ds_read_b128 v[104:107], v82
	ds_read_b128 v[112:115], v85 offset:20480
	s_waitcnt lgkmcnt(0)
	v_mfma_f32_32x32x16_bf16 v[48:63], v[104:107], v[108:111], v[48:63]
	v_mfma_f32_32x32x16_bf16 v[32:47], v[104:107], v[112:115], v[32:47]
	ds_read_b128 v[104:107], v82 offset:4096
	s_waitcnt lgkmcnt(0)
	v_mfma_f32_32x32x16_bf16 v[16:31], v[104:107], v[108:111], v[16:31]
	v_lshlrev_b32_e32 v108, 4, v86
	v_or_b32_e32 v86, v87, v108
	v_or_b32_e32 v87, v116, v108
	ds_read_b128 v[108:111], v87 offset:16384
	v_mfma_f32_32x32x16_bf16 v[0:15], v[104:107], v[112:115], v[0:15]
	ds_read_b128 v[104:107], v86
	ds_read_b128 v[112:115], v87 offset:20480
	ds_read_b128 v[144:147], v86 offset:4096
	s_waitcnt vmcnt(0)
	s_waitcnt vmcnt(0) lgkmcnt(0)
	s_barrier
	v_mfma_f32_32x32x16_bf16 v[48:63], v[104:107], v[108:111], v[48:63]
	v_mfma_f32_32x32x16_bf16 v[32:47], v[104:107], v[112:115], v[32:47]
	v_mfma_f32_32x32x16_bf16 v[16:31], v[144:147], v[108:111], v[16:31]
	v_mfma_f32_32x32x16_bf16 v[0:15], v[144:147], v[112:115], v[0:15]
	ds_read_b128 v[104:107], v79 offset:32768
	ds_read_b128 v[108:111], v81 offset:49152
	ds_read_b128 v[112:115], v81 offset:53248
	v_lshl_add_u64 v[140:141], v[64:65], 0, s[4:5]
	global_load_lds_dwordx4 v[140:141], off
	s_mov_b32 m0, s85
	v_lshl_add_u64 v[142:143], v[66:67], 0, s[4:5]
	global_load_lds_dwordx4 v76, s[16:17]
	s_mov_b32 m0, s86
	s_nop 0
	global_load_lds_dwordx4 v[142:143], off
	s_mov_b32 m0, s87
	v_lshl_add_u64 v[140:141], v[68:69], 0, s[4:5]
	global_load_lds_dwordx4 v77, s[16:17]
	s_mov_b32 m0, s88
	s_nop 0
	global_load_lds_dwordx4 v[140:141], off
	s_mov_b32 m0, s89
	v_lshl_add_u64 v[142:143], v[70:71], 0, s[4:5]
	global_load_lds_dwordx4 v78, s[16:17]
	s_mov_b32 m0, s90
	s_mov_b64 s[4:5], 0x180
	global_load_lds_dwordx4 v[142:143], off
	s_mov_b32 m0, s91
	s_nop 0
	global_load_lds_dwordx4 v84, s[16:17]
	s_waitcnt lgkmcnt(0)
	v_mfma_f32_32x32x16_bf16 v[48:63], v[104:107], v[108:111], v[48:63]
	s_mov_b32 m0, s18
	v_mfma_f32_32x32x16_bf16 v[32:47], v[104:107], v[112:115], v[32:47]
	ds_read_b128 v[104:107], v79 offset:36864
	s_waitcnt lgkmcnt(0)
	v_mfma_f32_32x32x16_bf16 v[16:31], v[104:107], v[108:111], v[16:31]
	v_mfma_f32_32x32x16_bf16 v[0:15], v[104:107], v[112:115], v[0:15]
	ds_read_b128 v[104:107], v80 offset:32768
	ds_read_b128 v[108:111], v83 offset:49152
	ds_read_b128 v[112:115], v83 offset:53248
	s_waitcnt lgkmcnt(0)
	v_mfma_f32_32x32x16_bf16 v[48:63], v[104:107], v[108:111], v[48:63]
	v_mfma_f32_32x32x16_bf16 v[32:47], v[104:107], v[112:115], v[32:47]
	ds_read_b128 v[104:107], v80 offset:36864
	s_waitcnt lgkmcnt(0)
	v_mfma_f32_32x32x16_bf16 v[16:31], v[104:107], v[108:111], v[16:31]
	v_mfma_f32_32x32x16_bf16 v[0:15], v[104:107], v[112:115], v[0:15]
	ds_read_b128 v[104:107], v82 offset:32768
	ds_read_b128 v[108:111], v85 offset:49152
	ds_read_b128 v[112:115], v85 offset:53248
	s_waitcnt lgkmcnt(0)
	v_mfma_f32_32x32x16_bf16 v[48:63], v[104:107], v[108:111], v[48:63]
	v_mfma_f32_32x32x16_bf16 v[32:47], v[104:107], v[112:115], v[32:47]
	ds_read_b128 v[104:107], v82 offset:36864
	s_waitcnt lgkmcnt(0)
	v_mfma_f32_32x32x16_bf16 v[16:31], v[104:107], v[108:111], v[16:31]
	v_mfma_f32_32x32x16_bf16 v[0:15], v[104:107], v[112:115], v[0:15]
	ds_read_b128 v[104:107], v86 offset:32768
	ds_read_b128 v[108:111], v87 offset:49152
	ds_read_b128 v[112:115], v87 offset:53248
	ds_read_b128 v[144:147], v86 offset:36864
	s_waitcnt vmcnt(0)
	s_waitcnt vmcnt(0) lgkmcnt(0)
	s_barrier
; #define WAIT_V0() asm volatile("s_waitcnt vmcnt(0)" ::: "memory")
; DI void gemm_core(char* smem, int nk, const char* Ab, const char* Bb, const unsigned (&aoff)[4], const unsigned (&boff)[4],
;                   f32x16 (&acc)[2][2]) {
;     ...
;   for (int kt = 0; kt < nk; ++kt) {
;     const int cur = kt & 1;
;     if (kt + 1 < nk) stage(cur ^ 1, kt + 1);
;     const char* sb = smem + cur * STAGE_B;
; #pragma unroll
;     for (int ks = 0; ks < 4; ++ks) {
;       bf16x8 af[2], bfr[2];
; #pragma unroll
;       for (int mb = 0; mb < 2; ++mb) af[mb] = *(const bf16x8*)(sb + a_base + mb * 4096 + xo[ks]);
; #pragma unroll
;       for (int nb = 0; nb < 2; ++nb) bfr[nb] = *(const bf16x8*)(sb + b_base + nb * 4096 + xo[ks]);
; #pragma unroll
;       for (int mb = 0; mb < 2; ++mb)
; #pragma unroll
;         for (int nb = 0; nb < 2; ++nb)
;           acc[mb][nb] = __builtin_amdgcn_mfma_f32_32x32x16_bf16(af[mb], bfr[nb], acc[mb][nb], 0, 0, 0);
;     }
;     WAIT_V0();
;     __syncthreads();
;   }
	v_mfma_f32_32x32x16_bf16 v[48:63], v[104:107], v[108:111], v[48:63]
	v_mfma_f32_32x32x16_bf16 v[32:47], v[104:107], v[112:115], v[32:47]
	v_mfma_f32_32x32x16_bf16 v[16:31], v[144:147], v[108:111], v[16:31]
	v_mfma_f32_32x32x16_bf16 v[0:15], v[144:147], v[112:115], v[0:15]
	ds_read_b128 v[104:107], v79
	ds_read_b128 v[108:111], v81 offset:16384
	ds_read_b128 v[112:115], v81 offset:20480
	v_lshl_add_u64 v[140:141], v[64:65], 0, s[4:5]
	global_load_lds_dwordx4 v[140:141], off
	s_mov_b32 m0, s19
	v_lshl_add_u64 v[142:143], v[66:67], 0, s[4:5]
	global_load_lds_dwordx4 v76, s[42:43]
	s_mov_b32 m0, s22
	s_nop 0
	global_load_lds_dwordx4 v[142:143], off
	s_mov_b32 m0, s23
	v_lshl_add_u64 v[140:141], v[68:69], 0, s[4:5]
	global_load_lds_dwordx4 v77, s[42:43]
	s_mov_b32 m0, s29
	s_nop 0
	global_load_lds_dwordx4 v[140:141], off
	s_mov_b32 m0, s69
	v_lshl_add_u64 v[142:143], v[70:71], 0, s[4:5]
	global_load_lds_dwordx4 v78, s[42:43]
	s_mov_b32 m0, s70
	s_mov_b64 s[4:5], 0x280
	global_load_lds_dwordx4 v[142:143], off
	s_mov_b32 m0, s71
	s_nop 0
	global_load_lds_dwordx4 v84, s[42:43]
	s_waitcnt lgkmcnt(0)
	v_mfma_f32_32x32x16_bf16 v[48:63], v[104:107], v[108:111], v[48:63]
	s_mov_b32 m0, s84
	v_mfma_f32_32x32x16_bf16 v[32:47], v[104:107], v[112:115], v[32:47]
	ds_read_b128 v[104:107], v79 offset:4096
	s_waitcnt lgkmcnt(0)
	v_mfma_f32_32x32x16_bf16 v[16:31], v[104:107], v[108:111], v[16:31]
	v_mfma_f32_32x32x16_bf16 v[0:15], v[104:107], v[112:115], v[0:15]
	ds_read_b128 v[104:107], v80
	ds_read_b128 v[108:111], v83 offset:16384
	ds_read_b128 v[112:115], v83 offset:20480
	s_waitcnt lgkmcnt(0)
	v_mfma_f32_32x32x16_bf16 v[48:63], v[104:107], v[108:111], v[48:63]
	v_mfma_f32_32x32x16_bf16 v[32:47], v[104:107], v[112:115], v[32:47]
	ds_read_b128 v[104:107], v80 offset:4096
	s_waitcnt lgkmcnt(0)
	v_mfma_f32_32x32x16_bf16 v[16:31], v[104:107], v[108:111], v[16:31]
	v_mfma_f32_32x32x16_bf16 v[0:15], v[104:107], v[112:115], v[0:15]
	ds_read_b128 v[104:107], v82
	ds_read_b128 v[108:111], v85 offset:16384
	ds_read_b128 v[112:115], v85 offset:20480
	s_waitcnt lgkmcnt(0)
	v_mfma_f32_32x32x16_bf16 v[48:63], v[104:107], v[108:111], v[48:63]
	v_mfma_f32_32x32x16_bf16 v[32:47], v[104:107], v[112:115], v[32:47]
	ds_read_b128 v[104:107], v82 offset:4096
	s_waitcnt lgkmcnt(0)
	v_mfma_f32_32x32x16_bf16 v[16:31], v[104:107], v[108:111], v[16:31]
	v_mfma_f32_32x32x16_bf16 v[0:15], v[104:107], v[112:115], v[0:15]
	ds_read_b128 v[104:107], v86
	ds_read_b128 v[108:111], v87 offset:16384
	ds_read_b128 v[112:115], v87 offset:20480
	ds_read_b128 v[144:147], v86 offset:4096
	s_waitcnt vmcnt(0)
	s_waitcnt vmcnt(0) lgkmcnt(0)
	s_barrier
	v_mfma_f32_32x32x16_bf16 v[48:63], v[104:107], v[108:111], v[48:63]
	v_mfma_f32_32x32x16_bf16 v[32:47], v[104:107], v[112:115], v[32:47]
	v_mfma_f32_32x32x16_bf16 v[16:31], v[144:147], v[108:111], v[16:31]
	v_mfma_f32_32x32x16_bf16 v[0:15], v[144:147], v[112:115], v[0:15]
	ds_read_b128 v[104:107], v79 offset:32768
	ds_read_b128 v[108:111], v81 offset:49152
	ds_read_b128 v[112:115], v81 offset:53248
	v_lshl_add_u64 v[140:141], v[64:65], 0, s[30:31]
	global_load_lds_dwordx4 v[140:141], off
	s_mov_b32 m0, s85
	v_lshl_add_u64 v[142:143], v[66:67], 0, s[30:31]
	global_load_lds_dwordx4 v76, s[44:45]
	s_mov_b32 m0, s86
	s_nop 0
	global_load_lds_dwordx4 v[142:143], off
	s_mov_b32 m0, s87
	v_lshl_add_u64 v[140:141], v[68:69], 0, s[30:31]
	global_load_lds_dwordx4 v77, s[44:45]
	s_mov_b32 m0, s88
	s_nop 0
	global_load_lds_dwordx4 v[140:141], off
	s_mov_b32 m0, s89
	v_lshl_add_u64 v[142:143], v[70:71], 0, s[30:31]
	global_load_lds_dwordx4 v78, s[44:45]
	s_mov_b32 m0, s90
	s_nop 0
	global_load_lds_dwordx4 v[142:143], off
	s_mov_b32 m0, s91
	s_nop 0
	global_load_lds_dwordx4 v84, s[44:45]
	s_waitcnt lgkmcnt(0)
	v_mfma_f32_32x32x16_bf16 v[48:63], v[104:107], v[108:111], v[48:63]
	s_mov_b32 m0, s18
	v_mfma_f32_32x32x16_bf16 v[32:47], v[104:107], v[112:115], v[32:47]
	ds_read_b128 v[104:107], v79 offset:36864
	s_waitcnt lgkmcnt(0)
	v_mfma_f32_32x32x16_bf16 v[16:31], v[104:107], v[108:111], v[16:31]
	v_mfma_f32_32x32x16_bf16 v[0:15], v[104:107], v[112:115], v[0:15]
	ds_read_b128 v[104:107], v80 offset:32768
	ds_read_b128 v[108:111], v83 offset:49152
	ds_read_b128 v[112:115], v83 offset:53248
	s_waitcnt lgkmcnt(0)
	v_mfma_f32_32x32x16_bf16 v[48:63], v[104:107], v[108:111], v[48:63]
	v_mfma_f32_32x32x16_bf16 v[32:47], v[104:107], v[112:115], v[32:47]
	ds_read_b128 v[104:107], v80 offset:36864
	s_waitcnt lgkmcnt(0)
	v_mfma_f32_32x32x16_bf16 v[16:31], v[104:107], v[108:111], v[16:31]
	v_mfma_f32_32x32x16_bf16 v[0:15], v[104:107], v[112:115], v[0:15]
	ds_read_b128 v[104:107], v82 offset:32768
	ds_read_b128 v[108:111], v85 offset:49152
	ds_read_b128 v[112:115], v85 offset:53248
	s_waitcnt lgkmcnt(0)
	v_mfma_f32_32x32x16_bf16 v[48:63], v[104:107], v[108:111], v[48:63]
	v_mfma_f32_32x32x16_bf16 v[32:47], v[104:107], v[112:115], v[32:47]
	ds_read_b128 v[104:107], v82 offset:36864
	s_waitcnt lgkmcnt(0)
	v_mfma_f32_32x32x16_bf16 v[16:31], v[104:107], v[108:111], v[16:31]
	v_mfma_f32_32x32x16_bf16 v[0:15], v[104:107], v[112:115], v[0:15]
	ds_read_b128 v[104:107], v86 offset:32768
	ds_read_b128 v[108:111], v87 offset:49152
	ds_read_b128 v[112:115], v87 offset:53248
	ds_read_b128 v[144:147], v86 offset:36864
	s_waitcnt vmcnt(0)
	s_waitcnt vmcnt(0) lgkmcnt(0)
	s_barrier
; #define WAIT_V0() asm volatile("s_waitcnt vmcnt(0)" ::: "memory")
; DI void gemm_core(char* smem, int nk, const char* Ab, const char* Bb, const unsigned (&aoff)[4], const unsigned (&boff)[4],
;                   f32x16 (&acc)[2][2]) {
;     ...
;   for (int kt = 0; kt < nk; ++kt) {
;     const int cur = kt & 1;
;     if (kt + 1 < nk) stage(cur ^ 1, kt + 1);
;     const char* sb = smem + cur * STAGE_B;
; #pragma unroll
;     for (int ks = 0; ks < 4; ++ks) {
;       bf16x8 af[2], bfr[2];
; #pragma unroll
;       for (int mb = 0; mb < 2; ++mb) af[mb] = *(const bf16x8*)(sb + a_base + mb * 4096 + xo[ks]);
; #pragma unroll
;       for (int nb = 0; nb < 2; ++nb) bfr[nb] = *(const bf16x8*)(sb + b_base + nb * 4096 + xo[ks]);
; #pragma unroll
;       for (int mb = 0; mb < 2; ++mb)
; #pragma unroll
;         for (int nb = 0; nb < 2; ++nb)
;           acc[mb][nb] = __builtin_amdgcn_mfma_f32_32x32x16_bf16(af[mb], bfr[nb], acc[mb][nb], 0, 0, 0);
;     }
;     WAIT_V0();
;     __syncthreads();
;   }
	v_mfma_f32_32x32x16_bf16 v[48:63], v[104:107], v[108:111], v[48:63]
	v_mfma_f32_32x32x16_bf16 v[32:47], v[104:107], v[112:115], v[32:47]
	v_mfma_f32_32x32x16_bf16 v[16:31], v[144:147], v[108:111], v[16:31]
	v_mfma_f32_32x32x16_bf16 v[0:15], v[144:147], v[112:115], v[0:15]
	ds_read_b128 v[104:107], v79
	ds_read_b128 v[108:111], v81 offset:16384
	ds_read_b128 v[112:115], v81 offset:20480
	v_lshl_add_u64 v[140:141], v[64:65], 0, s[4:5]
	global_load_lds_dwordx4 v[140:141], off
	s_mov_b32 m0, s19
	v_lshl_add_u64 v[142:143], v[66:67], 0, s[4:5]
	global_load_lds_dwordx4 v76, s[46:47]
	s_mov_b32 m0, s22
	s_nop 0
	global_load_lds_dwordx4 v[142:143], off
	s_mov_b32 m0, s23
	v_lshl_add_u64 v[140:141], v[68:69], 0, s[4:5]
	global_load_lds_dwordx4 v77, s[46:47]
	s_mov_b32 m0, s29
	s_nop 0
	global_load_lds_dwordx4 v[140:141], off
	s_mov_b32 m0, s69
	v_lshl_add_u64 v[142:143], v[70:71], 0, s[4:5]
	global_load_lds_dwordx4 v78, s[46:47]
	s_mov_b32 m0, s70
	s_mov_b64 s[4:5], 0x300
	global_load_lds_dwordx4 v[142:143], off
	s_mov_b32 m0, s71
	s_nop 0
	global_load_lds_dwordx4 v84, s[46:47]
	s_waitcnt lgkmcnt(0)
	v_mfma_f32_32x32x16_bf16 v[48:63], v[104:107], v[108:111], v[48:63]
	s_mov_b32 m0, s84
	v_mfma_f32_32x32x16_bf16 v[32:47], v[104:107], v[112:115], v[32:47]
	ds_read_b128 v[104:107], v79 offset:4096
	s_waitcnt lgkmcnt(0)
	v_mfma_f32_32x32x16_bf16 v[16:31], v[104:107], v[108:111], v[16:31]
	v_mfma_f32_32x32x16_bf16 v[0:15], v[104:107], v[112:115], v[0:15]
	ds_read_b128 v[104:107], v80
	ds_read_b128 v[108:111], v83 offset:16384
	ds_read_b128 v[112:115], v83 offset:20480
	s_waitcnt lgkmcnt(0)
	v_mfma_f32_32x32x16_bf16 v[48:63], v[104:107], v[108:111], v[48:63]
	v_mfma_f32_32x32x16_bf16 v[32:47], v[104:107], v[112:115], v[32:47]
	ds_read_b128 v[104:107], v80 offset:4096
	s_waitcnt lgkmcnt(0)
	v_mfma_f32_32x32x16_bf16 v[16:31], v[104:107], v[108:111], v[16:31]
	v_mfma_f32_32x32x16_bf16 v[0:15], v[104:107], v[112:115], v[0:15]
	ds_read_b128 v[104:107], v82
	ds_read_b128 v[108:111], v85 offset:16384
	ds_read_b128 v[112:115], v85 offset:20480
	s_waitcnt lgkmcnt(0)
	v_mfma_f32_32x32x16_bf16 v[48:63], v[104:107], v[108:111], v[48:63]
	v_mfma_f32_32x32x16_bf16 v[32:47], v[104:107], v[112:115], v[32:47]
	ds_read_b128 v[104:107], v82 offset:4096
	s_waitcnt lgkmcnt(0)
	v_mfma_f32_32x32x16_bf16 v[16:31], v[104:107], v[108:111], v[16:31]
	v_mfma_f32_32x32x16_bf16 v[0:15], v[104:107], v[112:115], v[0:15]
	ds_read_b128 v[104:107], v86
	ds_read_b128 v[108:111], v87 offset:16384
	ds_read_b128 v[112:115], v87 offset:20480
	ds_read_b128 v[144:147], v86 offset:4096
	s_waitcnt vmcnt(0)
	s_waitcnt vmcnt(0) lgkmcnt(0)
	s_barrier
	v_mfma_f32_32x32x16_bf16 v[48:63], v[104:107], v[108:111], v[48:63]
	v_mfma_f32_32x32x16_bf16 v[32:47], v[104:107], v[112:115], v[32:47]
	v_mfma_f32_32x32x16_bf16 v[16:31], v[144:147], v[108:111], v[16:31]
	v_mfma_f32_32x32x16_bf16 v[0:15], v[144:147], v[112:115], v[0:15]
	ds_read_b128 v[104:107], v79 offset:32768
	ds_read_b128 v[108:111], v81 offset:49152
	ds_read_b128 v[112:115], v81 offset:53248
	v_lshl_add_u64 v[140:141], v[64:65], 0, s[4:5]
	global_load_lds_dwordx4 v[140:141], off
	s_mov_b32 m0, s85
	v_lshl_add_u64 v[142:143], v[66:67], 0, s[4:5]
	global_load_lds_dwordx4 v76, s[48:49]
	s_mov_b32 m0, s86
	s_nop 0
	global_load_lds_dwordx4 v[142:143], off
	s_mov_b32 m0, s87
	v_lshl_add_u64 v[140:141], v[68:69], 0, s[4:5]
	global_load_lds_dwordx4 v77, s[48:49]
	s_mov_b32 m0, s88
	s_nop 0
	global_load_lds_dwordx4 v[140:141], off
	s_mov_b32 m0, s89
	v_lshl_add_u64 v[142:143], v[70:71], 0, s[4:5]
	global_load_lds_dwordx4 v78, s[48:49]
	s_mov_b32 m0, s90
	s_mov_b64 s[4:5], 0x380
	global_load_lds_dwordx4 v[142:143], off
	s_mov_b32 m0, s91
	s_nop 0
	global_load_lds_dwordx4 v84, s[48:49]
	s_waitcnt lgkmcnt(0)
	v_mfma_f32_32x32x16_bf16 v[48:63], v[104:107], v[108:111], v[48:63]
	s_mov_b32 m0, s18
	v_mfma_f32_32x32x16_bf16 v[32:47], v[104:107], v[112:115], v[32:47]
	ds_read_b128 v[104:107], v79 offset:36864
	s_waitcnt lgkmcnt(0)
	v_mfma_f32_32x32x16_bf16 v[16:31], v[104:107], v[108:111], v[16:31]
	v_mfma_f32_32x32x16_bf16 v[0:15], v[104:107], v[112:115], v[0:15]
	ds_read_b128 v[104:107], v80 offset:32768
	ds_read_b128 v[108:111], v83 offset:49152
	ds_read_b128 v[112:115], v83 offset:53248
	s_waitcnt lgkmcnt(0)
	v_mfma_f32_32x32x16_bf16 v[48:63], v[104:107], v[108:111], v[48:63]
	v_mfma_f32_32x32x16_bf16 v[32:47], v[104:107], v[112:115], v[32:47]
	ds_read_b128 v[104:107], v80 offset:36864
	s_waitcnt lgkmcnt(0)
	v_mfma_f32_32x32x16_bf16 v[16:31], v[104:107], v[108:111], v[16:31]
	v_mfma_f32_32x32x16_bf16 v[0:15], v[104:107], v[112:115], v[0:15]
	ds_read_b128 v[104:107], v82 offset:32768
	ds_read_b128 v[108:111], v85 offset:49152
	ds_read_b128 v[112:115], v85 offset:53248
	s_waitcnt lgkmcnt(0)
	v_mfma_f32_32x32x16_bf16 v[48:63], v[104:107], v[108:111], v[48:63]
	v_mfma_f32_32x32x16_bf16 v[32:47], v[104:107], v[112:115], v[32:47]
	ds_read_b128 v[104:107], v82 offset:36864
	s_waitcnt lgkmcnt(0)
	v_mfma_f32_32x32x16_bf16 v[16:31], v[104:107], v[108:111], v[16:31]
	v_mfma_f32_32x32x16_bf16 v[0:15], v[104:107], v[112:115], v[0:15]
	ds_read_b128 v[104:107], v86 offset:32768
	ds_read_b128 v[108:111], v87 offset:49152
	ds_read_b128 v[112:115], v87 offset:53248
	ds_read_b128 v[144:147], v86 offset:36864
	s_waitcnt vmcnt(0)
	s_waitcnt vmcnt(0) lgkmcnt(0)
	s_barrier
; #define WAIT_V0() asm volatile("s_waitcnt vmcnt(0)" ::: "memory")
; DI void gemm_core(char* smem, int nk, const char* Ab, const char* Bb, const unsigned (&aoff)[4], const unsigned (&boff)[4],
;                   f32x16 (&acc)[2][2]) {
;     ...
;   for (int kt = 0; kt < nk; ++kt) {
;     const int cur = kt & 1;
;     if (kt + 1 < nk) stage(cur ^ 1, kt + 1);
;     const char* sb = smem + cur * STAGE_B;
; #pragma unroll
;     for (int ks = 0; ks < 4; ++ks) {
;       bf16x8 af[2], bfr[2];
; #pragma unroll
;       for (int mb = 0; mb < 2; ++mb) af[mb] = *(const bf16x8*)(sb + a_base + mb * 4096 + xo[ks]);
; #pragma unroll
;       for (int nb = 0; nb < 2; ++nb) bfr[nb] = *(const bf16x8*)(sb + b_base + nb * 4096 + xo[ks]);
; #pragma unroll
;       for (int mb = 0; mb < 2; ++mb)
; #pragma unroll
;         for (int nb = 0; nb < 2; ++nb)
;           acc[mb][nb] = __builtin_amdgcn_mfma_f32_32x32x16_bf16(af[mb], bfr[nb], acc[mb][nb], 0, 0, 0);
;     }
;     WAIT_V0();
;     __syncthreads();
;   }
	v_mfma_f32_32x32x16_bf16 v[48:63], v[104:107], v[108:111], v[48:63]
	v_mfma_f32_32x32x16_bf16 v[32:47], v[104:107], v[112:115], v[32:47]
	v_mfma_f32_32x32x16_bf16 v[16:31], v[144:147], v[108:111], v[16:31]
	v_mfma_f32_32x32x16_bf16 v[0:15], v[144:147], v[112:115], v[0:15]
	ds_read_b128 v[104:107], v79
	ds_read_b128 v[108:111], v81 offset:16384
	ds_read_b128 v[112:115], v81 offset:20480
	v_lshl_add_u64 v[140:141], v[64:65], 0, s[4:5]
	global_load_lds_dwordx4 v[140:141], off
	s_mov_b32 m0, s19
	v_lshl_add_u64 v[142:143], v[66:67], 0, s[4:5]
	global_load_lds_dwordx4 v76, s[50:51]
	s_mov_b32 m0, s22
	s_nop 0
	global_load_lds_dwordx4 v[142:143], off
	s_mov_b32 m0, s23
	v_lshl_add_u64 v[140:141], v[68:69], 0, s[4:5]
	global_load_lds_dwordx4 v77, s[50:51]
	s_mov_b32 m0, s29
	s_nop 0
	global_load_lds_dwordx4 v[140:141], off
	s_mov_b32 m0, s69
	v_lshl_add_u64 v[142:143], v[70:71], 0, s[4:5]
	global_load_lds_dwordx4 v78, s[50:51]
	s_mov_b32 m0, s70
	s_mov_b64 s[4:5], 0x400
	global_load_lds_dwordx4 v[142:143], off
	s_mov_b32 m0, s71
	s_nop 0
	global_load_lds_dwordx4 v84, s[50:51]
	s_waitcnt lgkmcnt(0)
	v_mfma_f32_32x32x16_bf16 v[48:63], v[104:107], v[108:111], v[48:63]
	s_mov_b32 m0, s84
	v_readfirstlane_b32 s84, v89
	v_mfma_f32_32x32x16_bf16 v[32:47], v[104:107], v[112:115], v[32:47]
	ds_read_b128 v[104:107], v79 offset:4096
	s_waitcnt lgkmcnt(0)
	v_mfma_f32_32x32x16_bf16 v[16:31], v[104:107], v[108:111], v[16:31]
	v_mfma_f32_32x32x16_bf16 v[0:15], v[104:107], v[112:115], v[0:15]
	ds_read_b128 v[104:107], v80
	ds_read_b128 v[108:111], v83 offset:16384
	ds_read_b128 v[112:115], v83 offset:20480
	s_waitcnt lgkmcnt(0)
	v_mfma_f32_32x32x16_bf16 v[48:63], v[104:107], v[108:111], v[48:63]
	v_mfma_f32_32x32x16_bf16 v[32:47], v[104:107], v[112:115], v[32:47]
	ds_read_b128 v[104:107], v80 offset:4096
	s_waitcnt lgkmcnt(0)
	v_mfma_f32_32x32x16_bf16 v[16:31], v[104:107], v[108:111], v[16:31]
	v_mfma_f32_32x32x16_bf16 v[0:15], v[104:107], v[112:115], v[0:15]
	ds_read_b128 v[104:107], v82
	ds_read_b128 v[108:111], v85 offset:16384
	ds_read_b128 v[112:115], v85 offset:20480
	s_waitcnt lgkmcnt(0)
	v_mfma_f32_32x32x16_bf16 v[48:63], v[104:107], v[108:111], v[48:63]
	v_mfma_f32_32x32x16_bf16 v[32:47], v[104:107], v[112:115], v[32:47]
	ds_read_b128 v[104:107], v82 offset:4096
	s_waitcnt lgkmcnt(0)
	v_mfma_f32_32x32x16_bf16 v[16:31], v[104:107], v[108:111], v[16:31]
	v_mfma_f32_32x32x16_bf16 v[0:15], v[104:107], v[112:115], v[0:15]
	ds_read_b128 v[104:107], v86
	ds_read_b128 v[108:111], v87 offset:16384
	ds_read_b128 v[112:115], v87 offset:20480
	ds_read_b128 v[144:147], v86 offset:4096
	s_waitcnt vmcnt(0)
	s_waitcnt vmcnt(0) lgkmcnt(0)
	s_barrier
	v_mfma_f32_32x32x16_bf16 v[48:63], v[104:107], v[108:111], v[48:63]
	v_mfma_f32_32x32x16_bf16 v[32:47], v[104:107], v[112:115], v[32:47]
	v_mfma_f32_32x32x16_bf16 v[16:31], v[144:147], v[108:111], v[16:31]
	v_mfma_f32_32x32x16_bf16 v[0:15], v[144:147], v[112:115], v[0:15]
	ds_read_b128 v[104:107], v79 offset:32768
	ds_read_b128 v[108:111], v81 offset:49152
	ds_read_b128 v[112:115], v81 offset:53248
	v_lshl_add_u64 v[140:141], v[64:65], 0, s[4:5]
	global_load_lds_dwordx4 v[140:141], off
	s_mov_b32 m0, s85
	v_lshl_add_u64 v[142:143], v[66:67], 0, s[4:5]
	global_load_lds_dwordx4 v76, s[52:53]
	s_mov_b32 m0, s86
	v_readfirstlane_b32 s85, v88
	global_load_lds_dwordx4 v[142:143], off
	s_mov_b32 m0, s87
	v_lshl_add_u64 v[140:141], v[68:69], 0, s[4:5]
	global_load_lds_dwordx4 v77, s[52:53]
	s_mov_b32 m0, s88
	v_readfirstlane_b32 s86, v90
	global_load_lds_dwordx4 v[140:141], off
	s_mov_b32 m0, s89
	v_lshl_add_u64 v[142:143], v[70:71], 0, s[4:5]
	global_load_lds_dwordx4 v78, s[52:53]
	s_mov_b32 m0, s90
	s_mov_b64 s[4:5], 0x480
	global_load_lds_dwordx4 v[142:143], off
	s_mov_b32 m0, s91
	v_readfirstlane_b32 s87, v91
	global_load_lds_dwordx4 v84, s[52:53]
	s_waitcnt lgkmcnt(0)
	v_mfma_f32_32x32x16_bf16 v[48:63], v[104:107], v[108:111], v[48:63]
	s_mov_b32 m0, s18
	v_readfirstlane_b32 s18, v97
	v_readfirstlane_b32 s88, v92
	v_readfirstlane_b32 s89, v93
	v_readfirstlane_b32 s90, v94
	v_readfirstlane_b32 s91, v95
	v_mfma_f32_32x32x16_bf16 v[32:47], v[104:107], v[112:115], v[32:47]
	ds_read_b128 v[104:107], v79 offset:36864
	s_waitcnt lgkmcnt(0)
	v_mfma_f32_32x32x16_bf16 v[16:31], v[104:107], v[108:111], v[16:31]
	v_mfma_f32_32x32x16_bf16 v[0:15], v[104:107], v[112:115], v[0:15]
	ds_read_b128 v[104:107], v80 offset:32768
	ds_read_b128 v[108:111], v83 offset:49152
	ds_read_b128 v[112:115], v83 offset:53248
	s_waitcnt lgkmcnt(0)
	v_mfma_f32_32x32x16_bf16 v[48:63], v[104:107], v[108:111], v[48:63]
	v_mfma_f32_32x32x16_bf16 v[32:47], v[104:107], v[112:115], v[32:47]
	ds_read_b128 v[104:107], v80 offset:36864
	s_waitcnt lgkmcnt(0)
	v_mfma_f32_32x32x16_bf16 v[16:31], v[104:107], v[108:111], v[16:31]
	v_mfma_f32_32x32x16_bf16 v[0:15], v[104:107], v[112:115], v[0:15]
	ds_read_b128 v[104:107], v82 offset:32768
	ds_read_b128 v[108:111], v85 offset:49152
	ds_read_b128 v[112:115], v85 offset:53248
	s_waitcnt lgkmcnt(0)
	v_mfma_f32_32x32x16_bf16 v[48:63], v[104:107], v[108:111], v[48:63]
	v_mfma_f32_32x32x16_bf16 v[32:47], v[104:107], v[112:115], v[32:47]
	ds_read_b128 v[104:107], v82 offset:36864
	s_waitcnt lgkmcnt(0)
	v_mfma_f32_32x32x16_bf16 v[16:31], v[104:107], v[108:111], v[16:31]
	v_mfma_f32_32x32x16_bf16 v[0:15], v[104:107], v[112:115], v[0:15]
	ds_read_b128 v[104:107], v86 offset:32768
	ds_read_b128 v[108:111], v87 offset:49152
	ds_read_b128 v[112:115], v87 offset:53248
	ds_read_b128 v[144:147], v86 offset:36864
	s_waitcnt vmcnt(0)
	s_waitcnt vmcnt(0) lgkmcnt(0)
	s_barrier
; #define WAIT_V0() asm volatile("s_waitcnt vmcnt(0)" ::: "memory")
; DI void gemm_core(char* smem, int nk, const char* Ab, const char* Bb, const unsigned (&aoff)[4], const unsigned (&boff)[4],
;                   f32x16 (&acc)[2][2]) {
;     ...
;   for (int kt = 0; kt < nk; ++kt) {
;     const int cur = kt & 1;
;     if (kt + 1 < nk) stage(cur ^ 1, kt + 1);
;     const char* sb = smem + cur * STAGE_B;
; #pragma unroll
;     for (int ks = 0; ks < 4; ++ks) {
;       bf16x8 af[2], bfr[2];
; #pragma unroll
;       for (int mb = 0; mb < 2; ++mb) af[mb] = *(const bf16x8*)(sb + a_base + mb * 4096 + xo[ks]);
; #pragma unroll
;       for (int nb = 0; nb < 2; ++nb) bfr[nb] = *(const bf16x8*)(sb + b_base + nb * 4096 + xo[ks]);
; #pragma unroll
;       for (int mb = 0; mb < 2; ++mb)
; #pragma unroll
;         for (int nb = 0; nb < 2; ++nb)
;           acc[mb][nb] = __builtin_amdgcn_mfma_f32_32x32x16_bf16(af[mb], bfr[nb], acc[mb][nb], 0, 0, 0);
;     }
;     WAIT_V0();
;     __syncthreads();
;   }
	v_mfma_f32_32x32x16_bf16 v[48:63], v[104:107], v[108:111], v[48:63]
	v_mfma_f32_32x32x16_bf16 v[32:47], v[104:107], v[112:115], v[32:47]
	v_mfma_f32_32x32x16_bf16 v[16:31], v[144:147], v[108:111], v[16:31]
	v_mfma_f32_32x32x16_bf16 v[0:15], v[144:147], v[112:115], v[0:15]
	v_lshl_add_u64 v[104:105], v[64:65], 0, s[4:5]
	global_load_lds_dwordx4 v[104:105], off
	s_mov_b32 m0, s19
	v_lshl_add_u64 v[104:105], v[66:67], 0, s[4:5]
	global_load_lds_dwordx4 v76, s[54:55]
	s_mov_b32 m0, s22
	v_readfirstlane_b32 s19, v96
	global_load_lds_dwordx4 v[104:105], off
	s_mov_b32 m0, s23
	v_lshl_add_u64 v[104:105], v[68:69], 0, s[4:5]
	global_load_lds_dwordx4 v77, s[54:55]
	s_mov_b32 m0, s29
	v_readfirstlane_b32 s22, v98
	global_load_lds_dwordx4 v[104:105], off
	s_mov_b32 m0, s69
	v_lshl_add_u64 v[104:105], v[70:71], 0, s[4:5]
	global_load_lds_dwordx4 v78, s[54:55]
	s_mov_b32 m0, s70
	s_mov_b64 s[4:5], 0x500
	global_load_lds_dwordx4 v[104:105], off
	s_mov_b32 m0, s71
	v_lshl_add_u64 v[96:97], v[66:67], 0, s[4:5]
	global_load_lds_dwordx4 v84, s[54:55]
	ds_read_b128 v[104:107], v79
	ds_read_b128 v[108:111], v81 offset:16384
	ds_read_b128 v[112:115], v81 offset:20480
	s_waitcnt lgkmcnt(0)
	v_mfma_f32_32x32x16_bf16 v[48:63], v[104:107], v[108:111], v[48:63]
	s_mov_b32 m0, s18
	v_readfirstlane_b32 s23, v99
	v_readfirstlane_b32 s29, v100
	v_readfirstlane_b32 s69, v101
	v_readfirstlane_b32 s70, v102
	v_readfirstlane_b32 s71, v103
	v_mfma_f32_32x32x16_bf16 v[32:47], v[104:107], v[112:115], v[32:47]
	ds_read_b128 v[104:107], v79 offset:4096
	s_waitcnt lgkmcnt(0)
	v_mfma_f32_32x32x16_bf16 v[16:31], v[104:107], v[108:111], v[16:31]
	v_mfma_f32_32x32x16_bf16 v[0:15], v[104:107], v[112:115], v[0:15]
	ds_read_b128 v[104:107], v80
	ds_read_b128 v[108:111], v83 offset:16384
	ds_read_b128 v[112:115], v83 offset:20480
	s_waitcnt lgkmcnt(0)
	v_mfma_f32_32x32x16_bf16 v[48:63], v[104:107], v[108:111], v[48:63]
	v_mfma_f32_32x32x16_bf16 v[32:47], v[104:107], v[112:115], v[32:47]
	ds_read_b128 v[104:107], v80 offset:4096
	s_waitcnt lgkmcnt(0)
	v_mfma_f32_32x32x16_bf16 v[16:31], v[104:107], v[108:111], v[16:31]
	v_mfma_f32_32x32x16_bf16 v[0:15], v[104:107], v[112:115], v[0:15]
	ds_read_b128 v[104:107], v82
	ds_read_b128 v[108:111], v85 offset:16384
	ds_read_b128 v[112:115], v85 offset:20480
	s_waitcnt lgkmcnt(0)
	v_mfma_f32_32x32x16_bf16 v[48:63], v[104:107], v[108:111], v[48:63]
	v_mfma_f32_32x32x16_bf16 v[32:47], v[104:107], v[112:115], v[32:47]
	ds_read_b128 v[104:107], v82 offset:4096
	s_waitcnt lgkmcnt(0)
	v_mfma_f32_32x32x16_bf16 v[16:31], v[104:107], v[108:111], v[16:31]
	v_mfma_f32_32x32x16_bf16 v[0:15], v[104:107], v[112:115], v[0:15]
	ds_read_b128 v[104:107], v86
	ds_read_b128 v[108:111], v87 offset:16384
	ds_read_b128 v[112:115], v87 offset:20480
	ds_read_b128 v[144:147], v86 offset:4096
	s_waitcnt vmcnt(0)
	s_waitcnt vmcnt(0) lgkmcnt(0)
	s_barrier
	v_mfma_f32_32x32x16_bf16 v[48:63], v[104:107], v[108:111], v[48:63]
	v_mfma_f32_32x32x16_bf16 v[32:47], v[104:107], v[112:115], v[32:47]
	v_mfma_f32_32x32x16_bf16 v[16:31], v[144:147], v[108:111], v[16:31]
	v_mfma_f32_32x32x16_bf16 v[0:15], v[144:147], v[112:115], v[0:15]
	v_lshl_add_u64 v[104:105], v[64:65], 0, s[4:5]
	global_load_lds_dwordx4 v[104:105], off
	s_mov_b32 m0, s19
	s_nop 0
	global_load_lds_dwordx4 v76, s[56:57]
	s_mov_b32 m0, s22
	s_nop 0
	global_load_lds_dwordx4 v[96:97], off
	s_mov_b32 m0, s23
	v_lshl_add_u64 v[96:97], v[68:69], 0, s[4:5]
	global_load_lds_dwordx4 v77, s[56:57]
	s_mov_b32 m0, s29
	s_nop 0
	global_load_lds_dwordx4 v[96:97], off
	s_mov_b32 m0, s69
	v_lshl_add_u64 v[96:97], v[70:71], 0, s[4:5]
	global_load_lds_dwordx4 v78, s[56:57]
	s_mov_b32 m0, s70
	s_mov_b64 s[4:5], 0x580
	global_load_lds_dwordx4 v[96:97], off
	s_mov_b32 m0, s71
	v_lshl_add_u64 v[88:89], v[66:67], 0, s[4:5]
	global_load_lds_dwordx4 v84, s[56:57]
	ds_read_b128 v[96:99], v79 offset:32768
	ds_read_b128 v[100:103], v81 offset:49152
	ds_read_b128 v[104:107], v81 offset:53248
	s_waitcnt lgkmcnt(0)
	v_mfma_f32_32x32x16_bf16 v[48:63], v[96:99], v[100:103], v[48:63]
	s_mov_b32 m0, s84
	v_mfma_f32_32x32x16_bf16 v[32:47], v[96:99], v[104:107], v[32:47]
	ds_read_b128 v[96:99], v79 offset:36864
	s_waitcnt lgkmcnt(0)
	v_mfma_f32_32x32x16_bf16 v[16:31], v[96:99], v[100:103], v[16:31]
	v_mfma_f32_32x32x16_bf16 v[0:15], v[96:99], v[104:107], v[0:15]
	ds_read_b128 v[96:99], v80 offset:32768
	ds_read_b128 v[100:103], v83 offset:49152
	ds_read_b128 v[104:107], v83 offset:53248
	s_waitcnt lgkmcnt(0)
	v_mfma_f32_32x32x16_bf16 v[48:63], v[96:99], v[100:103], v[48:63]
	v_mfma_f32_32x32x16_bf16 v[32:47], v[96:99], v[104:107], v[32:47]
	ds_read_b128 v[96:99], v80 offset:36864
	s_waitcnt lgkmcnt(0)
	v_mfma_f32_32x32x16_bf16 v[16:31], v[96:99], v[100:103], v[16:31]
	v_mfma_f32_32x32x16_bf16 v[0:15], v[96:99], v[104:107], v[0:15]
	ds_read_b128 v[96:99], v82 offset:32768
	ds_read_b128 v[100:103], v85 offset:49152
	ds_read_b128 v[104:107], v85 offset:53248
	s_waitcnt lgkmcnt(0)
	v_mfma_f32_32x32x16_bf16 v[48:63], v[96:99], v[100:103], v[48:63]
	v_mfma_f32_32x32x16_bf16 v[32:47], v[96:99], v[104:107], v[32:47]
	ds_read_b128 v[96:99], v82 offset:36864
	s_waitcnt lgkmcnt(0)
	v_mfma_f32_32x32x16_bf16 v[16:31], v[96:99], v[100:103], v[16:31]
	v_mfma_f32_32x32x16_bf16 v[0:15], v[96:99], v[104:107], v[0:15]
	ds_read_b128 v[96:99], v86 offset:32768
	ds_read_b128 v[100:103], v87 offset:49152
	ds_read_b128 v[104:107], v87 offset:53248
	ds_read_b128 v[144:147], v86 offset:36864
	s_waitcnt vmcnt(0)
	s_waitcnt vmcnt(0) lgkmcnt(0)
	s_barrier
; #define WAIT_V0() asm volatile("s_waitcnt vmcnt(0)" ::: "memory")
; DI void gemm_core(char* smem, int nk, const char* Ab, const char* Bb, const unsigned (&aoff)[4], const unsigned (&boff)[4],
;                   f32x16 (&acc)[2][2]) {
;     ...
;   for (int kt = 0; kt < nk; ++kt) {
;     const int cur = kt & 1;
;     if (kt + 1 < nk) stage(cur ^ 1, kt + 1);
;     const char* sb = smem + cur * STAGE_B;
; #pragma unroll
;     for (int ks = 0; ks < 4; ++ks) {
;       bf16x8 af[2], bfr[2];
; #pragma unroll
;       for (int mb = 0; mb < 2; ++mb) af[mb] = *(const bf16x8*)(sb + a_base + mb * 4096 + xo[ks]);
; #pragma unroll
;       for (int nb = 0; nb < 2; ++nb) bfr[nb] = *(const bf16x8*)(sb + b_base + nb * 4096 + xo[ks]);
; #pragma unroll
;       for (int mb = 0; mb < 2; ++mb)
; #pragma unroll
;         for (int nb = 0; nb < 2; ++nb)
;           acc[mb][nb] = __builtin_amdgcn_mfma_f32_32x32x16_bf16(af[mb], bfr[nb], acc[mb][nb], 0, 0, 0);
;     }
;     WAIT_V0();
;     __syncthreads();
;   }
	v_mfma_f32_32x32x16_bf16 v[48:63], v[96:99], v[100:103], v[48:63]
	v_mfma_f32_32x32x16_bf16 v[32:47], v[96:99], v[104:107], v[32:47]
	v_mfma_f32_32x32x16_bf16 v[16:31], v[144:147], v[100:103], v[16:31]
	v_mfma_f32_32x32x16_bf16 v[0:15], v[144:147], v[104:107], v[0:15]
	v_lshl_add_u64 v[96:97], v[64:65], 0, s[4:5]
	global_load_lds_dwordx4 v[96:97], off
	s_mov_b32 m0, s85
	s_nop 0
	global_load_lds_dwordx4 v76, s[58:59]
	s_mov_b32 m0, s86
	s_nop 0
	global_load_lds_dwordx4 v[88:89], off
	s_mov_b32 m0, s87
	v_lshl_add_u64 v[88:89], v[68:69], 0, s[4:5]
	global_load_lds_dwordx4 v77, s[58:59]
	s_mov_b32 m0, s88
	s_nop 0
	global_load_lds_dwordx4 v[88:89], off
	s_mov_b32 m0, s89
	v_lshl_add_u64 v[88:89], v[70:71], 0, s[4:5]
	global_load_lds_dwordx4 v78, s[58:59]
	s_mov_b32 m0, s90
	s_mov_b64 s[4:5], 0x600
	global_load_lds_dwordx4 v[88:89], off
	s_mov_b32 m0, s91
	s_nop 0
	global_load_lds_dwordx4 v84, s[58:59]
	ds_read_b128 v[88:91], v79
	ds_read_b128 v[92:95], v81 offset:16384
	ds_read_b128 v[96:99], v81 offset:20480
	s_waitcnt lgkmcnt(0)
	v_mfma_f32_32x32x16_bf16 v[48:63], v[88:91], v[92:95], v[48:63]
	s_mov_b32 m0, s18
	v_mfma_f32_32x32x16_bf16 v[32:47], v[88:91], v[96:99], v[32:47]
	ds_read_b128 v[88:91], v79 offset:4096
	s_waitcnt lgkmcnt(0)
	v_mfma_f32_32x32x16_bf16 v[16:31], v[88:91], v[92:95], v[16:31]
	v_mfma_f32_32x32x16_bf16 v[0:15], v[88:91], v[96:99], v[0:15]
	ds_read_b128 v[88:91], v80
	ds_read_b128 v[92:95], v83 offset:16384
	ds_read_b128 v[96:99], v83 offset:20480
	s_waitcnt lgkmcnt(0)
	v_mfma_f32_32x32x16_bf16 v[48:63], v[88:91], v[92:95], v[48:63]
	v_mfma_f32_32x32x16_bf16 v[32:47], v[88:91], v[96:99], v[32:47]
	ds_read_b128 v[88:91], v80 offset:4096
	s_waitcnt lgkmcnt(0)
	v_mfma_f32_32x32x16_bf16 v[16:31], v[88:91], v[92:95], v[16:31]
	v_mfma_f32_32x32x16_bf16 v[0:15], v[88:91], v[96:99], v[0:15]
	ds_read_b128 v[88:91], v82
	ds_read_b128 v[92:95], v85 offset:16384
	ds_read_b128 v[96:99], v85 offset:20480
	s_waitcnt lgkmcnt(0)
	v_mfma_f32_32x32x16_bf16 v[48:63], v[88:91], v[92:95], v[48:63]
	v_mfma_f32_32x32x16_bf16 v[32:47], v[88:91], v[96:99], v[32:47]
	ds_read_b128 v[88:91], v82 offset:4096
	s_waitcnt lgkmcnt(0)
	v_mfma_f32_32x32x16_bf16 v[16:31], v[88:91], v[92:95], v[16:31]
	v_mfma_f32_32x32x16_bf16 v[0:15], v[88:91], v[96:99], v[0:15]
	ds_read_b128 v[88:91], v86
	ds_read_b128 v[92:95], v87 offset:16384
	ds_read_b128 v[96:99], v87 offset:20480
	ds_read_b128 v[144:147], v86 offset:4096
	s_waitcnt vmcnt(0)
	s_waitcnt vmcnt(0) lgkmcnt(0)
	s_barrier
	v_mfma_f32_32x32x16_bf16 v[48:63], v[88:91], v[92:95], v[48:63]
	v_mfma_f32_32x32x16_bf16 v[32:47], v[88:91], v[96:99], v[32:47]
	v_mfma_f32_32x32x16_bf16 v[16:31], v[144:147], v[92:95], v[16:31]
	v_mfma_f32_32x32x16_bf16 v[0:15], v[144:147], v[96:99], v[0:15]
	ds_read_b128 v[88:91], v79 offset:32768
	ds_read_b128 v[92:95], v81 offset:49152
	ds_read_b128 v[96:99], v81 offset:53248
	v_lshl_add_u64 v[140:141], v[64:65], 0, s[4:5]
	global_load_lds_dwordx4 v[140:141], off
	s_mov_b32 m0, s19
	v_lshl_add_u64 v[142:143], v[66:67], 0, s[4:5]
	global_load_lds_dwordx4 v76, s[60:61]
	s_mov_b32 m0, s22
	s_nop 0
	global_load_lds_dwordx4 v[142:143], off
	s_mov_b32 m0, s23
	v_lshl_add_u64 v[140:141], v[68:69], 0, s[4:5]
	global_load_lds_dwordx4 v77, s[60:61]
	s_mov_b32 m0, s29
	s_nop 0
	global_load_lds_dwordx4 v[140:141], off
	s_mov_b32 m0, s69
	v_lshl_add_u64 v[142:143], v[70:71], 0, s[4:5]
	global_load_lds_dwordx4 v78, s[60:61]
	s_mov_b32 m0, s70
	s_mov_b64 s[4:5], 0x680
	global_load_lds_dwordx4 v[142:143], off
	s_mov_b32 m0, s71
	s_nop 0
	global_load_lds_dwordx4 v84, s[60:61]
	s_waitcnt lgkmcnt(0)
	v_mfma_f32_32x32x16_bf16 v[48:63], v[88:91], v[92:95], v[48:63]
	s_mov_b32 m0, s84
	v_mfma_f32_32x32x16_bf16 v[32:47], v[88:91], v[96:99], v[32:47]
	ds_read_b128 v[88:91], v79 offset:36864
	s_waitcnt lgkmcnt(0)
	v_mfma_f32_32x32x16_bf16 v[16:31], v[88:91], v[92:95], v[16:31]
	v_mfma_f32_32x32x16_bf16 v[0:15], v[88:91], v[96:99], v[0:15]
	ds_read_b128 v[88:91], v80 offset:32768
	ds_read_b128 v[92:95], v83 offset:49152
	ds_read_b128 v[96:99], v83 offset:53248
	s_waitcnt lgkmcnt(0)
	v_mfma_f32_32x32x16_bf16 v[48:63], v[88:91], v[92:95], v[48:63]
	v_mfma_f32_32x32x16_bf16 v[32:47], v[88:91], v[96:99], v[32:47]
	ds_read_b128 v[88:91], v80 offset:36864
	s_waitcnt lgkmcnt(0)
	v_mfma_f32_32x32x16_bf16 v[16:31], v[88:91], v[92:95], v[16:31]
	v_mfma_f32_32x32x16_bf16 v[0:15], v[88:91], v[96:99], v[0:15]
	ds_read_b128 v[88:91], v82 offset:32768
	ds_read_b128 v[92:95], v85 offset:49152
	ds_read_b128 v[96:99], v85 offset:53248
	s_waitcnt lgkmcnt(0)
	v_mfma_f32_32x32x16_bf16 v[48:63], v[88:91], v[92:95], v[48:63]
	v_mfma_f32_32x32x16_bf16 v[32:47], v[88:91], v[96:99], v[32:47]
	ds_read_b128 v[88:91], v82 offset:36864
	s_waitcnt lgkmcnt(0)
	v_mfma_f32_32x32x16_bf16 v[16:31], v[88:91], v[92:95], v[16:31]
	v_mfma_f32_32x32x16_bf16 v[0:15], v[88:91], v[96:99], v[0:15]
	ds_read_b128 v[88:91], v86 offset:32768
	ds_read_b128 v[92:95], v87 offset:49152
	ds_read_b128 v[96:99], v87 offset:53248
	ds_read_b128 v[144:147], v86 offset:36864
	s_waitcnt vmcnt(0)
	s_waitcnt vmcnt(0) lgkmcnt(0)
	s_barrier
; #define WAIT_V0() asm volatile("s_waitcnt vmcnt(0)" ::: "memory")
; DI void gemm_core(char* smem, int nk, const char* Ab, const char* Bb, const unsigned (&aoff)[4], const unsigned (&boff)[4],
;                   f32x16 (&acc)[2][2]) {
;     ...
;   for (int kt = 0; kt < nk; ++kt) {
;     const int cur = kt & 1;
;     if (kt + 1 < nk) stage(cur ^ 1, kt + 1);
;     const char* sb = smem + cur * STAGE_B;
; #pragma unroll
;     for (int ks = 0; ks < 4; ++ks) {
;       bf16x8 af[2], bfr[2];
; #pragma unroll
;       for (int mb = 0; mb < 2; ++mb) af[mb] = *(const bf16x8*)(sb + a_base + mb * 4096 + xo[ks]);
; #pragma unroll
;       for (int nb = 0; nb < 2; ++nb) bfr[nb] = *(const bf16x8*)(sb + b_base + nb * 4096 + xo[ks]);
; #pragma unroll
;       for (int mb = 0; mb < 2; ++mb)
; #pragma unroll
;         for (int nb = 0; nb < 2; ++nb)
;           acc[mb][nb] = __builtin_amdgcn_mfma_f32_32x32x16_bf16(af[mb], bfr[nb], acc[mb][nb], 0, 0, 0);
;     }
;     WAIT_V0();
;     __syncthreads();
;   }
	v_mfma_f32_32x32x16_bf16 v[48:63], v[88:91], v[92:95], v[48:63]
	v_mfma_f32_32x32x16_bf16 v[32:47], v[88:91], v[96:99], v[32:47]
	v_mfma_f32_32x32x16_bf16 v[16:31], v[144:147], v[92:95], v[16:31]
	v_mfma_f32_32x32x16_bf16 v[0:15], v[144:147], v[96:99], v[0:15]
	ds_read_b128 v[88:91], v79
	ds_read_b128 v[92:95], v81 offset:16384
	ds_read_b128 v[96:99], v81 offset:20480
	v_lshl_add_u64 v[140:141], v[64:65], 0, s[4:5]
	global_load_lds_dwordx4 v[140:141], off
	s_mov_b32 m0, s85
	v_lshl_add_u64 v[142:143], v[66:67], 0, s[4:5]
	global_load_lds_dwordx4 v76, s[62:63]
	s_mov_b32 m0, s86
	s_nop 0
	global_load_lds_dwordx4 v[142:143], off
	s_mov_b32 m0, s87
	v_lshl_add_u64 v[140:141], v[68:69], 0, s[4:5]
	global_load_lds_dwordx4 v77, s[62:63]
	s_mov_b32 m0, s88
	s_nop 0
	global_load_lds_dwordx4 v[140:141], off
	s_mov_b32 m0, s89
	v_lshl_add_u64 v[142:143], v[70:71], 0, s[4:5]
	global_load_lds_dwordx4 v78, s[62:63]
	s_mov_b32 m0, s90
	s_mov_b64 s[4:5], 0x700
	global_load_lds_dwordx4 v[142:143], off
	s_mov_b32 m0, s91
	s_nop 0
	global_load_lds_dwordx4 v84, s[62:63]
	s_waitcnt lgkmcnt(0)
	v_mfma_f32_32x32x16_bf16 v[48:63], v[88:91], v[92:95], v[48:63]
	s_mov_b32 m0, s18
	v_mfma_f32_32x32x16_bf16 v[32:47], v[88:91], v[96:99], v[32:47]
	ds_read_b128 v[88:91], v79 offset:4096
	s_waitcnt lgkmcnt(0)
	v_mfma_f32_32x32x16_bf16 v[16:31], v[88:91], v[92:95], v[16:31]
	v_mfma_f32_32x32x16_bf16 v[0:15], v[88:91], v[96:99], v[0:15]
	ds_read_b128 v[88:91], v80
	ds_read_b128 v[92:95], v83 offset:16384
	ds_read_b128 v[96:99], v83 offset:20480
	s_waitcnt lgkmcnt(0)
	v_mfma_f32_32x32x16_bf16 v[48:63], v[88:91], v[92:95], v[48:63]
	v_mfma_f32_32x32x16_bf16 v[32:47], v[88:91], v[96:99], v[32:47]
	ds_read_b128 v[88:91], v80 offset:4096
	s_waitcnt lgkmcnt(0)
	v_mfma_f32_32x32x16_bf16 v[16:31], v[88:91], v[92:95], v[16:31]
	v_mfma_f32_32x32x16_bf16 v[0:15], v[88:91], v[96:99], v[0:15]
	ds_read_b128 v[88:91], v82
	ds_read_b128 v[92:95], v85 offset:16384
	ds_read_b128 v[96:99], v85 offset:20480
	s_waitcnt lgkmcnt(0)
	v_mfma_f32_32x32x16_bf16 v[48:63], v[88:91], v[92:95], v[48:63]
	v_mfma_f32_32x32x16_bf16 v[32:47], v[88:91], v[96:99], v[32:47]
	ds_read_b128 v[88:91], v82 offset:4096
	s_waitcnt lgkmcnt(0)
	v_mfma_f32_32x32x16_bf16 v[16:31], v[88:91], v[92:95], v[16:31]
	v_mfma_f32_32x32x16_bf16 v[0:15], v[88:91], v[96:99], v[0:15]
	ds_read_b128 v[88:91], v86
	ds_read_b128 v[92:95], v87 offset:16384
	ds_read_b128 v[96:99], v87 offset:20480
	ds_read_b128 v[144:147], v86 offset:4096
	s_waitcnt vmcnt(0)
	s_waitcnt vmcnt(0) lgkmcnt(0)
	s_barrier
	v_mfma_f32_32x32x16_bf16 v[48:63], v[88:91], v[92:95], v[48:63]
	v_mfma_f32_32x32x16_bf16 v[32:47], v[88:91], v[96:99], v[32:47]
	v_mfma_f32_32x32x16_bf16 v[16:31], v[144:147], v[92:95], v[16:31]
	v_mfma_f32_32x32x16_bf16 v[0:15], v[144:147], v[96:99], v[0:15]
	v_lshl_add_u64 v[88:89], v[64:65], 0, s[4:5]
	global_load_lds_dwordx4 v[88:89], off
	s_mov_b32 m0, s19
	v_lshl_add_u64 v[88:89], v[66:67], 0, s[4:5]
	global_load_lds_dwordx4 v76, s[64:65]
	s_mov_b32 m0, s22
	s_nop 0
	global_load_lds_dwordx4 v[88:89], off
	s_mov_b32 m0, s23
	v_lshl_add_u64 v[88:89], v[68:69], 0, s[4:5]
	global_load_lds_dwordx4 v77, s[64:65]
	s_mov_b32 m0, s29
	s_nop 0
	global_load_lds_dwordx4 v[88:89], off
	s_mov_b32 m0, s69
	v_lshl_add_u64 v[88:89], v[70:71], 0, s[4:5]
	global_load_lds_dwordx4 v78, s[64:65]
	s_mov_b32 m0, s70
	s_mov_b64 s[4:5], 0x780
	global_load_lds_dwordx4 v[88:89], off
	s_mov_b32 m0, s71
	v_lshl_add_u64 v[64:65], v[64:65], 0, s[4:5]
	global_load_lds_dwordx4 v84, s[64:65]
	ds_read_b128 v[88:91], v79 offset:32768
	ds_read_b128 v[92:95], v81 offset:49152
	ds_read_b128 v[96:99], v81 offset:53248
	s_waitcnt lgkmcnt(0)
	v_mfma_f32_32x32x16_bf16 v[48:63], v[88:91], v[92:95], v[48:63]
	s_mov_b32 m0, s84
	s_movk_i32 s4, 0x4000
	v_mfma_f32_32x32x16_bf16 v[32:47], v[88:91], v[96:99], v[32:47]
	ds_read_b128 v[88:91], v79 offset:36864
	s_waitcnt lgkmcnt(0)
	v_mfma_f32_32x32x16_bf16 v[16:31], v[88:91], v[92:95], v[16:31]
	v_mfma_f32_32x32x16_bf16 v[0:15], v[88:91], v[96:99], v[0:15]
	ds_read_b128 v[88:91], v80 offset:32768
	ds_read_b128 v[92:95], v83 offset:49152
	ds_read_b128 v[96:99], v83 offset:53248
	s_waitcnt lgkmcnt(0)
	v_mfma_f32_32x32x16_bf16 v[48:63], v[88:91], v[92:95], v[48:63]
	v_mfma_f32_32x32x16_bf16 v[32:47], v[88:91], v[96:99], v[32:47]
	ds_read_b128 v[88:91], v80 offset:36864
	s_waitcnt lgkmcnt(0)
	v_mfma_f32_32x32x16_bf16 v[16:31], v[88:91], v[92:95], v[16:31]
	v_mfma_f32_32x32x16_bf16 v[0:15], v[88:91], v[96:99], v[0:15]
	ds_read_b128 v[88:91], v82 offset:32768
	ds_read_b128 v[92:95], v85 offset:49152
	ds_read_b128 v[96:99], v85 offset:53248
	s_waitcnt lgkmcnt(0)
	v_mfma_f32_32x32x16_bf16 v[48:63], v[88:91], v[92:95], v[48:63]
	v_mfma_f32_32x32x16_bf16 v[32:47], v[88:91], v[96:99], v[32:47]
	ds_read_b128 v[88:91], v82 offset:36864
	s_waitcnt lgkmcnt(0)
	v_mfma_f32_32x32x16_bf16 v[16:31], v[88:91], v[92:95], v[16:31]
	v_mfma_f32_32x32x16_bf16 v[0:15], v[88:91], v[96:99], v[0:15]
	ds_read_b128 v[88:91], v86 offset:32768
	ds_read_b128 v[92:95], v87 offset:49152
	ds_read_b128 v[96:99], v87 offset:53248
	s_waitcnt lgkmcnt(0)
	v_mfma_f32_32x32x16_bf16 v[48:63], v[88:91], v[92:95], v[48:63]
	v_mfma_f32_32x32x16_bf16 v[32:47], v[88:91], v[96:99], v[32:47]
	ds_read_b128 v[88:91], v86 offset:36864
	s_waitcnt vmcnt(0)
	s_waitcnt vmcnt(0) lgkmcnt(0)
	s_barrier
; #define WAIT_V0() asm volatile("s_waitcnt vmcnt(0)" ::: "memory")
; DI void gemm_core(char* smem, int nk, const char* Ab, const char* Bb, const unsigned (&aoff)[4], const unsigned (&boff)[4],
;                   f32x16 (&acc)[2][2]) {
;     ...
;   for (int kt = 0; kt < nk; ++kt) {
;     const int cur = kt & 1;
;     if (kt + 1 < nk) stage(cur ^ 1, kt + 1);
;     const char* sb = smem + cur * STAGE_B;
; #pragma unroll
;     for (int ks = 0; ks < 4; ++ks) {
;       bf16x8 af[2], bfr[2];
; #pragma unroll
;       for (int mb = 0; mb < 2; ++mb) af[mb] = *(const bf16x8*)(sb + a_base + mb * 4096 + xo[ks]);
; #pragma unroll
;       for (int nb = 0; nb < 2; ++nb) bfr[nb] = *(const bf16x8*)(sb + b_base + nb * 4096 + xo[ks]);
; #pragma unroll
;       for (int mb = 0; mb < 2; ++mb)
; #pragma unroll
;         for (int nb = 0; nb < 2; ++nb)
;           acc[mb][nb] = __builtin_amdgcn_mfma_f32_32x32x16_bf16(af[mb], bfr[nb], acc[mb][nb], 0, 0, 0);
;     }
;     WAIT_V0();
;     __syncthreads();
;   }
	global_load_lds_dwordx4 v[64:65], off
	s_mov_b32 m0, s85
	v_lshl_add_u64 v[64:65], v[66:67], 0, s[6:7]
	global_load_lds_dwordx4 v76, s[66:67]
	s_mov_b32 m0, s86
	v_mfma_f32_32x32x16_bf16 v[16:31], v[88:91], v[92:95], v[16:31]
	global_load_lds_dwordx4 v[64:65], off
	s_mov_b32 m0, s87
	v_lshl_add_u64 v[64:65], v[68:69], 0, s[6:7]
	global_load_lds_dwordx4 v77, s[66:67]
	s_mov_b32 m0, s88
	v_mfma_f32_32x32x16_bf16 v[0:15], v[88:91], v[96:99], v[0:15]
	global_load_lds_dwordx4 v[64:65], off
	s_mov_b32 m0, s89
	v_lshl_add_u64 v[64:65], v[70:71], 0, s[6:7]
	global_load_lds_dwordx4 v78, s[66:67]
	s_mov_b32 m0, s90
	v_readlane_b32 s86, v254, 58
	global_load_lds_dwordx4 v[64:65], off
	s_mov_b32 m0, s91
	v_readlane_b32 s87, v254, 59
	global_load_lds_dwordx4 v84, s[66:67]
	ds_read_b128 v[64:67], v79
	ds_read_b128 v[68:71], v81 offset:16384
	ds_read_b128 v[88:91], v81 offset:20480
	s_waitcnt lgkmcnt(0)
	v_mfma_f32_32x32x16_bf16 v[48:63], v[64:67], v[68:71], v[48:63]
	v_mfma_f32_32x32x16_bf16 v[32:47], v[64:67], v[88:91], v[32:47]
	ds_read_b128 v[64:67], v79 offset:4096
	s_waitcnt lgkmcnt(0)
	v_mfma_f32_32x32x16_bf16 v[16:31], v[64:67], v[68:71], v[16:31]
	v_mfma_f32_32x32x16_bf16 v[0:15], v[64:67], v[88:91], v[0:15]
	ds_read_b128 v[64:67], v80
	ds_read_b128 v[68:71], v83 offset:16384
	ds_read_b128 v[88:91], v83 offset:20480
	s_waitcnt lgkmcnt(0)
	v_mfma_f32_32x32x16_bf16 v[48:63], v[64:67], v[68:71], v[48:63]
	v_mfma_f32_32x32x16_bf16 v[32:47], v[64:67], v[88:91], v[32:47]
	ds_read_b128 v[64:67], v80 offset:4096
	s_waitcnt lgkmcnt(0)
	v_mfma_f32_32x32x16_bf16 v[16:31], v[64:67], v[68:71], v[16:31]
	v_mfma_f32_32x32x16_bf16 v[0:15], v[64:67], v[88:91], v[0:15]
	ds_read_b128 v[64:67], v82
	ds_read_b128 v[68:71], v85 offset:16384
	ds_read_b128 v[88:91], v85 offset:20480
	s_waitcnt lgkmcnt(0)
	v_mfma_f32_32x32x16_bf16 v[48:63], v[64:67], v[68:71], v[48:63]
	v_mfma_f32_32x32x16_bf16 v[32:47], v[64:67], v[88:91], v[32:47]
	ds_read_b128 v[64:67], v82 offset:4096
	s_waitcnt lgkmcnt(0)
	v_mfma_f32_32x32x16_bf16 v[16:31], v[64:67], v[68:71], v[16:31]
	v_mfma_f32_32x32x16_bf16 v[0:15], v[64:67], v[88:91], v[0:15]
	ds_read_b128 v[64:67], v86
	ds_read_b128 v[68:71], v87 offset:16384
	ds_read_b128 v[88:91], v87 offset:20480
	ds_read_b128 v[144:147], v86 offset:4096
	s_waitcnt vmcnt(0)
	s_waitcnt vmcnt(0) lgkmcnt(0)
	s_barrier
	v_mfma_f32_32x32x16_bf16 v[48:63], v[64:67], v[68:71], v[48:63]
	v_mfma_f32_32x32x16_bf16 v[32:47], v[64:67], v[88:91], v[32:47]
	v_mfma_f32_32x32x16_bf16 v[16:31], v[144:147], v[68:71], v[16:31]
	v_mfma_f32_32x32x16_bf16 v[0:15], v[144:147], v[88:91], v[0:15]
	ds_read_b128 v[64:67], v79 offset:32768
	ds_read_b128 v[68:71], v81 offset:49152
	ds_read_b128 v[88:91], v81 offset:53248
	s_waitcnt lgkmcnt(1)
	v_mfma_f32_32x32x16_bf16 v[48:63], v[64:67], v[68:71], v[48:63]
	s_waitcnt lgkmcnt(0)
	v_mfma_f32_32x32x16_bf16 v[32:47], v[64:67], v[88:91], v[32:47]
	ds_read_b128 v[64:67], v79 offset:36864
	s_waitcnt lgkmcnt(0)
	v_mfma_f32_32x32x16_bf16 v[16:31], v[64:67], v[68:71], v[16:31]
	v_mfma_f32_32x32x16_bf16 v[0:15], v[64:67], v[88:91], v[0:15]
	ds_read_b128 v[64:67], v80 offset:32768
	ds_read_b128 v[68:71], v83 offset:49152
	ds_read_b128 v[76:79], v83 offset:53248
	s_waitcnt lgkmcnt(1)
	v_mfma_f32_32x32x16_bf16 v[48:63], v[64:67], v[68:71], v[48:63]
	s_waitcnt lgkmcnt(0)
	v_mfma_f32_32x32x16_bf16 v[32:47], v[64:67], v[76:79], v[32:47]
	ds_read_b128 v[64:67], v80 offset:36864
	s_waitcnt lgkmcnt(0)
	v_mfma_f32_32x32x16_bf16 v[16:31], v[64:67], v[68:71], v[16:31]
	v_mfma_f32_32x32x16_bf16 v[0:15], v[64:67], v[76:79], v[0:15]
	ds_read_b128 v[64:67], v82 offset:32768
	ds_read_b128 v[68:71], v85 offset:49152
	ds_read_b128 v[76:79], v85 offset:53248
	s_waitcnt lgkmcnt(1)
	v_mfma_f32_32x32x16_bf16 v[48:63], v[64:67], v[68:71], v[48:63]
	s_waitcnt lgkmcnt(0)
	v_mfma_f32_32x32x16_bf16 v[32:47], v[64:67], v[76:79], v[32:47]
	ds_read_b128 v[64:67], v82 offset:36864
	s_waitcnt lgkmcnt(0)
	v_mfma_f32_32x32x16_bf16 v[16:31], v[64:67], v[68:71], v[16:31]
	ds_read_b128 v[68:71], v87 offset:53248
	ds_read_b128 v[80:83], v87 offset:49152
	ds_read_b128 v[88:91], v86 offset:36864
	ds_read_b128 v[84:87], v86 offset:32768
	s_waitcnt vmcnt(0)
	s_waitcnt lgkmcnt(0)
	s_barrier
; DI int ltid() { int t = threadIdx.x; asm volatile("" : "+v"(t)); return t; }
; template <class F>
; DI void epi_foreach(const f32x16 (&acc)[2][2], F f) {
;   const int lane = ltid() & 63, w = ltid() >> 6;
;   const int wm = w >> 1, wn = w & 1;
; #pragma unroll
;   for (int mb = 0; mb < 2; ++mb)
; #pragma unroll
;     for (int nb = 0; nb < 2; ++nb)
; #pragma unroll
;       for (int r = 0; r < 16; ++r) {
;         const int row = wm * 64 + mb * 32 + (r & 3) + 8 * (r >> 2) + 4 * (lane >> 5);
;         const int col = wn * 64 + nb * 32 + (lane & 31);
;         f(row, col, acc[mb][nb][r]);
;         if ((r & 7) == 7) __builtin_amdgcn_sched_barrier(0);
;       }
; }
; DI void phase_up(const Params& P, int layer, char* smem) {
;     ...
;     epi_foreach(acc, [&](int row, int col, float v) __attribute__((always_inline)) { Cs[row * 136 + col] = f2bf(v); });
;     __syncthreads();
;     {
;       const int col = tid & 63, rb = tid >> 6;
;       const int cv = nt * 64 + col, cg_ = DFF + nt * 64 + col;
;       const float w0v = cw[cv], w1v = cw[5632 + cv], w2v = cw[2 * 5632 + cv], bv = cb[cv];
;       const float w0g = cw[cg_], w1g = cw[5632 + cg_], w2g = cw[2 * 5632 + cg_], bgt = cb[cg_];
;       for (int r = 2 + rb; r < 128; r += 4) {
	v_mfma_f32_32x32x16_bf16 v[48:63], v[84:87], v[80:83], v[48:63]
	v_mfma_f32_32x32x16_bf16 v[0:15], v[64:67], v[76:79], v[0:15]
	v_mov_b32_e32 v64, v161
	v_mov_b32_e32 v65, v161
	v_lshrrev_b32_e32 v67, 3, v64
	v_and_b32_e32 v67, 4, v67
	v_lshrrev_b32_e32 v66, 1, v65
	v_and_b32_e32 v64, 31, v64
	v_and_or_b32 v64, v65, 64, v64
	v_and_or_b32 v65, v66, s3, v67
	v_mul_lo_u32 v65, v65, s97
	s_nop 1
	v_cvt_pk_bf16_f32 v48, v48, s0
	v_lshl_add_u32 v64, v64, 1, v65
	ds_write_b16 v64, v48
	v_cvt_pk_bf16_f32 v48, v49, s0
	ds_write_b16 v64, v48 offset:272
	v_cvt_pk_bf16_f32 v48, v50, s0
	ds_write_b16 v64, v48 offset:544
	v_cvt_pk_bf16_f32 v48, v51, s0
	ds_write_b16 v64, v48 offset:816
	v_cvt_pk_bf16_f32 v48, v52, s0
	ds_write_b16 v64, v48 offset:2176
	v_cvt_pk_bf16_f32 v48, v53, s0
	ds_write_b16 v64, v48 offset:2448
	v_cvt_pk_bf16_f32 v48, v54, s0
	ds_write_b16 v64, v48 offset:2720
	v_cvt_pk_bf16_f32 v48, v55, s0
	v_mfma_f32_32x32x16_bf16 v[32:47], v[84:87], v[68:71], v[32:47]
	ds_write_b16 v64, v48 offset:2992
	v_mfma_f32_32x32x16_bf16 v[16:31], v[88:91], v[80:83], v[16:31]
	v_mfma_f32_32x32x16_bf16 v[0:15], v[88:91], v[68:71], v[0:15]
	v_cvt_pk_bf16_f32 v48, v56, s0
	ds_write_b16 v64, v48 offset:4352
	v_cvt_pk_bf16_f32 v48, v57, s0
	ds_write_b16 v64, v48 offset:4624
	v_cvt_pk_bf16_f32 v48, v58, s0
	ds_write_b16 v64, v48 offset:4896
	v_cvt_pk_bf16_f32 v48, v59, s0
	ds_write_b16 v64, v48 offset:5168
	v_cvt_pk_bf16_f32 v48, v60, s0
	ds_write_b16 v64, v48 offset:6528
	v_cvt_pk_bf16_f32 v48, v61, s0
	ds_write_b16 v64, v48 offset:6800
	v_cvt_pk_bf16_f32 v48, v62, s0
	ds_write_b16 v64, v48 offset:7072
	v_cvt_pk_bf16_f32 v48, v63, s0
	ds_write_b16 v64, v48 offset:7344
	v_cvt_pk_bf16_f32 v32, v32, s0
	ds_write_b16 v64, v32 offset:64
	v_cvt_pk_bf16_f32 v32, v33, s0
	ds_write_b16 v64, v32 offset:336
	v_cvt_pk_bf16_f32 v32, v34, s0
	ds_write_b16 v64, v32 offset:608
	v_cvt_pk_bf16_f32 v32, v35, s0
	ds_write_b16 v64, v32 offset:880
	v_cvt_pk_bf16_f32 v32, v36, s0
	ds_write_b16 v64, v32 offset:2240
	v_cvt_pk_bf16_f32 v32, v37, s0
	ds_write_b16 v64, v32 offset:2512
	v_cvt_pk_bf16_f32 v32, v38, s0
	ds_write_b16 v64, v32 offset:2784
	v_cvt_pk_bf16_f32 v32, v39, s0
	ds_write_b16 v64, v32 offset:3056
	v_cvt_pk_bf16_f32 v32, v40, s0
	ds_write_b16 v64, v32 offset:4416
	v_cvt_pk_bf16_f32 v32, v41, s0
	ds_write_b16 v64, v32 offset:4688
	v_cvt_pk_bf16_f32 v32, v42, s0
	ds_write_b16 v64, v32 offset:4960
	v_cvt_pk_bf16_f32 v32, v43, s0
	ds_write_b16 v64, v32 offset:5232
	v_cvt_pk_bf16_f32 v32, v44, s0
	ds_write_b16 v64, v32 offset:6592
	v_cvt_pk_bf16_f32 v32, v45, s0
	ds_write_b16 v64, v32 offset:6864
	v_cvt_pk_bf16_f32 v32, v46, s0
	ds_write_b16 v64, v32 offset:7136
	v_cvt_pk_bf16_f32 v32, v47, s0
	ds_write_b16 v64, v32 offset:7408
	v_cvt_pk_bf16_f32 v16, v16, s0
	ds_write_b16 v64, v16 offset:8704
	v_cvt_pk_bf16_f32 v16, v17, s0
	ds_write_b16 v64, v16 offset:8976
	v_cvt_pk_bf16_f32 v16, v18, s0
	ds_write_b16 v64, v16 offset:9248
	v_cvt_pk_bf16_f32 v16, v19, s0
	ds_write_b16 v64, v16 offset:9520
	v_cvt_pk_bf16_f32 v16, v20, s0
	ds_write_b16 v64, v16 offset:10880
	v_cvt_pk_bf16_f32 v16, v21, s0
	ds_write_b16 v64, v16 offset:11152
	v_cvt_pk_bf16_f32 v16, v22, s0
	ds_write_b16 v64, v16 offset:11424
	v_cvt_pk_bf16_f32 v16, v23, s0
	ds_write_b16 v64, v16 offset:11696
	v_cvt_pk_bf16_f32 v16, v24, s0
	ds_write_b16 v64, v16 offset:13056
	v_cvt_pk_bf16_f32 v16, v25, s0
	ds_write_b16 v64, v16 offset:13328
	v_cvt_pk_bf16_f32 v16, v26, s0
	ds_write_b16 v64, v16 offset:13600
	v_cvt_pk_bf16_f32 v16, v27, s0
	ds_write_b16 v64, v16 offset:13872
	v_cvt_pk_bf16_f32 v16, v28, s0
	ds_write_b16 v64, v16 offset:15232
	v_cvt_pk_bf16_f32 v16, v29, s0
	ds_write_b16 v64, v16 offset:15504
	v_cvt_pk_bf16_f32 v16, v30, s0
	ds_write_b16 v64, v16 offset:15776
	v_cvt_pk_bf16_f32 v16, v31, s0
	ds_write_b16 v64, v16 offset:16048
	v_cvt_pk_bf16_f32 v0, v0, s0
	ds_write_b16 v64, v0 offset:8768
	v_cvt_pk_bf16_f32 v0, v1, s0
	ds_write_b16 v64, v0 offset:9040
	v_cvt_pk_bf16_f32 v0, v2, s0
	ds_write_b16 v64, v0 offset:9312
	v_cvt_pk_bf16_f32 v0, v3, s0
	ds_write_b16 v64, v0 offset:9584
	v_cvt_pk_bf16_f32 v0, v4, s0
	ds_write_b16 v64, v0 offset:10944
	v_cvt_pk_bf16_f32 v0, v5, s0
	ds_write_b16 v64, v0 offset:11216
	v_cvt_pk_bf16_f32 v0, v6, s0
	ds_write_b16 v64, v0 offset:11488
	v_cvt_pk_bf16_f32 v0, v7, s0
	ds_write_b16 v64, v0 offset:11760
	v_cvt_pk_bf16_f32 v0, v8, s0
	ds_write_b16 v64, v0 offset:13120
	v_cvt_pk_bf16_f32 v0, v9, s0
	ds_write_b16 v64, v0 offset:13392
	v_cvt_pk_bf16_f32 v0, v10, s0
	ds_write_b16 v64, v0 offset:13664
	v_cvt_pk_bf16_f32 v0, v11, s0
	ds_write_b16 v64, v0 offset:13936
	v_cvt_pk_bf16_f32 v0, v12, s0
	ds_write_b16 v64, v0 offset:15296
	v_cvt_pk_bf16_f32 v0, v13, s0
	ds_write_b16 v64, v0 offset:15568
	v_cvt_pk_bf16_f32 v0, v14, s0
	ds_write_b16 v64, v0 offset:15840
	v_cvt_pk_bf16_f32 v0, v15, s0
	ds_write_b16 v64, v0 offset:16112
	s_waitcnt lgkmcnt(0)
	s_barrier
	s_and_saveexec_b64 s[18:19], s[40:41]
	s_mov_b32 s3, 0xb000
	s_cbranch_execz .LBB0_24
	v_add_u32_e32 v136, s21, v74
	v_lshlrev_b64 v[4:5], 2, v[136:137]
	v_lshl_add_u64 v[8:9], s[10:11], 0, v[4:5]
	v_or_b32_e32 v10, s21, v72
	v_lshlrev_b32_e32 v126, 1, v10
	v_lshl_add_u64 v[2:3], s[12:13], 0, v[4:5]
	v_add_co_u32_e32 v4, vcc, 0xb000, v8
	v_ashrrev_i32_e32 v11, 31, v10
	s_nop 0
	v_addc_co_u32_e32 v5, vcc, 0, v9, vcc
	v_lshl_add_u64 v[0:1], v[10:11], 1, s[86:87]
	v_add_co_u32_e32 v6, vcc, 0x5000, v8
	v_lshlrev_b64 v[10:11], 2, v[10:11]
	s_nop 0
	v_addc_co_u32_e32 v7, vcc, 0, v9, vcc
	v_lshl_add_u64 v[12:13], s[12:13], 0, v[10:11]
	v_lshl_add_u64 v[10:11], s[10:11], 0, v[10:11]
	global_load_dword v3, v[2:3], off
	s_mulk_i32 s20, 0x7e
	global_load_dword v5, v[4:5], off
	s_nop 0
	global_load_dword v7, v[6:7], off offset:2048
	s_nop 0
	global_load_dword v9, v[8:9], off
	s_mul_i32 s21, s68, 0x7a
	global_load_dword v2, v[12:13], off
	v_add_co_u32_e32 v12, vcc, s3, v10
	s_sub_i32 s29, s20, s21
	s_nop 0
	v_addc_co_u32_e32 v13, vcc, 0, v11, vcc
	global_load_dword v4, v[12:13], off
	v_add_co_u32_e32 v12, vcc, 0x5000, v10
	s_mov_b64 s[20:21], 0
	s_nop 0
	v_addc_co_u32_e32 v13, vcc, 0, v11, vcc
	global_load_dword v6, v[12:13], off offset:2048
	global_load_dword v8, v[10:11], off
	v_mov_b32_e32 v11, v73
	v_mul_u32_u24_e32 v10, 0x110, v73
	v_mov_b32_e32 v128, 0
	v_mov_b32_e32 v129, 0
	v_mov_b32_e32 v130, 0
	v_mov_b32_e32 v131, 0
	v_mov_b32_e32 v132, 0
	v_mov_b32_e32 v133, 0
	v_mov_b32_e32 v134, 0
	v_mov_b32_e32 v135, 0
	s_waitcnt vmcnt(0)
	v_readfirstlane_b32 s22, v73
	v_add_u32_e32 v10, v75, v10
	v_add_u32_e32 v127, 0x1600, v126
	s_lshl_b32 s22, s22, 1
	s_add_i32 s23, s29, s22
	s_mul_hi_i32 s21, s23, 0x1600
	s_mul_i32 s20, s23, 0x1600
	s_add_u32 s20, s20, s86
	s_addc_u32 s21, s21, s87
	s_branch .LBB0_28

; #define WAIT_V0() asm volatile("s_waitcnt vmcnt(0)" ::: "memory")
; DI int glds_row(int i) { const int tid = ltid(); return ((tid >> 6) * 4 + i) * 8 + ((tid & 63) >> 3); }
; DI int glds_chunk(int row) { return (ltid() & 7) ^ ((row >> 1) & 7); }
; DI void gemm_core(char* smem, int nk, const char* Ab, const char* Bb, const unsigned (&aoff)[4], const unsigned (&boff)[4],
;                   f32x16 (&acc)[2][2]) {
;     ...
;   auto stage = [&](int buf, int kt) __attribute__((always_inline)) {
;     const char* ak = Ab + kt * 128;
;     const char* bk = Bb + kt * 128;
;     char* sa = smem + buf * STAGE_B + w * 4096;
; #pragma unroll
;     for (int i = 0; i < 4; ++i) {
;       __builtin_amdgcn_global_load_lds((const unsigned*)(ak + aoff[i]), (unsigned*)(sa + i * 1024), 16, 0, 0);
;       __builtin_amdgcn_global_load_lds((const unsigned*)(bk + boff[i]), (unsigned*)(sa + 16384 + i * 1024), 16, 0, 0);
;     }
;   };
;   stage(0, 0);
;   WAIT_V0();
;   __syncthreads();
; DI void gemm_tile(char* smem, int nk, const bf16* A, int lda, int m0, const bf16* Bt, int ldb, int n0, f32x16 (&acc)[2][2]) {
;   unsigned aoff[4], boff[4];
; #pragma unroll
;   for (int i = 0; i < 4; ++i) {
;     const int row = glds_row(i), ch = glds_chunk(row);
;     aoff[i] = (unsigned)((row * lda + ch * 8) * 2);
;     boff[i] = (unsigned)((row * ldb + ch * 8) * 2);
;   }
;   gemm_core(smem, nk, (const char*)(A + (size_t)m0 * lda), (const char*)(Bt + (size_t)n0 * ldb), aoff, boff, acc);
.LBB0_436:
	v_mov_b32_e32 v0, v161
	s_ashr_i32 s0, s14, 3
	v_lshrrev_b32_e32 v1, 1, v0
	v_lshrrev_b32_e32 v2, 3, v0
	v_bfe_u32 v0, v0, 3, 3
	v_and_or_b32 v0, v1, s9, v0
	v_mov_b32_e32 v1, v161
	v_bfe_u32 v2, v2, 1, 2
	v_xor_b32_e32 v1, v2, v1
	v_lshlrev_b32_e32 v0, 11, v0
	v_lshlrev_b32_e32 v1, 4, v1
	v_and_or_b32 v136, v1, s92, v0
	v_mov_b32_e32 v0, v161
	s_and_b32 s1, s0, 0xffffffc0
	v_ashrrev_i32_e32 v1, 1, v0
	v_and_b32_e32 v1, 0xffffffe0, v1
	v_bfe_u32 v0, v0, 3, 3
	v_or3_b32 v0, v0, v1, 8
	v_mov_b32_e32 v1, v161
	v_lshrrev_b32_e32 v2, 1, v0
	v_xor_b32_e32 v1, v2, v1
	v_lshlrev_b32_e32 v0, 11, v0
	v_lshlrev_b32_e32 v1, 4, v1
	v_and_or_b32 v0, v1, s92, v0
	v_mov_b32_e32 v1, v161
	s_lshl_b32 s10, s0, 1
	v_lshrrev_b32_e32 v2, 1, v1
	v_lshrrev_b32_e32 v3, 3, v1
	v_bfe_u32 v1, v1, 3, 3
	v_and_or_b32 v1, v2, s9, v1
	v_mov_b32_e32 v2, v161
	s_bfe_u32 s11, s0, 0x10005
	v_bfe_u32 v3, v3, 1, 2
	s_and_b32 s10, s10, 62
	s_or_b32 s1, s11, s1
	v_xor_b32_e32 v2, v3, v2
	s_or_b32 s1, s1, s10
	s_or_b32 s10, s0, 63
	v_lshlrev_b32_e32 v2, 4, v2
	s_cmpk_lt_i32 s10, 0x2c0
	v_lshlrev_b32_e32 v1, 11, v1
	v_and_b32_e32 v2, 0x70, v2
	s_cselect_b32 s1, s1, s0
	v_or3_b32 v2, v1, v2, s8
	v_mov_b32_e32 v1, v161
	s_mul_hi_i32 s10, s1, 0x2e8ba2e9
	s_lshr_b32 s11, s10, 31
	v_ashrrev_i32_e32 v3, 1, v1
	s_ashr_i32 s10, s10, 1
	v_and_b32_e32 v3, 0xffffffe0, v3
	v_bfe_u32 v1, v1, 3, 3
	s_and_b32 s0, s13, 0xc0
	s_add_i32 s10, s10, s11
	v_or3_b32 v1, v1, v3, 24
	v_mov_b32_e32 v3, v161
	s_add_i32 s15, s10, s0
	s_bfe_i32 s11, s14, 0x10002
	s_mul_i32 s10, s10, 11
	v_lshrrev_b32_e32 v4, 1, v1
	s_and_b32 s11, s11, 11
	s_sub_i32 s1, s1, s10
	v_xor_b32_e32 v3, v4, v3
	s_lshl_b32 s0, s15, 7
	s_add_i32 s1, s1, s11
	v_lshlrev_b32_e32 v1, 11, v1
	v_lshlrev_b32_e32 v3, 4, v3
	v_mov_b32_e32 v12, v161
	s_lshl_b32 s10, s1, 7
	v_and_or_b32 v4, v3, s92, v1
	s_ashr_i32 s1, s0, 31
	s_lshl_b64 s[16:17], s[0:1], 11
	v_and_b32_e32 v1, 31, v12
	v_lshrrev_b32_e32 v5, 1, v12
	v_and_or_b32 v1, v5, s6, v1
	s_add_u32 s16, s84, s16
	v_lshlrev_b32_e32 v112, 7, v1
	v_lshlrev_b32_e32 v1, 6, v12
	s_addc_u32 s17, s85, s17
	s_ashr_i32 s11, s10, 31
	v_and_b32_e32 v89, 0xfffff000, v1
	s_lshl_b64 s[18:19], s[10:11], 11
	v_add_u32_e32 v88, 0x4000, v89
	v_readfirstlane_b32 s20, v89
	s_add_u32 s18, s2, s18
	s_mov_b32 m0, s20
	v_readfirstlane_b32 s21, v88
	v_or_b32_e32 v90, 0x400, v89
	s_addc_u32 s19, s12, s19
	global_load_lds_dwordx4 v136, s[16:17]
	s_mov_b32 m0, s21
	v_readfirstlane_b32 s22, v90
	v_add_u32_e32 v91, 0x4400, v89
	global_load_lds_dwordx4 v136, s[18:19]
	s_mov_b32 m0, s22
	v_readfirstlane_b32 s23, v91
	v_or_b32_e32 v92, 0x800, v89
	global_load_lds_dwordx4 v0, s[16:17]
	s_mov_b32 m0, s23
	v_readfirstlane_b32 s28, v92
	v_add_u32_e32 v93, 0x4800, v89
	global_load_lds_dwordx4 v0, s[18:19]
	s_mov_b32 m0, s28
	v_readfirstlane_b32 s29, v93
	v_or_b32_e32 v94, 0xc00, v89
	global_load_lds_dwordx4 v2, s[16:17]
	s_mov_b32 m0, s29
	v_readfirstlane_b32 s40, v94
	v_add_u32_e32 v95, 0x4c00, v89
	v_lshrrev_b32_e32 v3, 5, v12
	v_bfe_u32 v99, v12, 1, 3
	global_load_lds_dwordx4 v2, s[18:19]
	s_mov_b32 m0, s40
	v_readfirstlane_b32 s41, v95
	v_add_u32_e32 v97, 0x8000, v89
	v_bitop3_b32 v3, v3, v99, 1 bitop3:0x6c
	v_lshl_add_u64 v[64:65], s[16:17], 0, v[136:137]
	v_mov_b32_e32 v1, v137
	global_load_lds_dwordx4 v4, s[16:17]
	s_mov_b32 m0, s41
	v_add_u32_e32 v96, 0xc000, v89
	v_readfirstlane_b32 s42, v97
	v_lshlrev_b32_e32 v6, 4, v3
	v_lshl_add_u64 v[66:67], s[18:19], 0, v[136:137]
	v_lshl_add_u64 v[68:69], s[16:17], 0, v[0:1]
	v_lshl_add_u64 v[70:71], s[18:19], 0, v[0:1]
	v_mov_b32_e32 v3, v137
	global_load_lds_dwordx4 v4, s[18:19]
	v_lshl_add_u64 v[0:1], v[64:65], 0, s[94:95]
	s_mov_b32 m0, s42
	v_readfirstlane_b32 s43, v96
	v_add_u32_e32 v98, 0x8400, v89
	v_lshl_add_u64 v[72:73], s[16:17], 0, v[2:3]
	v_lshl_add_u64 v[74:75], s[18:19], 0, v[2:3]
	global_load_lds_dwordx4 v[0:1], off
	v_lshl_add_u64 v[0:1], v[66:67], 0, s[94:95]
	s_mov_b32 m0, s43
	v_readfirstlane_b32 s44, v98
	v_add_u32_e32 v2, 0xc400, v89
	v_mov_b32_e32 v5, v137
	global_load_lds_dwordx4 v[0:1], off
	v_lshl_add_u64 v[0:1], v[68:69], 0, s[94:95]
	s_mov_b32 m0, s44
	v_readfirstlane_b32 s1, v2
	v_add_u32_e32 v2, 0x8800, v89
	v_lshl_add_u64 v[76:77], s[16:17], 0, v[4:5]
	global_load_lds_dwordx4 v[0:1], off
	v_lshl_add_u64 v[0:1], v[70:71], 0, s[94:95]
	s_mov_b32 m0, s1
	v_readfirstlane_b32 s16, v2
	v_add_u32_e32 v2, 0xc800, v89
	global_load_lds_dwordx4 v[0:1], off
	v_lshl_add_u64 v[0:1], v[72:73], 0, s[94:95]
	s_mov_b32 m0, s16
	v_readfirstlane_b32 s17, v2
	v_add_u32_e32 v2, 0x8c00, v89
	v_lshl_add_u64 v[78:79], s[18:19], 0, v[4:5]
	global_load_lds_dwordx4 v[0:1], off
	v_lshl_add_u64 v[0:1], v[74:75], 0, s[94:95]
	s_mov_b32 m0, s17
	v_readfirstlane_b32 s18, v2
	v_add_u32_e32 v2, 0xcc00, v89
	global_load_lds_dwordx4 v[0:1], off
	v_lshl_add_u64 v[0:1], v[76:77], 0, s[94:95]
	s_mov_b32 m0, s18
	v_readfirstlane_b32 s19, v2
	global_load_lds_dwordx4 v[0:1], off
	v_lshl_add_u64 v[0:1], v[78:79], 0, s[94:95]
	s_mov_b32 m0, s19
	v_or_b32_e32 v80, v112, v6
	global_load_lds_dwordx4 v[0:1], off
	s_waitcnt vmcnt(8)
	s_waitcnt vmcnt(8) lgkmcnt(0)
	s_barrier
; #define WAIT_V0() asm volatile("s_waitcnt vmcnt(0)" ::: "memory")
; DI void gemm_core(char* smem, int nk, const char* Ab, const char* Bb, const unsigned (&aoff)[4], const unsigned (&boff)[4],
;                   f32x16 (&acc)[2][2]) {
;     ...
;   for (int kt = 0; kt < nk; ++kt) {
;     const int cur = kt & 1;
;     if (kt + 1 < nk) stage(cur ^ 1, kt + 1);
;     const char* sb = smem + cur * STAGE_B;
; #pragma unroll
;     for (int ks = 0; ks < 4; ++ks) {
;       bf16x8 af[2], bfr[2];
; #pragma unroll
;       for (int mb = 0; mb < 2; ++mb) af[mb] = *(const bf16x8*)(sb + a_base + mb * 4096 + xo[ks]);
; #pragma unroll
;       for (int nb = 0; nb < 2; ++nb) bfr[nb] = *(const bf16x8*)(sb + b_base + nb * 4096 + xo[ks]);
; #pragma unroll
;       for (int mb = 0; mb < 2; ++mb)
; #pragma unroll
;         for (int nb = 0; nb < 2; ++nb)
;           acc[mb][nb] = __builtin_amdgcn_mfma_f32_32x32x16_bf16(af[mb], bfr[nb], acc[mb][nb], 0, 0, 0);
;     }
;     WAIT_V0();
;     __syncthreads();
;   }
	ds_read_b128 v[0:3], v80
	v_lshlrev_b32_e32 v4, 7, v12
	v_and_b32_e32 v113, 0x2f80, v4
	v_or_b32_e32 v82, v113, v6
	ds_read_b128 v[4:7], v82 offset:16384
	ds_read_b128 v[8:11], v82 offset:20480
	s_waitcnt lgkmcnt(0)
	v_mfma_f32_32x32x16_bf16 v[48:63], v[0:3], v[4:7], 0
	v_bfe_u32 v114, v12, 5, 1
	s_mov_b32 m0, s20
	v_mfma_f32_32x32x16_bf16 v[32:47], v[0:3], v[8:11], 0
	ds_read_b128 v[0:3], v80 offset:4096
	s_waitcnt lgkmcnt(0)
	v_mfma_f32_32x32x16_bf16 v[16:31], v[0:3], v[4:7], 0
	v_bitop3_b32 v4, v114, v99, 2 bitop3:0x36
	v_lshlrev_b32_e32 v83, 4, v4
	v_or_b32_e32 v81, v112, v83
	ds_read_b128 v[84:87], v81
	v_or_b32_e32 v83, v113, v83
	ds_read_b128 v[100:103], v83 offset:16384
	ds_read_b128 v[104:107], v83 offset:20480
	s_waitcnt lgkmcnt(0)
	v_mfma_f32_32x32x16_bf16 v[48:63], v[84:87], v[100:103], v[48:63]
	v_mfma_f32_32x32x16_bf16 v[32:47], v[84:87], v[104:107], v[32:47]
	ds_read_b128 v[84:87], v81 offset:4096
	v_mfma_f32_32x32x16_bf16 v[0:15], v[0:3], v[8:11], 0
	s_waitcnt lgkmcnt(0)
	v_mfma_f32_32x32x16_bf16 v[16:31], v[84:87], v[100:103], v[16:31]
	v_bitop3_b32 v100, v114, v99, 4 bitop3:0x36
	v_lshlrev_b32_e32 v108, 4, v100
	v_mfma_f32_32x32x16_bf16 v[0:15], v[84:87], v[104:107], v[0:15]
	v_or_b32_e32 v84, v112, v108
	ds_read_b128 v[100:103], v84
	v_or_b32_e32 v85, v113, v108
	ds_read_b128 v[104:107], v85 offset:16384
	ds_read_b128 v[108:111], v85 offset:20480
	v_bitop3_b32 v86, v114, v99, 6 bitop3:0x36
	v_lshlrev_b32_e32 v87, 4, v86
	s_waitcnt lgkmcnt(0)
	v_mfma_f32_32x32x16_bf16 v[48:63], v[100:103], v[104:107], v[48:63]
	v_or_b32_e32 v86, v112, v87
	v_or_b32_e32 v87, v113, v87
	v_mfma_f32_32x32x16_bf16 v[32:47], v[100:103], v[108:111], v[32:47]
	ds_read_b128 v[100:103], v84 offset:4096
	s_waitcnt lgkmcnt(0)
	v_mfma_f32_32x32x16_bf16 v[16:31], v[100:103], v[104:107], v[16:31]
	ds_read_b128 v[104:107], v87 offset:16384
	v_mfma_f32_32x32x16_bf16 v[0:15], v[100:103], v[108:111], v[0:15]
	ds_read_b128 v[100:103], v86
	ds_read_b128 v[108:111], v87 offset:20480
	ds_read_b128 v[120:123], v86 offset:4096
	s_waitcnt vmcnt(0)
	s_waitcnt vmcnt(0) lgkmcnt(0)
	s_barrier
	v_mfma_f32_32x32x16_bf16 v[48:63], v[100:103], v[104:107], v[48:63]
	v_mfma_f32_32x32x16_bf16 v[32:47], v[100:103], v[108:111], v[32:47]
	v_mfma_f32_32x32x16_bf16 v[16:31], v[120:123], v[104:107], v[16:31]
	v_mfma_f32_32x32x16_bf16 v[0:15], v[120:123], v[108:111], v[0:15]
	ds_read_b128 v[100:103], v80 offset:32768
	ds_read_b128 v[104:107], v82 offset:49152
	ds_read_b128 v[108:111], v82 offset:53248
	v_lshl_add_u64 v[116:117], v[64:65], 0, s[36:37]
	global_load_lds_dwordx4 v[116:117], off
	v_lshl_add_u64 v[118:119], v[66:67], 0, s[36:37]
	s_mov_b32 m0, s21
	s_nop 0
	global_load_lds_dwordx4 v[118:119], off
	v_lshl_add_u64 v[116:117], v[68:69], 0, s[36:37]
	s_mov_b32 m0, s22
	s_nop 0
	global_load_lds_dwordx4 v[116:117], off
	v_lshl_add_u64 v[118:119], v[70:71], 0, s[36:37]
	s_mov_b32 m0, s23
	s_nop 0
	global_load_lds_dwordx4 v[118:119], off
	v_lshl_add_u64 v[116:117], v[72:73], 0, s[36:37]
	s_mov_b32 m0, s28
	s_nop 0
	global_load_lds_dwordx4 v[116:117], off
	v_lshl_add_u64 v[118:119], v[74:75], 0, s[36:37]
	s_mov_b32 m0, s29
	s_nop 0
	global_load_lds_dwordx4 v[118:119], off
	v_lshl_add_u64 v[116:117], v[76:77], 0, s[36:37]
	s_mov_b32 m0, s40
	s_nop 0
	global_load_lds_dwordx4 v[116:117], off
	v_lshl_add_u64 v[118:119], v[78:79], 0, s[36:37]
	s_mov_b32 m0, s41
	s_nop 0
	global_load_lds_dwordx4 v[118:119], off
	s_waitcnt lgkmcnt(0)
	v_mfma_f32_32x32x16_bf16 v[48:63], v[100:103], v[104:107], v[48:63]
	s_mov_b32 m0, s42
	v_mfma_f32_32x32x16_bf16 v[32:47], v[100:103], v[108:111], v[32:47]
	ds_read_b128 v[100:103], v80 offset:36864
	s_waitcnt lgkmcnt(0)
	v_mfma_f32_32x32x16_bf16 v[16:31], v[100:103], v[104:107], v[16:31]
	v_mfma_f32_32x32x16_bf16 v[0:15], v[100:103], v[108:111], v[0:15]
	ds_read_b128 v[100:103], v81 offset:32768
	ds_read_b128 v[104:107], v83 offset:49152
	ds_read_b128 v[108:111], v83 offset:53248
	s_waitcnt lgkmcnt(0)
	v_mfma_f32_32x32x16_bf16 v[48:63], v[100:103], v[104:107], v[48:63]
	v_mfma_f32_32x32x16_bf16 v[32:47], v[100:103], v[108:111], v[32:47]
	ds_read_b128 v[100:103], v81 offset:36864
	s_waitcnt lgkmcnt(0)
	v_mfma_f32_32x32x16_bf16 v[16:31], v[100:103], v[104:107], v[16:31]
	v_mfma_f32_32x32x16_bf16 v[0:15], v[100:103], v[108:111], v[0:15]
	ds_read_b128 v[100:103], v84 offset:32768
	ds_read_b128 v[104:107], v85 offset:49152
	ds_read_b128 v[108:111], v85 offset:53248
	s_waitcnt lgkmcnt(0)
	v_mfma_f32_32x32x16_bf16 v[48:63], v[100:103], v[104:107], v[48:63]
	v_mfma_f32_32x32x16_bf16 v[32:47], v[100:103], v[108:111], v[32:47]
	ds_read_b128 v[100:103], v84 offset:36864
	s_waitcnt lgkmcnt(0)
	v_mfma_f32_32x32x16_bf16 v[16:31], v[100:103], v[104:107], v[16:31]
	v_mfma_f32_32x32x16_bf16 v[0:15], v[100:103], v[108:111], v[0:15]
	ds_read_b128 v[100:103], v86 offset:32768
	ds_read_b128 v[104:107], v87 offset:49152
	ds_read_b128 v[108:111], v87 offset:53248
	ds_read_b128 v[120:123], v86 offset:36864
	s_waitcnt vmcnt(0)
	s_waitcnt vmcnt(0) lgkmcnt(0)
	s_barrier
; #define WAIT_V0() asm volatile("s_waitcnt vmcnt(0)" ::: "memory")
; DI void gemm_core(char* smem, int nk, const char* Ab, const char* Bb, const unsigned (&aoff)[4], const unsigned (&boff)[4],
;                   f32x16 (&acc)[2][2]) {
;     ...
;   for (int kt = 0; kt < nk; ++kt) {
;     const int cur = kt & 1;
;     if (kt + 1 < nk) stage(cur ^ 1, kt + 1);
;     const char* sb = smem + cur * STAGE_B;
; #pragma unroll
;     for (int ks = 0; ks < 4; ++ks) {
;       bf16x8 af[2], bfr[2];
; #pragma unroll
;       for (int mb = 0; mb < 2; ++mb) af[mb] = *(const bf16x8*)(sb + a_base + mb * 4096 + xo[ks]);
; #pragma unroll
;       for (int nb = 0; nb < 2; ++nb) bfr[nb] = *(const bf16x8*)(sb + b_base + nb * 4096 + xo[ks]);
; #pragma unroll
;       for (int mb = 0; mb < 2; ++mb)
; #pragma unroll
;         for (int nb = 0; nb < 2; ++nb)
;           acc[mb][nb] = __builtin_amdgcn_mfma_f32_32x32x16_bf16(af[mb], bfr[nb], acc[mb][nb], 0, 0, 0);
;     }
;     WAIT_V0();
;     __syncthreads();
;   }
	v_mfma_f32_32x32x16_bf16 v[48:63], v[100:103], v[104:107], v[48:63]
	v_mfma_f32_32x32x16_bf16 v[32:47], v[100:103], v[108:111], v[32:47]
	v_mfma_f32_32x32x16_bf16 v[16:31], v[120:123], v[104:107], v[16:31]
	v_mfma_f32_32x32x16_bf16 v[0:15], v[120:123], v[108:111], v[0:15]
	ds_read_b128 v[100:103], v80
	ds_read_b128 v[104:107], v82 offset:16384
	ds_read_b128 v[108:111], v82 offset:20480
	v_lshl_add_u64 v[116:117], v[64:65], 0, s[38:39]
	global_load_lds_dwordx4 v[116:117], off
	v_lshl_add_u64 v[118:119], v[66:67], 0, s[38:39]
	s_mov_b32 m0, s43
	s_nop 0
	global_load_lds_dwordx4 v[118:119], off
	v_lshl_add_u64 v[116:117], v[68:69], 0, s[38:39]
	s_mov_b32 m0, s44
	s_nop 0
	global_load_lds_dwordx4 v[116:117], off
	v_lshl_add_u64 v[118:119], v[70:71], 0, s[38:39]
	s_mov_b32 m0, s1
	s_nop 0
	global_load_lds_dwordx4 v[118:119], off
	v_lshl_add_u64 v[116:117], v[72:73], 0, s[38:39]
	s_mov_b32 m0, s16
	s_nop 0
	global_load_lds_dwordx4 v[116:117], off
	v_lshl_add_u64 v[118:119], v[74:75], 0, s[38:39]
	s_mov_b32 m0, s17
	s_nop 0
	global_load_lds_dwordx4 v[118:119], off
	v_lshl_add_u64 v[116:117], v[76:77], 0, s[38:39]
	s_mov_b32 m0, s18
	s_nop 0
	global_load_lds_dwordx4 v[116:117], off
	v_lshl_add_u64 v[118:119], v[78:79], 0, s[38:39]
	s_mov_b32 m0, s19
	s_nop 0
	global_load_lds_dwordx4 v[118:119], off
	s_waitcnt lgkmcnt(0)
	v_mfma_f32_32x32x16_bf16 v[48:63], v[100:103], v[104:107], v[48:63]
	s_mov_b32 m0, s20
	v_mfma_f32_32x32x16_bf16 v[32:47], v[100:103], v[108:111], v[32:47]
	ds_read_b128 v[100:103], v80 offset:4096
	s_waitcnt lgkmcnt(0)
	v_mfma_f32_32x32x16_bf16 v[16:31], v[100:103], v[104:107], v[16:31]
	v_mfma_f32_32x32x16_bf16 v[0:15], v[100:103], v[108:111], v[0:15]
	ds_read_b128 v[100:103], v81
	ds_read_b128 v[104:107], v83 offset:16384
	ds_read_b128 v[108:111], v83 offset:20480
	s_waitcnt lgkmcnt(0)
	v_mfma_f32_32x32x16_bf16 v[48:63], v[100:103], v[104:107], v[48:63]
	v_mfma_f32_32x32x16_bf16 v[32:47], v[100:103], v[108:111], v[32:47]
	ds_read_b128 v[100:103], v81 offset:4096
	s_waitcnt lgkmcnt(0)
	v_mfma_f32_32x32x16_bf16 v[16:31], v[100:103], v[104:107], v[16:31]
	v_mfma_f32_32x32x16_bf16 v[0:15], v[100:103], v[108:111], v[0:15]
	ds_read_b128 v[100:103], v84
	ds_read_b128 v[104:107], v85 offset:16384
	ds_read_b128 v[108:111], v85 offset:20480
	s_waitcnt lgkmcnt(0)
	v_mfma_f32_32x32x16_bf16 v[48:63], v[100:103], v[104:107], v[48:63]
	v_mfma_f32_32x32x16_bf16 v[32:47], v[100:103], v[108:111], v[32:47]
	ds_read_b128 v[100:103], v84 offset:4096
	s_waitcnt lgkmcnt(0)
	v_mfma_f32_32x32x16_bf16 v[16:31], v[100:103], v[104:107], v[16:31]
	v_mfma_f32_32x32x16_bf16 v[0:15], v[100:103], v[108:111], v[0:15]
	ds_read_b128 v[100:103], v86
	ds_read_b128 v[104:107], v87 offset:16384
	ds_read_b128 v[108:111], v87 offset:20480
	ds_read_b128 v[120:123], v86 offset:4096
	s_waitcnt vmcnt(0)
	s_waitcnt vmcnt(0) lgkmcnt(0)
	s_barrier
	v_mfma_f32_32x32x16_bf16 v[48:63], v[100:103], v[104:107], v[48:63]
	v_mfma_f32_32x32x16_bf16 v[32:47], v[100:103], v[108:111], v[32:47]
	v_mfma_f32_32x32x16_bf16 v[16:31], v[120:123], v[104:107], v[16:31]
	v_mfma_f32_32x32x16_bf16 v[0:15], v[120:123], v[108:111], v[0:15]
	ds_read_b128 v[100:103], v80 offset:32768
	ds_read_b128 v[104:107], v82 offset:49152
	ds_read_b128 v[108:111], v82 offset:53248
	v_lshl_add_u64 v[116:117], v[64:65], 0, s[30:31]
	global_load_lds_dwordx4 v[116:117], off
	v_lshl_add_u64 v[118:119], v[66:67], 0, s[30:31]
	s_mov_b32 m0, s21
	s_nop 0
	global_load_lds_dwordx4 v[118:119], off
	v_lshl_add_u64 v[116:117], v[68:69], 0, s[30:31]
	s_mov_b32 m0, s22
	s_nop 0
	global_load_lds_dwordx4 v[116:117], off
	v_lshl_add_u64 v[118:119], v[70:71], 0, s[30:31]
	s_mov_b32 m0, s23
	s_nop 0
	global_load_lds_dwordx4 v[118:119], off
	v_lshl_add_u64 v[116:117], v[72:73], 0, s[30:31]
	s_mov_b32 m0, s28
	s_nop 0
	global_load_lds_dwordx4 v[116:117], off
	v_lshl_add_u64 v[118:119], v[74:75], 0, s[30:31]
	s_mov_b32 m0, s29
	s_nop 0
	global_load_lds_dwordx4 v[118:119], off
	v_lshl_add_u64 v[116:117], v[76:77], 0, s[30:31]
	s_mov_b32 m0, s40
	s_nop 0
	global_load_lds_dwordx4 v[116:117], off
	v_lshl_add_u64 v[118:119], v[78:79], 0, s[30:31]
	s_mov_b32 m0, s41
	s_nop 0
	global_load_lds_dwordx4 v[118:119], off
	s_waitcnt lgkmcnt(0)
	v_mfma_f32_32x32x16_bf16 v[48:63], v[100:103], v[104:107], v[48:63]
	s_mov_b32 m0, s42
	v_mfma_f32_32x32x16_bf16 v[32:47], v[100:103], v[108:111], v[32:47]
	ds_read_b128 v[100:103], v80 offset:36864
	s_waitcnt lgkmcnt(0)
	v_mfma_f32_32x32x16_bf16 v[16:31], v[100:103], v[104:107], v[16:31]
	v_mfma_f32_32x32x16_bf16 v[0:15], v[100:103], v[108:111], v[0:15]
	ds_read_b128 v[100:103], v81 offset:32768
	ds_read_b128 v[104:107], v83 offset:49152
	ds_read_b128 v[108:111], v83 offset:53248
	s_waitcnt lgkmcnt(0)
	v_mfma_f32_32x32x16_bf16 v[48:63], v[100:103], v[104:107], v[48:63]
	v_mfma_f32_32x32x16_bf16 v[32:47], v[100:103], v[108:111], v[32:47]
	ds_read_b128 v[100:103], v81 offset:36864
	s_waitcnt lgkmcnt(0)
	v_mfma_f32_32x32x16_bf16 v[16:31], v[100:103], v[104:107], v[16:31]
	v_mfma_f32_32x32x16_bf16 v[0:15], v[100:103], v[108:111], v[0:15]
	ds_read_b128 v[100:103], v84 offset:32768
	ds_read_b128 v[104:107], v85 offset:49152
	ds_read_b128 v[108:111], v85 offset:53248
	s_waitcnt lgkmcnt(0)
	v_mfma_f32_32x32x16_bf16 v[48:63], v[100:103], v[104:107], v[48:63]
	v_mfma_f32_32x32x16_bf16 v[32:47], v[100:103], v[108:111], v[32:47]
	ds_read_b128 v[100:103], v84 offset:36864
	s_waitcnt lgkmcnt(0)
	v_mfma_f32_32x32x16_bf16 v[16:31], v[100:103], v[104:107], v[16:31]
	v_mfma_f32_32x32x16_bf16 v[0:15], v[100:103], v[108:111], v[0:15]
	ds_read_b128 v[100:103], v86 offset:32768
	ds_read_b128 v[104:107], v87 offset:49152
	ds_read_b128 v[108:111], v87 offset:53248
	ds_read_b128 v[120:123], v86 offset:36864
	s_waitcnt vmcnt(0)
	s_waitcnt vmcnt(0) lgkmcnt(0)
	s_barrier
; #define WAIT_V0() asm volatile("s_waitcnt vmcnt(0)" ::: "memory")
; DI void gemm_core(char* smem, int nk, const char* Ab, const char* Bb, const unsigned (&aoff)[4], const unsigned (&boff)[4],
;                   f32x16 (&acc)[2][2]) {
;     ...
;   for (int kt = 0; kt < nk; ++kt) {
;     const int cur = kt & 1;
;     if (kt + 1 < nk) stage(cur ^ 1, kt + 1);
;     const char* sb = smem + cur * STAGE_B;
; #pragma unroll
;     for (int ks = 0; ks < 4; ++ks) {
;       bf16x8 af[2], bfr[2];
; #pragma unroll
;       for (int mb = 0; mb < 2; ++mb) af[mb] = *(const bf16x8*)(sb + a_base + mb * 4096 + xo[ks]);
; #pragma unroll
;       for (int nb = 0; nb < 2; ++nb) bfr[nb] = *(const bf16x8*)(sb + b_base + nb * 4096 + xo[ks]);
; #pragma unroll
;       for (int mb = 0; mb < 2; ++mb)
; #pragma unroll
;         for (int nb = 0; nb < 2; ++nb)
;           acc[mb][nb] = __builtin_amdgcn_mfma_f32_32x32x16_bf16(af[mb], bfr[nb], acc[mb][nb], 0, 0, 0);
;     }
;     WAIT_V0();
;     __syncthreads();
;   }
	v_mfma_f32_32x32x16_bf16 v[48:63], v[100:103], v[104:107], v[48:63]
	v_mfma_f32_32x32x16_bf16 v[32:47], v[100:103], v[108:111], v[32:47]
	v_mfma_f32_32x32x16_bf16 v[16:31], v[120:123], v[104:107], v[16:31]
	v_mfma_f32_32x32x16_bf16 v[0:15], v[120:123], v[108:111], v[0:15]
	ds_read_b128 v[100:103], v80
	ds_read_b128 v[104:107], v82 offset:16384
	ds_read_b128 v[108:111], v82 offset:20480
	v_lshl_add_u64 v[116:117], v[64:65], 0, s[46:47]
	global_load_lds_dwordx4 v[116:117], off
	v_lshl_add_u64 v[118:119], v[66:67], 0, s[46:47]
	s_mov_b32 m0, s43
	s_nop 0
	global_load_lds_dwordx4 v[118:119], off
	v_lshl_add_u64 v[116:117], v[68:69], 0, s[46:47]
	s_mov_b32 m0, s44
	s_nop 0
	global_load_lds_dwordx4 v[116:117], off
	v_lshl_add_u64 v[118:119], v[70:71], 0, s[46:47]
	s_mov_b32 m0, s1
	s_nop 0
	global_load_lds_dwordx4 v[118:119], off
	v_lshl_add_u64 v[116:117], v[72:73], 0, s[46:47]
	s_mov_b32 m0, s16
	s_nop 0
	global_load_lds_dwordx4 v[116:117], off
	v_lshl_add_u64 v[118:119], v[74:75], 0, s[46:47]
	s_mov_b32 m0, s17
	s_nop 0
	global_load_lds_dwordx4 v[118:119], off
	v_lshl_add_u64 v[116:117], v[76:77], 0, s[46:47]
	s_mov_b32 m0, s18
	s_nop 0
	global_load_lds_dwordx4 v[116:117], off
	v_lshl_add_u64 v[118:119], v[78:79], 0, s[46:47]
	s_mov_b32 m0, s19
	s_nop 0
	global_load_lds_dwordx4 v[118:119], off
	s_waitcnt lgkmcnt(0)
	v_mfma_f32_32x32x16_bf16 v[48:63], v[100:103], v[104:107], v[48:63]
	s_mov_b32 m0, s20
	v_mfma_f32_32x32x16_bf16 v[32:47], v[100:103], v[108:111], v[32:47]
	ds_read_b128 v[100:103], v80 offset:4096
	s_waitcnt lgkmcnt(0)
	v_mfma_f32_32x32x16_bf16 v[16:31], v[100:103], v[104:107], v[16:31]
	v_mfma_f32_32x32x16_bf16 v[0:15], v[100:103], v[108:111], v[0:15]
	ds_read_b128 v[100:103], v81
	ds_read_b128 v[104:107], v83 offset:16384
	ds_read_b128 v[108:111], v83 offset:20480
	s_waitcnt lgkmcnt(0)
	v_mfma_f32_32x32x16_bf16 v[48:63], v[100:103], v[104:107], v[48:63]
	v_mfma_f32_32x32x16_bf16 v[32:47], v[100:103], v[108:111], v[32:47]
	ds_read_b128 v[100:103], v81 offset:4096
	s_waitcnt lgkmcnt(0)
	v_mfma_f32_32x32x16_bf16 v[16:31], v[100:103], v[104:107], v[16:31]
	v_mfma_f32_32x32x16_bf16 v[0:15], v[100:103], v[108:111], v[0:15]
	ds_read_b128 v[100:103], v84
	ds_read_b128 v[104:107], v85 offset:16384
	ds_read_b128 v[108:111], v85 offset:20480
	s_waitcnt lgkmcnt(0)
	v_mfma_f32_32x32x16_bf16 v[48:63], v[100:103], v[104:107], v[48:63]
	v_mfma_f32_32x32x16_bf16 v[32:47], v[100:103], v[108:111], v[32:47]
	ds_read_b128 v[100:103], v84 offset:4096
	s_waitcnt lgkmcnt(0)
	v_mfma_f32_32x32x16_bf16 v[16:31], v[100:103], v[104:107], v[16:31]
	v_mfma_f32_32x32x16_bf16 v[0:15], v[100:103], v[108:111], v[0:15]
	ds_read_b128 v[100:103], v86
	ds_read_b128 v[104:107], v87 offset:16384
	ds_read_b128 v[108:111], v87 offset:20480
	ds_read_b128 v[120:123], v86 offset:4096
	s_waitcnt vmcnt(0)
	s_waitcnt vmcnt(0) lgkmcnt(0)
	s_barrier
	v_mfma_f32_32x32x16_bf16 v[48:63], v[100:103], v[104:107], v[48:63]
	v_mfma_f32_32x32x16_bf16 v[32:47], v[100:103], v[108:111], v[32:47]
	v_mfma_f32_32x32x16_bf16 v[16:31], v[120:123], v[104:107], v[16:31]
	v_mfma_f32_32x32x16_bf16 v[0:15], v[120:123], v[108:111], v[0:15]
	ds_read_b128 v[100:103], v80 offset:32768
	ds_read_b128 v[104:107], v82 offset:49152
	ds_read_b128 v[108:111], v82 offset:53248
	v_lshl_add_u64 v[116:117], v[64:65], 0, s[48:49]
	global_load_lds_dwordx4 v[116:117], off
	v_lshl_add_u64 v[118:119], v[66:67], 0, s[48:49]
	s_mov_b32 m0, s21
	s_nop 0
	global_load_lds_dwordx4 v[118:119], off
	v_lshl_add_u64 v[116:117], v[68:69], 0, s[48:49]
	s_mov_b32 m0, s22
	s_nop 0
	global_load_lds_dwordx4 v[116:117], off
	v_lshl_add_u64 v[118:119], v[70:71], 0, s[48:49]
	s_mov_b32 m0, s23
	s_nop 0
	global_load_lds_dwordx4 v[118:119], off
	v_lshl_add_u64 v[116:117], v[72:73], 0, s[48:49]
	s_mov_b32 m0, s28
	s_nop 0
	global_load_lds_dwordx4 v[116:117], off
	v_lshl_add_u64 v[118:119], v[74:75], 0, s[48:49]
	s_mov_b32 m0, s29
	s_nop 0
	global_load_lds_dwordx4 v[118:119], off
	v_lshl_add_u64 v[116:117], v[76:77], 0, s[48:49]
	s_mov_b32 m0, s40
	s_nop 0
	global_load_lds_dwordx4 v[116:117], off
	v_lshl_add_u64 v[118:119], v[78:79], 0, s[48:49]
	s_mov_b32 m0, s41
	s_nop 0
	global_load_lds_dwordx4 v[118:119], off
	s_waitcnt lgkmcnt(0)
	v_mfma_f32_32x32x16_bf16 v[48:63], v[100:103], v[104:107], v[48:63]
	s_mov_b32 m0, s42
	v_readfirstlane_b32 s42, v93
	v_mfma_f32_32x32x16_bf16 v[32:47], v[100:103], v[108:111], v[32:47]
	ds_read_b128 v[100:103], v80 offset:36864
	s_waitcnt lgkmcnt(0)
	v_mfma_f32_32x32x16_bf16 v[16:31], v[100:103], v[104:107], v[16:31]
	v_mfma_f32_32x32x16_bf16 v[0:15], v[100:103], v[108:111], v[0:15]
	ds_read_b128 v[100:103], v81 offset:32768
	ds_read_b128 v[104:107], v83 offset:49152
	ds_read_b128 v[108:111], v83 offset:53248
	s_waitcnt lgkmcnt(0)
	v_mfma_f32_32x32x16_bf16 v[48:63], v[100:103], v[104:107], v[48:63]
	v_mfma_f32_32x32x16_bf16 v[32:47], v[100:103], v[108:111], v[32:47]
	ds_read_b128 v[100:103], v81 offset:36864
	s_waitcnt lgkmcnt(0)
	v_mfma_f32_32x32x16_bf16 v[16:31], v[100:103], v[104:107], v[16:31]
	v_mfma_f32_32x32x16_bf16 v[0:15], v[100:103], v[108:111], v[0:15]
	ds_read_b128 v[100:103], v84 offset:32768
	ds_read_b128 v[104:107], v85 offset:49152
	ds_read_b128 v[108:111], v85 offset:53248
	s_waitcnt lgkmcnt(0)
	v_mfma_f32_32x32x16_bf16 v[48:63], v[100:103], v[104:107], v[48:63]
	v_mfma_f32_32x32x16_bf16 v[32:47], v[100:103], v[108:111], v[32:47]
	ds_read_b128 v[100:103], v84 offset:36864
	s_waitcnt lgkmcnt(0)
	v_mfma_f32_32x32x16_bf16 v[16:31], v[100:103], v[104:107], v[16:31]
	v_mfma_f32_32x32x16_bf16 v[0:15], v[100:103], v[108:111], v[0:15]
	ds_read_b128 v[100:103], v86 offset:32768
	ds_read_b128 v[104:107], v87 offset:49152
	ds_read_b128 v[108:111], v87 offset:53248
	ds_read_b128 v[120:123], v86 offset:36864
	s_waitcnt vmcnt(0)
	s_waitcnt vmcnt(0) lgkmcnt(0)
	s_barrier
; #define WAIT_V0() asm volatile("s_waitcnt vmcnt(0)" ::: "memory")
; DI void gemm_core(char* smem, int nk, const char* Ab, const char* Bb, const unsigned (&aoff)[4], const unsigned (&boff)[4],
;                   f32x16 (&acc)[2][2]) {
;     ...
;   for (int kt = 0; kt < nk; ++kt) {
;     const int cur = kt & 1;
;     if (kt + 1 < nk) stage(cur ^ 1, kt + 1);
;     const char* sb = smem + cur * STAGE_B;
; #pragma unroll
;     for (int ks = 0; ks < 4; ++ks) {
;       bf16x8 af[2], bfr[2];
; #pragma unroll
;       for (int mb = 0; mb < 2; ++mb) af[mb] = *(const bf16x8*)(sb + a_base + mb * 4096 + xo[ks]);
; #pragma unroll
;       for (int nb = 0; nb < 2; ++nb) bfr[nb] = *(const bf16x8*)(sb + b_base + nb * 4096 + xo[ks]);
; #pragma unroll
;       for (int mb = 0; mb < 2; ++mb)
; #pragma unroll
;         for (int nb = 0; nb < 2; ++nb)
;           acc[mb][nb] = __builtin_amdgcn_mfma_f32_32x32x16_bf16(af[mb], bfr[nb], acc[mb][nb], 0, 0, 0);
;     }
;     WAIT_V0();
;     __syncthreads();
;   }
	v_mfma_f32_32x32x16_bf16 v[48:63], v[100:103], v[104:107], v[48:63]
	v_mfma_f32_32x32x16_bf16 v[32:47], v[100:103], v[108:111], v[32:47]
	v_mfma_f32_32x32x16_bf16 v[16:31], v[120:123], v[104:107], v[16:31]
	v_mfma_f32_32x32x16_bf16 v[0:15], v[120:123], v[108:111], v[0:15]
	ds_read_b128 v[100:103], v80
	ds_read_b128 v[104:107], v82 offset:16384
	ds_read_b128 v[108:111], v82 offset:20480
	v_lshl_add_u64 v[116:117], v[64:65], 0, s[50:51]
	global_load_lds_dwordx4 v[116:117], off
	v_lshl_add_u64 v[118:119], v[66:67], 0, s[50:51]
	s_mov_b32 m0, s43
	v_readfirstlane_b32 s43, v94
	global_load_lds_dwordx4 v[118:119], off
	v_lshl_add_u64 v[116:117], v[68:69], 0, s[50:51]
	s_mov_b32 m0, s44
	v_readfirstlane_b32 s44, v95
	global_load_lds_dwordx4 v[116:117], off
	v_lshl_add_u64 v[118:119], v[70:71], 0, s[50:51]
	s_mov_b32 m0, s1
	s_nop 0
	global_load_lds_dwordx4 v[118:119], off
	v_lshl_add_u64 v[116:117], v[72:73], 0, s[50:51]
	s_mov_b32 m0, s16
	s_nop 0
	global_load_lds_dwordx4 v[116:117], off
	v_lshl_add_u64 v[118:119], v[74:75], 0, s[50:51]
	s_mov_b32 m0, s17
	s_nop 0
	global_load_lds_dwordx4 v[118:119], off
	v_lshl_add_u64 v[116:117], v[76:77], 0, s[50:51]
	s_mov_b32 m0, s18
	s_nop 0
	global_load_lds_dwordx4 v[116:117], off
	v_lshl_add_u64 v[118:119], v[78:79], 0, s[50:51]
	s_mov_b32 m0, s19
	s_nop 0
	global_load_lds_dwordx4 v[118:119], off
	s_waitcnt lgkmcnt(0)
	v_mfma_f32_32x32x16_bf16 v[48:63], v[100:103], v[104:107], v[48:63]
	s_mov_b32 m0, s20
	v_readfirstlane_b32 s20, v97
	v_mfma_f32_32x32x16_bf16 v[32:47], v[100:103], v[108:111], v[32:47]
	ds_read_b128 v[100:103], v80 offset:4096
	s_waitcnt lgkmcnt(0)
	v_mfma_f32_32x32x16_bf16 v[16:31], v[100:103], v[104:107], v[16:31]
	v_mfma_f32_32x32x16_bf16 v[0:15], v[100:103], v[108:111], v[0:15]
	ds_read_b128 v[100:103], v81
	ds_read_b128 v[104:107], v83 offset:16384
	ds_read_b128 v[108:111], v83 offset:20480
	s_waitcnt lgkmcnt(0)
	v_mfma_f32_32x32x16_bf16 v[48:63], v[100:103], v[104:107], v[48:63]
	v_mfma_f32_32x32x16_bf16 v[32:47], v[100:103], v[108:111], v[32:47]
	ds_read_b128 v[100:103], v81 offset:4096
	s_waitcnt lgkmcnt(0)
	v_mfma_f32_32x32x16_bf16 v[16:31], v[100:103], v[104:107], v[16:31]
	v_mfma_f32_32x32x16_bf16 v[0:15], v[100:103], v[108:111], v[0:15]
	ds_read_b128 v[100:103], v84
	ds_read_b128 v[104:107], v85 offset:16384
	ds_read_b128 v[108:111], v85 offset:20480
	s_waitcnt lgkmcnt(0)
	v_mfma_f32_32x32x16_bf16 v[48:63], v[100:103], v[104:107], v[48:63]
	v_mfma_f32_32x32x16_bf16 v[32:47], v[100:103], v[108:111], v[32:47]
	ds_read_b128 v[100:103], v84 offset:4096
	s_waitcnt lgkmcnt(0)
	v_mfma_f32_32x32x16_bf16 v[16:31], v[100:103], v[104:107], v[16:31]
	v_mfma_f32_32x32x16_bf16 v[0:15], v[100:103], v[108:111], v[0:15]
	ds_read_b128 v[100:103], v86
	ds_read_b128 v[104:107], v87 offset:16384
	ds_read_b128 v[108:111], v87 offset:20480
	ds_read_b128 v[120:123], v86 offset:4096
	s_waitcnt vmcnt(0)
	s_waitcnt vmcnt(0) lgkmcnt(0)
	s_barrier
	v_mfma_f32_32x32x16_bf16 v[48:63], v[100:103], v[104:107], v[48:63]
	v_mfma_f32_32x32x16_bf16 v[32:47], v[100:103], v[108:111], v[32:47]
	v_mfma_f32_32x32x16_bf16 v[16:31], v[120:123], v[104:107], v[16:31]
	v_mfma_f32_32x32x16_bf16 v[0:15], v[120:123], v[108:111], v[0:15]
	v_lshl_add_u64 v[100:101], v[64:65], 0, s[52:53]
	global_load_lds_dwordx4 v[100:101], off
	v_lshl_add_u64 v[100:101], v[66:67], 0, s[52:53]
	s_mov_b32 m0, s21
	v_readfirstlane_b32 s21, v96
	global_load_lds_dwordx4 v[100:101], off
	v_lshl_add_u64 v[100:101], v[68:69], 0, s[52:53]
	s_mov_b32 m0, s22
	v_readfirstlane_b32 s22, v98
	global_load_lds_dwordx4 v[100:101], off
	v_lshl_add_u64 v[100:101], v[70:71], 0, s[52:53]
	s_mov_b32 m0, s23
	v_lshl_add_u64 v[96:97], v[68:69], 0, s[54:55]
	global_load_lds_dwordx4 v[100:101], off
	v_lshl_add_u64 v[100:101], v[72:73], 0, s[52:53]
	s_mov_b32 m0, s28
	v_readfirstlane_b32 s23, v89
	global_load_lds_dwordx4 v[100:101], off
	v_lshl_add_u64 v[100:101], v[74:75], 0, s[52:53]
	s_mov_b32 m0, s29
	v_readfirstlane_b32 s28, v88
	global_load_lds_dwordx4 v[100:101], off
	v_lshl_add_u64 v[100:101], v[76:77], 0, s[52:53]
	s_mov_b32 m0, s40
	v_readfirstlane_b32 s29, v90
	global_load_lds_dwordx4 v[100:101], off
	v_lshl_add_u64 v[100:101], v[78:79], 0, s[52:53]
	s_mov_b32 m0, s41
	v_lshl_add_u64 v[88:89], v[68:69], 0, s[56:57]
	global_load_lds_dwordx4 v[100:101], off
	ds_read_b128 v[100:103], v80 offset:32768
	ds_read_b128 v[104:107], v82 offset:49152
	ds_read_b128 v[108:111], v82 offset:53248
	s_waitcnt lgkmcnt(0)
	v_mfma_f32_32x32x16_bf16 v[48:63], v[100:103], v[104:107], v[48:63]
	s_mov_b32 m0, s20
	v_readfirstlane_b32 s40, v91
	v_readfirstlane_b32 s41, v92
	v_mfma_f32_32x32x16_bf16 v[32:47], v[100:103], v[108:111], v[32:47]
	ds_read_b128 v[100:103], v80 offset:36864
	s_waitcnt lgkmcnt(0)
	v_mfma_f32_32x32x16_bf16 v[16:31], v[100:103], v[104:107], v[16:31]
	v_mfma_f32_32x32x16_bf16 v[0:15], v[100:103], v[108:111], v[0:15]
	ds_read_b128 v[100:103], v81 offset:32768
	ds_read_b128 v[104:107], v83 offset:49152
	ds_read_b128 v[108:111], v83 offset:53248
	s_waitcnt lgkmcnt(0)
	v_mfma_f32_32x32x16_bf16 v[48:63], v[100:103], v[104:107], v[48:63]
	v_mfma_f32_32x32x16_bf16 v[32:47], v[100:103], v[108:111], v[32:47]
	ds_read_b128 v[100:103], v81 offset:36864
	s_waitcnt lgkmcnt(0)
	v_mfma_f32_32x32x16_bf16 v[16:31], v[100:103], v[104:107], v[16:31]
	v_mfma_f32_32x32x16_bf16 v[0:15], v[100:103], v[108:111], v[0:15]
	ds_read_b128 v[100:103], v84 offset:32768
	ds_read_b128 v[104:107], v85 offset:49152
	ds_read_b128 v[108:111], v85 offset:53248
	s_waitcnt lgkmcnt(0)
	v_mfma_f32_32x32x16_bf16 v[48:63], v[100:103], v[104:107], v[48:63]
	v_mfma_f32_32x32x16_bf16 v[32:47], v[100:103], v[108:111], v[32:47]
	ds_read_b128 v[100:103], v84 offset:36864
	s_waitcnt lgkmcnt(0)
	v_mfma_f32_32x32x16_bf16 v[16:31], v[100:103], v[104:107], v[16:31]
	v_mfma_f32_32x32x16_bf16 v[0:15], v[100:103], v[108:111], v[0:15]
	ds_read_b128 v[100:103], v86 offset:32768
	ds_read_b128 v[104:107], v87 offset:49152
	ds_read_b128 v[108:111], v87 offset:53248
	ds_read_b128 v[120:123], v86 offset:36864
	s_waitcnt vmcnt(0)
	s_waitcnt vmcnt(0) lgkmcnt(0)
	s_barrier
; #define WAIT_V0() asm volatile("s_waitcnt vmcnt(0)" ::: "memory")
; DI void gemm_core(char* smem, int nk, const char* Ab, const char* Bb, const unsigned (&aoff)[4], const unsigned (&boff)[4],
;                   f32x16 (&acc)[2][2]) {
;     ...
;   for (int kt = 0; kt < nk; ++kt) {
;     const int cur = kt & 1;
;     if (kt + 1 < nk) stage(cur ^ 1, kt + 1);
;     const char* sb = smem + cur * STAGE_B;
; #pragma unroll
;     for (int ks = 0; ks < 4; ++ks) {
;       bf16x8 af[2], bfr[2];
; #pragma unroll
;       for (int mb = 0; mb < 2; ++mb) af[mb] = *(const bf16x8*)(sb + a_base + mb * 4096 + xo[ks]);
; #pragma unroll
;       for (int nb = 0; nb < 2; ++nb) bfr[nb] = *(const bf16x8*)(sb + b_base + nb * 4096 + xo[ks]);
; #pragma unroll
;       for (int mb = 0; mb < 2; ++mb)
; #pragma unroll
;         for (int nb = 0; nb < 2; ++nb)
;           acc[mb][nb] = __builtin_amdgcn_mfma_f32_32x32x16_bf16(af[mb], bfr[nb], acc[mb][nb], 0, 0, 0);
;     }
;     WAIT_V0();
;     __syncthreads();
;   }
	v_mfma_f32_32x32x16_bf16 v[48:63], v[100:103], v[104:107], v[48:63]
	v_mfma_f32_32x32x16_bf16 v[32:47], v[100:103], v[108:111], v[32:47]
	v_mfma_f32_32x32x16_bf16 v[16:31], v[120:123], v[104:107], v[16:31]
	v_mfma_f32_32x32x16_bf16 v[0:15], v[120:123], v[108:111], v[0:15]
	v_lshl_add_u64 v[100:101], v[64:65], 0, s[54:55]
	global_load_lds_dwordx4 v[100:101], off
	v_lshl_add_u64 v[100:101], v[66:67], 0, s[54:55]
	s_mov_b32 m0, s21
	s_nop 0
	global_load_lds_dwordx4 v[100:101], off
	s_mov_b32 m0, s22
	s_nop 0
	global_load_lds_dwordx4 v[96:97], off
	v_lshl_add_u64 v[96:97], v[70:71], 0, s[54:55]
	s_mov_b32 m0, s1
	s_nop 0
	global_load_lds_dwordx4 v[96:97], off
	v_lshl_add_u64 v[96:97], v[72:73], 0, s[54:55]
	s_mov_b32 m0, s16
	s_nop 0
	global_load_lds_dwordx4 v[96:97], off
	v_lshl_add_u64 v[96:97], v[74:75], 0, s[54:55]
	s_mov_b32 m0, s17
	s_nop 0
	global_load_lds_dwordx4 v[96:97], off
	v_lshl_add_u64 v[96:97], v[76:77], 0, s[54:55]
	s_mov_b32 m0, s18
	s_nop 0
	global_load_lds_dwordx4 v[96:97], off
	v_lshl_add_u64 v[96:97], v[78:79], 0, s[54:55]
	s_mov_b32 m0, s19
	s_nop 0
	global_load_lds_dwordx4 v[96:97], off
	ds_read_b128 v[96:99], v80
	ds_read_b128 v[100:103], v82 offset:16384
	ds_read_b128 v[104:107], v82 offset:20480
	s_waitcnt lgkmcnt(0)
	v_mfma_f32_32x32x16_bf16 v[48:63], v[96:99], v[100:103], v[48:63]
	s_mov_b32 m0, s23
	v_mfma_f32_32x32x16_bf16 v[32:47], v[96:99], v[104:107], v[32:47]
	ds_read_b128 v[96:99], v80 offset:4096
	s_waitcnt lgkmcnt(0)
	v_mfma_f32_32x32x16_bf16 v[16:31], v[96:99], v[100:103], v[16:31]
	v_mfma_f32_32x32x16_bf16 v[0:15], v[96:99], v[104:107], v[0:15]
	ds_read_b128 v[96:99], v81
	ds_read_b128 v[100:103], v83 offset:16384
	ds_read_b128 v[104:107], v83 offset:20480
	s_waitcnt lgkmcnt(0)
	v_mfma_f32_32x32x16_bf16 v[48:63], v[96:99], v[100:103], v[48:63]
	v_mfma_f32_32x32x16_bf16 v[32:47], v[96:99], v[104:107], v[32:47]
	ds_read_b128 v[96:99], v81 offset:4096
	s_waitcnt lgkmcnt(0)
	v_mfma_f32_32x32x16_bf16 v[16:31], v[96:99], v[100:103], v[16:31]
	v_mfma_f32_32x32x16_bf16 v[0:15], v[96:99], v[104:107], v[0:15]
	ds_read_b128 v[96:99], v84
	ds_read_b128 v[100:103], v85 offset:16384
	ds_read_b128 v[104:107], v85 offset:20480
	s_waitcnt lgkmcnt(0)
	v_mfma_f32_32x32x16_bf16 v[48:63], v[96:99], v[100:103], v[48:63]
	v_mfma_f32_32x32x16_bf16 v[32:47], v[96:99], v[104:107], v[32:47]
	ds_read_b128 v[96:99], v84 offset:4096
	s_waitcnt lgkmcnt(0)
	v_mfma_f32_32x32x16_bf16 v[16:31], v[96:99], v[100:103], v[16:31]
	v_mfma_f32_32x32x16_bf16 v[0:15], v[96:99], v[104:107], v[0:15]
	ds_read_b128 v[96:99], v86
	ds_read_b128 v[100:103], v87 offset:16384
	ds_read_b128 v[104:107], v87 offset:20480
	ds_read_b128 v[120:123], v86 offset:4096
	s_waitcnt vmcnt(0)
	s_waitcnt vmcnt(0) lgkmcnt(0)
	s_barrier
	v_mfma_f32_32x32x16_bf16 v[48:63], v[96:99], v[100:103], v[48:63]
	v_mfma_f32_32x32x16_bf16 v[32:47], v[96:99], v[104:107], v[32:47]
	v_mfma_f32_32x32x16_bf16 v[16:31], v[120:123], v[100:103], v[16:31]
	v_mfma_f32_32x32x16_bf16 v[0:15], v[120:123], v[104:107], v[0:15]
	v_lshl_add_u64 v[96:97], v[64:65], 0, s[56:57]
	global_load_lds_dwordx4 v[96:97], off
	v_lshl_add_u64 v[96:97], v[66:67], 0, s[56:57]
	s_mov_b32 m0, s28
	s_nop 0
	global_load_lds_dwordx4 v[96:97], off
	s_mov_b32 m0, s29
	s_nop 0
	global_load_lds_dwordx4 v[88:89], off
	v_lshl_add_u64 v[88:89], v[70:71], 0, s[56:57]
	s_mov_b32 m0, s40
	s_nop 0
	global_load_lds_dwordx4 v[88:89], off
	v_lshl_add_u64 v[88:89], v[72:73], 0, s[56:57]
	s_mov_b32 m0, s41
	s_nop 0
	global_load_lds_dwordx4 v[88:89], off
	v_lshl_add_u64 v[88:89], v[74:75], 0, s[56:57]
	s_mov_b32 m0, s42
	s_nop 0
	global_load_lds_dwordx4 v[88:89], off
	v_lshl_add_u64 v[88:89], v[76:77], 0, s[56:57]
	s_mov_b32 m0, s43
	s_nop 0
	global_load_lds_dwordx4 v[88:89], off
	v_lshl_add_u64 v[88:89], v[78:79], 0, s[56:57]
	s_mov_b32 m0, s44
	s_nop 0
	global_load_lds_dwordx4 v[88:89], off
	ds_read_b128 v[88:91], v80 offset:32768
	ds_read_b128 v[92:95], v82 offset:49152
	ds_read_b128 v[96:99], v82 offset:53248
	s_waitcnt lgkmcnt(0)
	v_mfma_f32_32x32x16_bf16 v[48:63], v[88:91], v[92:95], v[48:63]
	s_mov_b32 m0, s20
	v_mfma_f32_32x32x16_bf16 v[32:47], v[88:91], v[96:99], v[32:47]
	ds_read_b128 v[88:91], v80 offset:36864
	s_waitcnt lgkmcnt(0)
	v_mfma_f32_32x32x16_bf16 v[16:31], v[88:91], v[92:95], v[16:31]
	v_mfma_f32_32x32x16_bf16 v[0:15], v[88:91], v[96:99], v[0:15]
	ds_read_b128 v[88:91], v81 offset:32768
	ds_read_b128 v[92:95], v83 offset:49152
	ds_read_b128 v[96:99], v83 offset:53248
	s_waitcnt lgkmcnt(0)
	v_mfma_f32_32x32x16_bf16 v[48:63], v[88:91], v[92:95], v[48:63]
	v_mfma_f32_32x32x16_bf16 v[32:47], v[88:91], v[96:99], v[32:47]
	ds_read_b128 v[88:91], v81 offset:36864
	s_waitcnt lgkmcnt(0)
	v_mfma_f32_32x32x16_bf16 v[16:31], v[88:91], v[92:95], v[16:31]
	v_mfma_f32_32x32x16_bf16 v[0:15], v[88:91], v[96:99], v[0:15]
	ds_read_b128 v[88:91], v84 offset:32768
	ds_read_b128 v[92:95], v85 offset:49152
	ds_read_b128 v[96:99], v85 offset:53248
	s_waitcnt lgkmcnt(0)
	v_mfma_f32_32x32x16_bf16 v[48:63], v[88:91], v[92:95], v[48:63]
	v_mfma_f32_32x32x16_bf16 v[32:47], v[88:91], v[96:99], v[32:47]
	ds_read_b128 v[88:91], v84 offset:36864
	s_waitcnt lgkmcnt(0)
	v_mfma_f32_32x32x16_bf16 v[16:31], v[88:91], v[92:95], v[16:31]
	v_mfma_f32_32x32x16_bf16 v[0:15], v[88:91], v[96:99], v[0:15]
	ds_read_b128 v[88:91], v86 offset:32768
	ds_read_b128 v[92:95], v87 offset:49152
	ds_read_b128 v[96:99], v87 offset:53248
	ds_read_b128 v[120:123], v86 offset:36864
	s_waitcnt vmcnt(0)
	s_waitcnt vmcnt(0) lgkmcnt(0)
	s_barrier
; #define WAIT_V0() asm volatile("s_waitcnt vmcnt(0)" ::: "memory")
; DI void gemm_core(char* smem, int nk, const char* Ab, const char* Bb, const unsigned (&aoff)[4], const unsigned (&boff)[4],
;                   f32x16 (&acc)[2][2]) {
;     ...
;   for (int kt = 0; kt < nk; ++kt) {
;     const int cur = kt & 1;
;     if (kt + 1 < nk) stage(cur ^ 1, kt + 1);
;     const char* sb = smem + cur * STAGE_B;
; #pragma unroll
;     for (int ks = 0; ks < 4; ++ks) {
;       bf16x8 af[2], bfr[2];
; #pragma unroll
;       for (int mb = 0; mb < 2; ++mb) af[mb] = *(const bf16x8*)(sb + a_base + mb * 4096 + xo[ks]);
; #pragma unroll
;       for (int nb = 0; nb < 2; ++nb) bfr[nb] = *(const bf16x8*)(sb + b_base + nb * 4096 + xo[ks]);
; #pragma unroll
;       for (int mb = 0; mb < 2; ++mb)
; #pragma unroll
;         for (int nb = 0; nb < 2; ++nb)
;           acc[mb][nb] = __builtin_amdgcn_mfma_f32_32x32x16_bf16(af[mb], bfr[nb], acc[mb][nb], 0, 0, 0);
;     }
;     WAIT_V0();
;     __syncthreads();
;   }
	v_mfma_f32_32x32x16_bf16 v[48:63], v[88:91], v[92:95], v[48:63]
	v_mfma_f32_32x32x16_bf16 v[32:47], v[88:91], v[96:99], v[32:47]
	v_mfma_f32_32x32x16_bf16 v[16:31], v[120:123], v[92:95], v[16:31]
	v_mfma_f32_32x32x16_bf16 v[0:15], v[120:123], v[96:99], v[0:15]
	ds_read_b128 v[88:91], v80
	ds_read_b128 v[92:95], v82 offset:16384
	ds_read_b128 v[96:99], v82 offset:20480
	v_lshl_add_u64 v[116:117], v[64:65], 0, s[58:59]
	global_load_lds_dwordx4 v[116:117], off
	v_lshl_add_u64 v[118:119], v[66:67], 0, s[58:59]
	s_mov_b32 m0, s21
	s_nop 0
	global_load_lds_dwordx4 v[118:119], off
	v_lshl_add_u64 v[116:117], v[68:69], 0, s[58:59]
	s_mov_b32 m0, s22
	s_nop 0
	global_load_lds_dwordx4 v[116:117], off
	v_lshl_add_u64 v[118:119], v[70:71], 0, s[58:59]
	s_mov_b32 m0, s1
	s_nop 0
	global_load_lds_dwordx4 v[118:119], off
	v_lshl_add_u64 v[116:117], v[72:73], 0, s[58:59]
	s_mov_b32 m0, s16
	s_nop 0
	global_load_lds_dwordx4 v[116:117], off
	v_lshl_add_u64 v[118:119], v[74:75], 0, s[58:59]
	s_mov_b32 m0, s17
	s_nop 0
	global_load_lds_dwordx4 v[118:119], off
	v_lshl_add_u64 v[116:117], v[76:77], 0, s[58:59]
	s_mov_b32 m0, s18
	s_nop 0
	global_load_lds_dwordx4 v[116:117], off
	v_lshl_add_u64 v[118:119], v[78:79], 0, s[58:59]
	s_mov_b32 m0, s19
	s_nop 0
	global_load_lds_dwordx4 v[118:119], off
	s_waitcnt lgkmcnt(0)
	v_mfma_f32_32x32x16_bf16 v[48:63], v[88:91], v[92:95], v[48:63]
	s_mov_b32 m0, s23
	v_mfma_f32_32x32x16_bf16 v[32:47], v[88:91], v[96:99], v[32:47]
	ds_read_b128 v[88:91], v80 offset:4096
	s_waitcnt lgkmcnt(0)
	v_mfma_f32_32x32x16_bf16 v[16:31], v[88:91], v[92:95], v[16:31]
	v_mfma_f32_32x32x16_bf16 v[0:15], v[88:91], v[96:99], v[0:15]
	ds_read_b128 v[88:91], v81
	ds_read_b128 v[92:95], v83 offset:16384
	ds_read_b128 v[96:99], v83 offset:20480
	s_waitcnt lgkmcnt(0)
	v_mfma_f32_32x32x16_bf16 v[48:63], v[88:91], v[92:95], v[48:63]
	v_mfma_f32_32x32x16_bf16 v[32:47], v[88:91], v[96:99], v[32:47]
	ds_read_b128 v[88:91], v81 offset:4096
	s_waitcnt lgkmcnt(0)
	v_mfma_f32_32x32x16_bf16 v[16:31], v[88:91], v[92:95], v[16:31]
	v_mfma_f32_32x32x16_bf16 v[0:15], v[88:91], v[96:99], v[0:15]
	ds_read_b128 v[88:91], v84
	ds_read_b128 v[92:95], v85 offset:16384
	ds_read_b128 v[96:99], v85 offset:20480
	s_waitcnt lgkmcnt(0)
	v_mfma_f32_32x32x16_bf16 v[48:63], v[88:91], v[92:95], v[48:63]
	v_mfma_f32_32x32x16_bf16 v[32:47], v[88:91], v[96:99], v[32:47]
	ds_read_b128 v[88:91], v84 offset:4096
	s_waitcnt lgkmcnt(0)
	v_mfma_f32_32x32x16_bf16 v[16:31], v[88:91], v[92:95], v[16:31]
	v_mfma_f32_32x32x16_bf16 v[0:15], v[88:91], v[96:99], v[0:15]
	ds_read_b128 v[88:91], v86
	ds_read_b128 v[92:95], v87 offset:16384
	ds_read_b128 v[96:99], v87 offset:20480
	ds_read_b128 v[120:123], v86 offset:4096
	s_waitcnt vmcnt(0)
	s_waitcnt vmcnt(0) lgkmcnt(0)
	s_barrier
	v_mfma_f32_32x32x16_bf16 v[48:63], v[88:91], v[92:95], v[48:63]
	v_mfma_f32_32x32x16_bf16 v[32:47], v[88:91], v[96:99], v[32:47]
	v_mfma_f32_32x32x16_bf16 v[16:31], v[120:123], v[92:95], v[16:31]
	v_mfma_f32_32x32x16_bf16 v[0:15], v[120:123], v[96:99], v[0:15]
	ds_read_b128 v[88:91], v80 offset:32768
	ds_read_b128 v[92:95], v82 offset:49152
	ds_read_b128 v[96:99], v82 offset:53248
	v_lshl_add_u64 v[116:117], v[64:65], 0, s[60:61]
	global_load_lds_dwordx4 v[116:117], off
	v_lshl_add_u64 v[118:119], v[66:67], 0, s[60:61]
	s_mov_b32 m0, s28
	s_nop 0
	global_load_lds_dwordx4 v[118:119], off
	v_lshl_add_u64 v[116:117], v[68:69], 0, s[60:61]
	s_mov_b32 m0, s29
	s_nop 0
	global_load_lds_dwordx4 v[116:117], off
	v_lshl_add_u64 v[118:119], v[70:71], 0, s[60:61]
	s_mov_b32 m0, s40
	s_nop 0
	global_load_lds_dwordx4 v[118:119], off
	v_lshl_add_u64 v[116:117], v[72:73], 0, s[60:61]
	s_mov_b32 m0, s41
	s_nop 0
	global_load_lds_dwordx4 v[116:117], off
	v_lshl_add_u64 v[118:119], v[74:75], 0, s[60:61]
	s_mov_b32 m0, s42
	s_nop 0
	global_load_lds_dwordx4 v[118:119], off
	v_lshl_add_u64 v[116:117], v[76:77], 0, s[60:61]
	s_mov_b32 m0, s43
	s_nop 0
	global_load_lds_dwordx4 v[116:117], off
	v_lshl_add_u64 v[118:119], v[78:79], 0, s[60:61]
	s_mov_b32 m0, s44
	s_nop 0
	global_load_lds_dwordx4 v[118:119], off
	s_waitcnt lgkmcnt(0)
	v_mfma_f32_32x32x16_bf16 v[48:63], v[88:91], v[92:95], v[48:63]
	s_mov_b32 m0, s20
	v_mfma_f32_32x32x16_bf16 v[32:47], v[88:91], v[96:99], v[32:47]
	ds_read_b128 v[88:91], v80 offset:36864
	s_waitcnt lgkmcnt(0)
	v_mfma_f32_32x32x16_bf16 v[16:31], v[88:91], v[92:95], v[16:31]
	v_mfma_f32_32x32x16_bf16 v[0:15], v[88:91], v[96:99], v[0:15]
	ds_read_b128 v[88:91], v81 offset:32768
	ds_read_b128 v[92:95], v83 offset:49152
	ds_read_b128 v[96:99], v83 offset:53248
	s_waitcnt lgkmcnt(0)
	v_mfma_f32_32x32x16_bf16 v[48:63], v[88:91], v[92:95], v[48:63]
	v_mfma_f32_32x32x16_bf16 v[32:47], v[88:91], v[96:99], v[32:47]
	ds_read_b128 v[88:91], v81 offset:36864
	s_waitcnt lgkmcnt(0)
	v_mfma_f32_32x32x16_bf16 v[16:31], v[88:91], v[92:95], v[16:31]
	v_mfma_f32_32x32x16_bf16 v[0:15], v[88:91], v[96:99], v[0:15]
	ds_read_b128 v[88:91], v84 offset:32768
	ds_read_b128 v[92:95], v85 offset:49152
	ds_read_b128 v[96:99], v85 offset:53248
	s_waitcnt lgkmcnt(0)
	v_mfma_f32_32x32x16_bf16 v[48:63], v[88:91], v[92:95], v[48:63]
	v_mfma_f32_32x32x16_bf16 v[32:47], v[88:91], v[96:99], v[32:47]
	ds_read_b128 v[88:91], v84 offset:36864
	s_waitcnt lgkmcnt(0)
	v_mfma_f32_32x32x16_bf16 v[16:31], v[88:91], v[92:95], v[16:31]
	v_mfma_f32_32x32x16_bf16 v[0:15], v[88:91], v[96:99], v[0:15]
	ds_read_b128 v[88:91], v86 offset:32768
	ds_read_b128 v[92:95], v87 offset:49152
	ds_read_b128 v[96:99], v87 offset:53248
	ds_read_b128 v[120:123], v86 offset:36864
	s_waitcnt vmcnt(0)
	s_waitcnt vmcnt(0) lgkmcnt(0)
	s_barrier
; #define WAIT_V0() asm volatile("s_waitcnt vmcnt(0)" ::: "memory")
; DI void gemm_core(char* smem, int nk, const char* Ab, const char* Bb, const unsigned (&aoff)[4], const unsigned (&boff)[4],
;                   f32x16 (&acc)[2][2]) {
;     ...
;   for (int kt = 0; kt < nk; ++kt) {
;     const int cur = kt & 1;
;     if (kt + 1 < nk) stage(cur ^ 1, kt + 1);
;     const char* sb = smem + cur * STAGE_B;
; #pragma unroll
;     for (int ks = 0; ks < 4; ++ks) {
;       bf16x8 af[2], bfr[2];
; #pragma unroll
;       for (int mb = 0; mb < 2; ++mb) af[mb] = *(const bf16x8*)(sb + a_base + mb * 4096 + xo[ks]);
; #pragma unroll
;       for (int nb = 0; nb < 2; ++nb) bfr[nb] = *(const bf16x8*)(sb + b_base + nb * 4096 + xo[ks]);
; #pragma unroll
;       for (int mb = 0; mb < 2; ++mb)
; #pragma unroll
;         for (int nb = 0; nb < 2; ++nb)
;           acc[mb][nb] = __builtin_amdgcn_mfma_f32_32x32x16_bf16(af[mb], bfr[nb], acc[mb][nb], 0, 0, 0);
;     }
;     WAIT_V0();
;     __syncthreads();
;   }
	v_mfma_f32_32x32x16_bf16 v[48:63], v[88:91], v[92:95], v[48:63]
	v_mfma_f32_32x32x16_bf16 v[32:47], v[88:91], v[96:99], v[32:47]
	v_mfma_f32_32x32x16_bf16 v[16:31], v[120:123], v[92:95], v[16:31]
	v_mfma_f32_32x32x16_bf16 v[0:15], v[120:123], v[96:99], v[0:15]
	ds_read_b128 v[88:91], v80
	ds_read_b128 v[92:95], v82 offset:16384
	ds_read_b128 v[96:99], v82 offset:20480
	v_lshl_add_u64 v[116:117], v[64:65], 0, s[62:63]
	global_load_lds_dwordx4 v[116:117], off
	v_lshl_add_u64 v[118:119], v[66:67], 0, s[62:63]
	s_mov_b32 m0, s21
	s_nop 0
	global_load_lds_dwordx4 v[118:119], off
	v_lshl_add_u64 v[116:117], v[68:69], 0, s[62:63]
	s_mov_b32 m0, s22
	s_nop 0
	global_load_lds_dwordx4 v[116:117], off
	v_lshl_add_u64 v[118:119], v[70:71], 0, s[62:63]
	s_mov_b32 m0, s1
	s_nop 0
	global_load_lds_dwordx4 v[118:119], off
	v_lshl_add_u64 v[116:117], v[72:73], 0, s[62:63]
	s_mov_b32 m0, s16
	s_nop 0
	global_load_lds_dwordx4 v[116:117], off
	v_lshl_add_u64 v[118:119], v[74:75], 0, s[62:63]
	s_mov_b32 m0, s17
	s_nop 0
	global_load_lds_dwordx4 v[118:119], off
	v_lshl_add_u64 v[116:117], v[76:77], 0, s[62:63]
	s_mov_b32 m0, s18
	s_nop 0
	global_load_lds_dwordx4 v[116:117], off
	v_lshl_add_u64 v[118:119], v[78:79], 0, s[62:63]
	s_mov_b32 m0, s19
	s_nop 0
	global_load_lds_dwordx4 v[118:119], off
	s_waitcnt lgkmcnt(0)
	v_mfma_f32_32x32x16_bf16 v[48:63], v[88:91], v[92:95], v[48:63]
	s_mov_b32 m0, s23
	v_mfma_f32_32x32x16_bf16 v[32:47], v[88:91], v[96:99], v[32:47]
	ds_read_b128 v[88:91], v80 offset:4096
	s_waitcnt lgkmcnt(0)
	v_mfma_f32_32x32x16_bf16 v[16:31], v[88:91], v[92:95], v[16:31]
	v_mfma_f32_32x32x16_bf16 v[0:15], v[88:91], v[96:99], v[0:15]
	ds_read_b128 v[88:91], v81
	ds_read_b128 v[92:95], v83 offset:16384
	ds_read_b128 v[96:99], v83 offset:20480
	s_waitcnt lgkmcnt(0)
	v_mfma_f32_32x32x16_bf16 v[48:63], v[88:91], v[92:95], v[48:63]
	v_mfma_f32_32x32x16_bf16 v[32:47], v[88:91], v[96:99], v[32:47]
	ds_read_b128 v[88:91], v81 offset:4096
	s_waitcnt lgkmcnt(0)
	v_mfma_f32_32x32x16_bf16 v[16:31], v[88:91], v[92:95], v[16:31]
	v_mfma_f32_32x32x16_bf16 v[0:15], v[88:91], v[96:99], v[0:15]
	ds_read_b128 v[88:91], v84
	ds_read_b128 v[92:95], v85 offset:16384
	ds_read_b128 v[96:99], v85 offset:20480
	s_waitcnt lgkmcnt(0)
	v_mfma_f32_32x32x16_bf16 v[48:63], v[88:91], v[92:95], v[48:63]
	v_mfma_f32_32x32x16_bf16 v[32:47], v[88:91], v[96:99], v[32:47]
	ds_read_b128 v[88:91], v84 offset:4096
	s_waitcnt lgkmcnt(0)
	v_mfma_f32_32x32x16_bf16 v[16:31], v[88:91], v[92:95], v[16:31]
	v_mfma_f32_32x32x16_bf16 v[0:15], v[88:91], v[96:99], v[0:15]
	ds_read_b128 v[88:91], v86
	ds_read_b128 v[92:95], v87 offset:16384
	ds_read_b128 v[96:99], v87 offset:20480
	ds_read_b128 v[120:123], v86 offset:4096
	s_waitcnt vmcnt(0)
	s_waitcnt vmcnt(0) lgkmcnt(0)
	s_barrier
	v_mfma_f32_32x32x16_bf16 v[48:63], v[88:91], v[92:95], v[48:63]
	v_mfma_f32_32x32x16_bf16 v[32:47], v[88:91], v[96:99], v[32:47]
	v_mfma_f32_32x32x16_bf16 v[16:31], v[120:123], v[92:95], v[16:31]
	v_mfma_f32_32x32x16_bf16 v[0:15], v[120:123], v[96:99], v[0:15]
	v_lshl_add_u64 v[88:89], v[64:65], 0, s[64:65]
	global_load_lds_dwordx4 v[88:89], off
	v_lshl_add_u64 v[88:89], v[66:67], 0, s[64:65]
	s_mov_b32 m0, s28
	v_lshl_add_u64 v[64:65], v[64:65], 0, s[66:67]
	global_load_lds_dwordx4 v[88:89], off
	v_lshl_add_u64 v[88:89], v[68:69], 0, s[64:65]
	s_mov_b32 m0, s29
	s_nop 0
	global_load_lds_dwordx4 v[88:89], off
	v_lshl_add_u64 v[88:89], v[70:71], 0, s[64:65]
	s_mov_b32 m0, s40
	s_nop 0
	global_load_lds_dwordx4 v[88:89], off
	v_lshl_add_u64 v[88:89], v[72:73], 0, s[64:65]
	s_mov_b32 m0, s41
	s_nop 0
	global_load_lds_dwordx4 v[88:89], off
	v_lshl_add_u64 v[88:89], v[74:75], 0, s[64:65]
	s_mov_b32 m0, s42
	s_nop 0
	global_load_lds_dwordx4 v[88:89], off
	v_lshl_add_u64 v[88:89], v[76:77], 0, s[64:65]
	s_mov_b32 m0, s43
	s_nop 0
	global_load_lds_dwordx4 v[88:89], off
	v_lshl_add_u64 v[88:89], v[78:79], 0, s[64:65]
	s_mov_b32 m0, s44
	s_nop 0
	global_load_lds_dwordx4 v[88:89], off
	ds_read_b128 v[88:91], v80 offset:32768
	ds_read_b128 v[92:95], v82 offset:49152
	ds_read_b128 v[96:99], v82 offset:53248
	s_waitcnt lgkmcnt(0)
	v_mfma_f32_32x32x16_bf16 v[48:63], v[88:91], v[92:95], v[48:63]
	s_mov_b32 m0, s20
	v_mfma_f32_32x32x16_bf16 v[32:47], v[88:91], v[96:99], v[32:47]
	ds_read_b128 v[88:91], v80 offset:36864
	s_waitcnt lgkmcnt(0)
	v_mfma_f32_32x32x16_bf16 v[16:31], v[88:91], v[92:95], v[16:31]
	v_mfma_f32_32x32x16_bf16 v[0:15], v[88:91], v[96:99], v[0:15]
	ds_read_b128 v[88:91], v81 offset:32768
	ds_read_b128 v[92:95], v83 offset:49152
	ds_read_b128 v[96:99], v83 offset:53248
	s_waitcnt lgkmcnt(0)
	v_mfma_f32_32x32x16_bf16 v[48:63], v[88:91], v[92:95], v[48:63]
	v_mfma_f32_32x32x16_bf16 v[32:47], v[88:91], v[96:99], v[32:47]
	ds_read_b128 v[88:91], v81 offset:36864
	s_waitcnt lgkmcnt(0)
	v_mfma_f32_32x32x16_bf16 v[16:31], v[88:91], v[92:95], v[16:31]
	v_mfma_f32_32x32x16_bf16 v[0:15], v[88:91], v[96:99], v[0:15]
	ds_read_b128 v[88:91], v84 offset:32768
	ds_read_b128 v[92:95], v85 offset:49152
	ds_read_b128 v[96:99], v85 offset:53248
	s_waitcnt lgkmcnt(0)
	v_mfma_f32_32x32x16_bf16 v[48:63], v[88:91], v[92:95], v[48:63]
	v_mfma_f32_32x32x16_bf16 v[32:47], v[88:91], v[96:99], v[32:47]
	ds_read_b128 v[88:91], v84 offset:36864
	s_waitcnt lgkmcnt(0)
	v_mfma_f32_32x32x16_bf16 v[16:31], v[88:91], v[92:95], v[16:31]
	v_mfma_f32_32x32x16_bf16 v[0:15], v[88:91], v[96:99], v[0:15]
	ds_read_b128 v[88:91], v86 offset:32768
	ds_read_b128 v[92:95], v87 offset:49152
	ds_read_b128 v[96:99], v87 offset:53248
	s_waitcnt lgkmcnt(0)
	v_mfma_f32_32x32x16_bf16 v[48:63], v[88:91], v[92:95], v[48:63]
	v_mfma_f32_32x32x16_bf16 v[32:47], v[88:91], v[96:99], v[32:47]
	ds_read_b128 v[88:91], v86 offset:36864
	s_waitcnt vmcnt(0)
	s_waitcnt vmcnt(0) lgkmcnt(0)
	s_barrier
; #define WAIT_V0() asm volatile("s_waitcnt vmcnt(0)" ::: "memory")
; DI void gemm_core(char* smem, int nk, const char* Ab, const char* Bb, const unsigned (&aoff)[4], const unsigned (&boff)[4],
;                   f32x16 (&acc)[2][2]) {
;     ...
;   for (int kt = 0; kt < nk; ++kt) {
;     const int cur = kt & 1;
;     if (kt + 1 < nk) stage(cur ^ 1, kt + 1);
;     const char* sb = smem + cur * STAGE_B;
; #pragma unroll
;     for (int ks = 0; ks < 4; ++ks) {
;       bf16x8 af[2], bfr[2];
; #pragma unroll
;       for (int mb = 0; mb < 2; ++mb) af[mb] = *(const bf16x8*)(sb + a_base + mb * 4096 + xo[ks]);
; #pragma unroll
;       for (int nb = 0; nb < 2; ++nb) bfr[nb] = *(const bf16x8*)(sb + b_base + nb * 4096 + xo[ks]);
; #pragma unroll
;       for (int mb = 0; mb < 2; ++mb)
; #pragma unroll
;         for (int nb = 0; nb < 2; ++nb)
;           acc[mb][nb] = __builtin_amdgcn_mfma_f32_32x32x16_bf16(af[mb], bfr[nb], acc[mb][nb], 0, 0, 0);
;     }
;     WAIT_V0();
;     __syncthreads();
;   }
; DI void phase_gemm_in(const Params& P, int layer, char* smem) {
;     ...
;     epi_foreach(acc, [&](int row, int col, float v) __attribute__((always_inline)) {
;       const int c = n0 + col;
;       Cs[row * 136 + col] = (c >= C_QI && c < C_CQ) ? f2h(v) : f2bf(v);
;     });
	global_load_lds_dwordx4 v[64:65], off
	v_lshl_add_u64 v[64:65], v[66:67], 0, s[66:67]
	s_mov_b32 m0, s21
	v_mfma_f32_32x32x16_bf16 v[16:31], v[88:91], v[92:95], v[16:31]
	global_load_lds_dwordx4 v[64:65], off
	v_lshl_add_u64 v[64:65], v[68:69], 0, s[66:67]
	s_mov_b32 m0, s22
	s_nop 0
	global_load_lds_dwordx4 v[64:65], off
	v_lshl_add_u64 v[64:65], v[70:71], 0, s[66:67]
	s_mov_b32 m0, s1
	v_mfma_f32_32x32x16_bf16 v[0:15], v[88:91], v[96:99], v[0:15]
	global_load_lds_dwordx4 v[64:65], off
	v_lshl_add_u64 v[64:65], v[72:73], 0, s[66:67]
	s_mov_b32 m0, s16
	v_mov_b32_e32 v96, v161
	global_load_lds_dwordx4 v[64:65], off
	v_lshl_add_u64 v[64:65], v[74:75], 0, s[66:67]
	s_mov_b32 m0, s17
	v_mov_b32_e32 v97, v161
	global_load_lds_dwordx4 v[64:65], off
	v_lshl_add_u64 v[64:65], v[76:77], 0, s[66:67]
	s_mov_b32 m0, s18
	s_add_i32 s1, s10, 0xfffffa00
	global_load_lds_dwordx4 v[64:65], off
	v_lshl_add_u64 v[64:65], v[78:79], 0, s[66:67]
	s_mov_b32 m0, s19
	s_nop 0
	global_load_lds_dwordx4 v[64:65], off
	ds_read_b128 v[64:67], v80
	ds_read_b128 v[68:71], v82 offset:16384
	ds_read_b128 v[72:75], v82 offset:20480
	s_waitcnt lgkmcnt(0)
	v_mfma_f32_32x32x16_bf16 v[48:63], v[64:67], v[68:71], v[48:63]
	v_mfma_f32_32x32x16_bf16 v[32:47], v[64:67], v[72:75], v[32:47]
	ds_read_b128 v[64:67], v80 offset:4096
	s_waitcnt lgkmcnt(0)
	v_mfma_f32_32x32x16_bf16 v[16:31], v[64:67], v[68:71], v[16:31]
	v_mfma_f32_32x32x16_bf16 v[0:15], v[64:67], v[72:75], v[0:15]
	ds_read_b128 v[64:67], v81
	ds_read_b128 v[68:71], v83 offset:16384
	ds_read_b128 v[72:75], v83 offset:20480
	s_waitcnt lgkmcnt(0)
	v_mfma_f32_32x32x16_bf16 v[48:63], v[64:67], v[68:71], v[48:63]
	v_mfma_f32_32x32x16_bf16 v[32:47], v[64:67], v[72:75], v[32:47]
	ds_read_b128 v[64:67], v81 offset:4096
	s_waitcnt lgkmcnt(0)
	v_mfma_f32_32x32x16_bf16 v[16:31], v[64:67], v[68:71], v[16:31]
	v_mfma_f32_32x32x16_bf16 v[0:15], v[64:67], v[72:75], v[0:15]
	ds_read_b128 v[64:67], v84
	ds_read_b128 v[68:71], v85 offset:16384
	ds_read_b128 v[72:75], v85 offset:20480
	s_waitcnt lgkmcnt(0)
	v_mfma_f32_32x32x16_bf16 v[48:63], v[64:67], v[68:71], v[48:63]
	v_mfma_f32_32x32x16_bf16 v[32:47], v[64:67], v[72:75], v[32:47]
	ds_read_b128 v[64:67], v84 offset:4096
	s_waitcnt lgkmcnt(0)
	v_mfma_f32_32x32x16_bf16 v[16:31], v[64:67], v[68:71], v[16:31]
	v_mfma_f32_32x32x16_bf16 v[0:15], v[64:67], v[72:75], v[0:15]
	ds_read_b128 v[64:67], v86
	ds_read_b128 v[68:71], v87 offset:16384
	ds_read_b128 v[72:75], v87 offset:20480
	ds_read_b128 v[120:123], v86 offset:4096
	s_waitcnt vmcnt(0)
	s_waitcnt vmcnt(0) lgkmcnt(0)
	s_barrier
	v_mfma_f32_32x32x16_bf16 v[48:63], v[64:67], v[68:71], v[48:63]
	v_mfma_f32_32x32x16_bf16 v[32:47], v[64:67], v[72:75], v[32:47]
	v_mfma_f32_32x32x16_bf16 v[16:31], v[120:123], v[68:71], v[16:31]
	v_mfma_f32_32x32x16_bf16 v[0:15], v[120:123], v[72:75], v[0:15]
	ds_read_b128 v[64:67], v80 offset:32768
	ds_read_b128 v[68:71], v82 offset:49152
	ds_read_b128 v[72:75], v82 offset:53248
	s_waitcnt lgkmcnt(1)
	v_mfma_f32_32x32x16_bf16 v[48:63], v[64:67], v[68:71], v[48:63]
	s_waitcnt lgkmcnt(0)
	v_mfma_f32_32x32x16_bf16 v[32:47], v[64:67], v[72:75], v[32:47]
	ds_read_b128 v[64:67], v80 offset:36864
	s_waitcnt lgkmcnt(0)
	v_mfma_f32_32x32x16_bf16 v[16:31], v[64:67], v[68:71], v[16:31]
	v_mfma_f32_32x32x16_bf16 v[0:15], v[64:67], v[72:75], v[0:15]
	ds_read_b128 v[64:67], v81 offset:32768
	ds_read_b128 v[68:71], v83 offset:49152
	ds_read_b128 v[72:75], v83 offset:53248
	s_waitcnt lgkmcnt(1)
	v_mfma_f32_32x32x16_bf16 v[48:63], v[64:67], v[68:71], v[48:63]
	s_waitcnt lgkmcnt(0)
	v_mfma_f32_32x32x16_bf16 v[32:47], v[64:67], v[72:75], v[32:47]
	ds_read_b128 v[64:67], v81 offset:36864
	s_waitcnt lgkmcnt(0)
	v_mfma_f32_32x32x16_bf16 v[16:31], v[64:67], v[68:71], v[16:31]
	ds_read_b128 v[68:71], v84 offset:32768
	ds_read_b128 v[76:79], v84 offset:36864
	v_mfma_f32_32x32x16_bf16 v[0:15], v[64:67], v[72:75], v[0:15]
	ds_read_b128 v[64:67], v85 offset:49152
	ds_read_b128 v[72:75], v85 offset:53248
	ds_read_b128 v[80:83], v86 offset:32768
	ds_read_b128 v[88:91], v86 offset:36864
	ds_read_b128 v[92:95], v87 offset:49152
	ds_read_b128 v[84:87], v87 offset:53248
	s_waitcnt vmcnt(0)
	s_waitcnt lgkmcnt(0)
	s_barrier
	v_mfma_f32_32x32x16_bf16 v[48:63], v[68:71], v[64:67], v[48:63]
	v_mfma_f32_32x32x16_bf16 v[48:63], v[80:83], v[92:95], v[48:63]
	v_mfma_f32_32x32x16_bf16 v[32:47], v[68:71], v[72:75], v[32:47]
	v_lshrrev_b32_e32 v69, 3, v96
	v_lshrrev_b32_e32 v68, 1, v97
	v_and_b32_e32 v69, 4, v69
	v_and_b32_e32 v70, 31, v96
	v_and_or_b32 v68, v68, s7, v69
	s_nop 5
	v_cvt_f16_f32_e32 v69, v48
	v_and_or_b32 v70, v97, 64, v70
	v_or_b32_e32 v71, s1, v70
	v_cmp_gt_u32_e64 s[40:41], s45, v71
	v_cvt_pk_bf16_f32 v48, v48, s0
	v_mfma_f32_32x32x16_bf16 v[16:31], v[76:79], v[64:67], v[16:31]
	v_cndmask_b32_e64 v69, v48, v69, s[40:41]
	v_mul_lo_u32 v48, v68, s97
	v_cvt_f16_f32_e32 v68, v49
	v_cvt_pk_bf16_f32 v49, v49, s0
	v_lshl_add_u32 v48, v70, 1, v48
	v_cvt_f16_f32_e32 v64, v51
	v_cndmask_b32_e64 v49, v49, v68, s[40:41]
	ds_write_b16 v48, v49 offset:272
	v_cvt_f16_f32_e32 v49, v50
	v_cvt_pk_bf16_f32 v50, v50, s0
	v_mfma_f32_32x32x16_bf16 v[0:15], v[76:79], v[72:75], v[0:15]
	ds_write_b16 v48, v69
	v_cndmask_b32_e64 v49, v50, v49, s[40:41]
	ds_write_b16 v48, v49 offset:544
	v_cvt_pk_bf16_f32 v49, v51, s0
	v_cndmask_b32_e64 v49, v49, v64, s[40:41]
	ds_write_b16 v48, v49 offset:816
	v_cvt_f16_f32_e32 v49, v52
	v_cvt_f16_f32_e32 v51, v53
	v_cvt_pk_bf16_f32 v50, v52, s0
	v_mfma_f32_32x32x16_bf16 v[32:47], v[80:83], v[84:87], v[32:47]
	v_cndmask_b32_e64 v49, v50, v49, s[40:41]
	v_cvt_f16_f32_e32 v50, v54
	ds_write_b16 v48, v49 offset:2176
; DI int ltid() { int t = threadIdx.x; asm volatile("" : "+v"(t)); return t; }
; template <class F>
; DI void epi_foreach(const f32x16 (&acc)[2][2], F f) {
;   const int lane = ltid() & 63, w = ltid() >> 6;
;   const int wm = w >> 1, wn = w & 1;
; #pragma unroll
;   for (int mb = 0; mb < 2; ++mb)
; #pragma unroll
;     for (int nb = 0; nb < 2; ++nb)
; #pragma unroll
;       for (int r = 0; r < 16; ++r) {
;         const int row = wm * 64 + mb * 32 + (r & 3) + 8 * (r >> 2) + 4 * (lane >> 5);
;         const int col = wn * 64 + nb * 32 + (lane & 31);
;         f(row, col, acc[mb][nb][r]);
;         if ((r & 7) == 7) __builtin_amdgcn_sched_barrier(0);
;       }
; }
; DI void phase_gemm_in(const Params& P, int layer, char* smem) {
;     ...
;     epi_foreach(acc, [&](int row, int col, float v) __attribute__((always_inline)) {
;       const int c = n0 + col;
;       Cs[row * 136 + col] = (c >= C_QI && c < C_CQ) ? f2h(v) : f2bf(v);
;     });
	v_cvt_pk_bf16_f32 v49, v53, s0
	v_cndmask_b32_e64 v49, v49, v51, s[40:41]
	v_cvt_f16_f32_e32 v51, v55
	ds_write_b16 v48, v49 offset:2448
	v_cvt_pk_bf16_f32 v49, v54, s0
	v_cndmask_b32_e64 v49, v49, v50, s[40:41]
	ds_write_b16 v48, v49 offset:2720
	v_cvt_pk_bf16_f32 v49, v55, s0
	v_cndmask_b32_e64 v49, v49, v51, s[40:41]
	v_mfma_f32_32x32x16_bf16 v[16:31], v[88:91], v[92:95], v[16:31]
	ds_write_b16 v48, v49 offset:2992
	v_mfma_f32_32x32x16_bf16 v[0:15], v[88:91], v[84:87], v[0:15]
	v_cvt_f16_f32_e32 v49, v56
	v_cvt_pk_bf16_f32 v50, v56, s0
	v_cndmask_b32_e64 v49, v50, v49, s[40:41]
	ds_write_b16 v48, v49 offset:4352
	v_cvt_f16_f32_e32 v49, v57
	v_cvt_pk_bf16_f32 v50, v57, s0
	v_cndmask_b32_e64 v49, v50, v49, s[40:41]
	ds_write_b16 v48, v49 offset:4624
	v_cvt_f16_f32_e32 v49, v58
	v_cvt_pk_bf16_f32 v50, v58, s0
	v_cndmask_b32_e64 v49, v50, v49, s[40:41]
	ds_write_b16 v48, v49 offset:4896
	v_cvt_f16_f32_e32 v49, v59
	v_cvt_pk_bf16_f32 v50, v59, s0
	v_cndmask_b32_e64 v49, v50, v49, s[40:41]
	ds_write_b16 v48, v49 offset:5168
	v_cvt_f16_f32_e32 v49, v60
	v_cvt_pk_bf16_f32 v50, v60, s0
	v_cndmask_b32_e64 v49, v50, v49, s[40:41]
	ds_write_b16 v48, v49 offset:6528
	v_cvt_f16_f32_e32 v49, v61
	v_cvt_pk_bf16_f32 v50, v61, s0
	v_cndmask_b32_e64 v49, v50, v49, s[40:41]
	ds_write_b16 v48, v49 offset:6800
	v_cvt_f16_f32_e32 v49, v62
	v_cvt_pk_bf16_f32 v50, v62, s0
	v_cndmask_b32_e64 v49, v50, v49, s[40:41]
	ds_write_b16 v48, v49 offset:7072
	v_cvt_f16_f32_e32 v49, v63
	v_cvt_pk_bf16_f32 v50, v63, s0
	v_cndmask_b32_e64 v49, v50, v49, s[40:41]
	ds_write_b16 v48, v49 offset:7344
	s_add_i32 s1, s10, 0xfffffa20
	v_or_b32_e32 v49, s1, v70
	v_cmp_gt_u32_e32 vcc, s45, v49
	v_cvt_f16_f32_e32 v49, v32
	v_cvt_pk_bf16_f32 v32, v32, s0
	v_cndmask_b32_e32 v32, v32, v49, vcc
	ds_write_b16 v48, v32 offset:64
	v_cvt_f16_f32_e32 v32, v33
	v_cvt_pk_bf16_f32 v33, v33, s0
	v_cndmask_b32_e32 v32, v33, v32, vcc
	ds_write_b16 v48, v32 offset:336
	v_cvt_f16_f32_e32 v32, v34
	v_cvt_pk_bf16_f32 v33, v34, s0
	v_cndmask_b32_e32 v32, v33, v32, vcc
	ds_write_b16 v48, v32 offset:608
	v_cvt_f16_f32_e32 v32, v35
	v_cvt_pk_bf16_f32 v33, v35, s0
	v_cndmask_b32_e32 v32, v33, v32, vcc
	ds_write_b16 v48, v32 offset:880
	v_cvt_f16_f32_e32 v32, v36
	v_cvt_pk_bf16_f32 v33, v36, s0
	v_cndmask_b32_e32 v32, v33, v32, vcc
	ds_write_b16 v48, v32 offset:2240
	v_cvt_f16_f32_e32 v32, v37
	v_cvt_pk_bf16_f32 v33, v37, s0
	v_cndmask_b32_e32 v32, v33, v32, vcc
	ds_write_b16 v48, v32 offset:2512
	v_cvt_f16_f32_e32 v32, v38
	v_cvt_pk_bf16_f32 v33, v38, s0
	v_cndmask_b32_e32 v32, v33, v32, vcc
	ds_write_b16 v48, v32 offset:2784
	v_cvt_f16_f32_e32 v32, v39
	v_cvt_pk_bf16_f32 v33, v39, s0
	v_cndmask_b32_e32 v32, v33, v32, vcc
	ds_write_b16 v48, v32 offset:3056
	v_cvt_f16_f32_e32 v32, v40
	v_cvt_pk_bf16_f32 v33, v40, s0
	v_cndmask_b32_e32 v32, v33, v32, vcc
	ds_write_b16 v48, v32 offset:4416
	v_cvt_f16_f32_e32 v32, v41
	v_cvt_pk_bf16_f32 v33, v41, s0
	v_cndmask_b32_e32 v32, v33, v32, vcc
	ds_write_b16 v48, v32 offset:4688
	v_cvt_f16_f32_e32 v32, v42
	v_cvt_pk_bf16_f32 v33, v42, s0
	v_cndmask_b32_e32 v32, v33, v32, vcc
	ds_write_b16 v48, v32 offset:4960
	v_cvt_f16_f32_e32 v32, v43
	v_cvt_pk_bf16_f32 v33, v43, s0
	v_cndmask_b32_e32 v32, v33, v32, vcc
	ds_write_b16 v48, v32 offset:5232
	v_cvt_f16_f32_e32 v32, v44
	v_cvt_pk_bf16_f32 v33, v44, s0
	v_cndmask_b32_e32 v32, v33, v32, vcc
	ds_write_b16 v48, v32 offset:6592
	v_cvt_f16_f32_e32 v32, v45
	v_cvt_pk_bf16_f32 v33, v45, s0
	v_cndmask_b32_e32 v32, v33, v32, vcc
	ds_write_b16 v48, v32 offset:6864
	v_cvt_f16_f32_e32 v32, v46
	v_cvt_pk_bf16_f32 v33, v46, s0
	v_cndmask_b32_e32 v32, v33, v32, vcc
	ds_write_b16 v48, v32 offset:7136
	v_cvt_f16_f32_e32 v32, v47
	v_cvt_pk_bf16_f32 v33, v47, s0
	v_cndmask_b32_e32 v32, v33, v32, vcc
	ds_write_b16 v48, v32 offset:7408
	v_cvt_f16_f32_e32 v32, v16
	v_cvt_pk_bf16_f32 v16, v16, s0
	v_cndmask_b32_e64 v16, v16, v32, s[40:41]
	ds_write_b16 v48, v16 offset:8704
	v_cvt_f16_f32_e32 v16, v17
	v_cvt_pk_bf16_f32 v17, v17, s0
	v_cndmask_b32_e64 v16, v17, v16, s[40:41]
	ds_write_b16 v48, v16 offset:8976
	v_cvt_f16_f32_e32 v16, v18
	v_cvt_pk_bf16_f32 v17, v18, s0
	v_cndmask_b32_e64 v16, v17, v16, s[40:41]
	ds_write_b16 v48, v16 offset:9248
	v_cvt_f16_f32_e32 v16, v19
	v_cvt_pk_bf16_f32 v17, v19, s0
	v_cndmask_b32_e64 v16, v17, v16, s[40:41]
	ds_write_b16 v48, v16 offset:9520
	v_cvt_f16_f32_e32 v16, v20
	v_cvt_pk_bf16_f32 v17, v20, s0
	v_cndmask_b32_e64 v16, v17, v16, s[40:41]
	ds_write_b16 v48, v16 offset:10880
	v_cvt_f16_f32_e32 v16, v21
	v_cvt_pk_bf16_f32 v17, v21, s0
	v_cndmask_b32_e64 v16, v17, v16, s[40:41]
	ds_write_b16 v48, v16 offset:11152
	v_cvt_f16_f32_e32 v16, v22
	v_cvt_pk_bf16_f32 v17, v22, s0
	v_cndmask_b32_e64 v16, v17, v16, s[40:41]
	ds_write_b16 v48, v16 offset:11424
	v_cvt_f16_f32_e32 v16, v23
	v_cvt_pk_bf16_f32 v17, v23, s0
	v_cndmask_b32_e64 v16, v17, v16, s[40:41]
	ds_write_b16 v48, v16 offset:11696
	v_cvt_f16_f32_e32 v16, v24
	v_cvt_pk_bf16_f32 v17, v24, s0
	v_cndmask_b32_e64 v16, v17, v16, s[40:41]
	ds_write_b16 v48, v16 offset:13056
	v_cvt_f16_f32_e32 v16, v25
	v_cvt_pk_bf16_f32 v17, v25, s0
	v_cndmask_b32_e64 v16, v17, v16, s[40:41]
	ds_write_b16 v48, v16 offset:13328
	v_cvt_f16_f32_e32 v16, v26
	v_cvt_pk_bf16_f32 v17, v26, s0
; DI int ltid() { int t = threadIdx.x; asm volatile("" : "+v"(t)); return t; }
; template <class F>
; DI void epi_foreach(const f32x16 (&acc)[2][2], F f) {
;     ...
;         const int row = wm * 64 + mb * 32 + (r & 3) + 8 * (r >> 2) + 4 * (lane >> 5);
;         const int col = wn * 64 + nb * 32 + (lane & 31);
;         f(row, col, acc[mb][nb][r]);
;         if ((r & 7) == 7) __builtin_amdgcn_sched_barrier(0);
;       }
; }
; DI void store_tile16(const unsigned short* Cs, unsigned short* dst, int ldd) {
;   const int tid = ltid();
; #pragma unroll
;   for (int i = 0; i < 8; ++i) {
;     const int idx = tid + 256 * i;
;     const int row = idx >> 4, c8 = (idx & 15) * 8;
;     *(u32x4*)(dst + (size_t)row * ldd + c8) = *(const u32x4*)(Cs + row * 136 + c8);
;   }
; }
; DI void phase_gemm_in(const Params& P, int layer, char* smem) {
;     ...
;       Cs[row * 136 + col] = (c >= C_QI && c < C_CQ) ? f2h(v) : f2bf(v);
;     });
;     __syncthreads();
;     store_tile16(Cs, Z + (size_t)m0 * ZLD + n0, ZLD);
;     __syncthreads();
	v_cndmask_b32_e64 v16, v17, v16, s[40:41]
	ds_write_b16 v48, v16 offset:13600
	v_cvt_f16_f32_e32 v16, v27
	v_cvt_pk_bf16_f32 v17, v27, s0
	v_cndmask_b32_e64 v16, v17, v16, s[40:41]
	ds_write_b16 v48, v16 offset:13872
	v_cvt_f16_f32_e32 v16, v28
	v_cvt_pk_bf16_f32 v17, v28, s0
	v_cndmask_b32_e64 v16, v17, v16, s[40:41]
	ds_write_b16 v48, v16 offset:15232
	v_cvt_f16_f32_e32 v16, v29
	v_cvt_pk_bf16_f32 v17, v29, s0
	v_cndmask_b32_e64 v16, v17, v16, s[40:41]
	ds_write_b16 v48, v16 offset:15504
	v_cvt_f16_f32_e32 v16, v30
	v_cvt_pk_bf16_f32 v17, v30, s0
	v_cndmask_b32_e64 v16, v17, v16, s[40:41]
	ds_write_b16 v48, v16 offset:15776
	v_cvt_f16_f32_e32 v16, v31
	v_cvt_pk_bf16_f32 v17, v31, s0
	v_cndmask_b32_e64 v16, v17, v16, s[40:41]
	ds_write_b16 v48, v16 offset:16048
	v_cvt_f16_f32_e32 v16, v0
	v_cvt_pk_bf16_f32 v0, v0, s0
	v_cndmask_b32_e32 v0, v0, v16, vcc
	ds_write_b16 v48, v0 offset:8768
	v_cvt_f16_f32_e32 v0, v1
	v_cvt_pk_bf16_f32 v1, v1, s0
	v_cndmask_b32_e32 v0, v1, v0, vcc
	ds_write_b16 v48, v0 offset:9040
	v_cvt_f16_f32_e32 v0, v2
	v_cvt_pk_bf16_f32 v1, v2, s0
	v_cndmask_b32_e32 v0, v1, v0, vcc
	ds_write_b16 v48, v0 offset:9312
	v_cvt_f16_f32_e32 v0, v3
	v_cvt_pk_bf16_f32 v1, v3, s0
	v_cndmask_b32_e32 v0, v1, v0, vcc
	ds_write_b16 v48, v0 offset:9584
	v_cvt_f16_f32_e32 v0, v4
	v_cvt_pk_bf16_f32 v1, v4, s0
	v_cndmask_b32_e32 v0, v1, v0, vcc
	ds_write_b16 v48, v0 offset:10944
	v_cvt_f16_f32_e32 v0, v5
	v_cvt_pk_bf16_f32 v1, v5, s0
	v_cndmask_b32_e32 v0, v1, v0, vcc
	ds_write_b16 v48, v0 offset:11216
	v_cvt_f16_f32_e32 v0, v6
	v_cvt_pk_bf16_f32 v1, v6, s0
	v_cndmask_b32_e32 v0, v1, v0, vcc
	ds_write_b16 v48, v0 offset:11488
	v_cvt_f16_f32_e32 v0, v7
	v_cvt_pk_bf16_f32 v1, v7, s0
	v_cndmask_b32_e32 v0, v1, v0, vcc
	ds_write_b16 v48, v0 offset:11760
	v_cvt_f16_f32_e32 v0, v8
	v_cvt_pk_bf16_f32 v1, v8, s0
	v_cndmask_b32_e32 v0, v1, v0, vcc
	ds_write_b16 v48, v0 offset:13120
	v_cvt_f16_f32_e32 v0, v9
	v_cvt_pk_bf16_f32 v1, v9, s0
	v_cndmask_b32_e32 v0, v1, v0, vcc
	ds_write_b16 v48, v0 offset:13392
	v_cvt_f16_f32_e32 v0, v10
	v_cvt_pk_bf16_f32 v1, v10, s0
	v_cndmask_b32_e32 v0, v1, v0, vcc
	ds_write_b16 v48, v0 offset:13664
	v_cvt_f16_f32_e32 v0, v11
	v_cvt_pk_bf16_f32 v1, v11, s0
	v_cndmask_b32_e32 v0, v1, v0, vcc
	ds_write_b16 v48, v0 offset:13936
	v_cvt_f16_f32_e32 v0, v12
	v_cvt_pk_bf16_f32 v1, v12, s0
	v_cndmask_b32_e32 v0, v1, v0, vcc
	ds_write_b16 v48, v0 offset:15296
	v_cvt_f16_f32_e32 v0, v13
	v_cvt_pk_bf16_f32 v1, v13, s0
	v_cndmask_b32_e32 v0, v1, v0, vcc
	ds_write_b16 v48, v0 offset:15568
	v_cvt_f16_f32_e32 v0, v14
	v_cvt_pk_bf16_f32 v1, v14, s0
	v_cndmask_b32_e32 v0, v1, v0, vcc
	ds_write_b16 v48, v0 offset:15840
	v_cvt_f16_f32_e32 v0, v15
	v_cvt_pk_bf16_f32 v1, v15, s0
	v_cndmask_b32_e32 v0, v1, v0, vcc
	ds_write_b16 v48, v0 offset:16112
	s_mul_i32 s15, s15, 0xb0000
	s_mul_hi_i32 s0, s0, 0x1600
	s_add_u32 s15, s86, s15
	s_addc_u32 s16, s87, s0
	s_lshl_b64 s[0:1], s[10:11], 1
	v_mov_b32_e32 v8, v161
	s_waitcnt lgkmcnt(0)
	s_barrier
	s_add_u32 s0, s15, s0
	s_addc_u32 s1, s16, s1
	v_lshlrev_b32_e32 v0, 4, v8
	v_and_b32_e32 v136, 0xf0, v0
	v_ashrrev_i32_e32 v6, 4, v8
	v_lshl_add_u64 v[4:5], s[0:1], 0, v[136:137]
	v_mad_u64_u32 v[0:1], s[0:1], v6, s97, v[136:137]
	ds_read_b128 v[0:3], v0
	v_mad_i64_i32 v[6:7], s[0:1], v6, s33, v[4:5]
	s_add_i32 s14, s14, s70
	s_add_i32 s13, s13, s3
	s_waitcnt lgkmcnt(0)
	global_store_dwordx4 v[6:7], v[0:3], off
	s_cmpk_gt_i32 s14, 0x15ff
	s_nop 0
	v_add_u32_e32 v0, 0x100, v8
	v_ashrrev_i32_e32 v6, 4, v0
	v_mad_u64_u32 v[0:1], s[0:1], v6, s97, v[136:137]
	ds_read_b128 v[0:3], v0
	v_mad_i64_i32 v[6:7], s[0:1], v6, s33, v[4:5]
	s_waitcnt lgkmcnt(0)
	global_store_dwordx4 v[6:7], v[0:3], off
	s_nop 1
	v_add_u32_e32 v0, 0x200, v8
	v_ashrrev_i32_e32 v6, 4, v0
	v_mad_u64_u32 v[0:1], s[0:1], v6, s97, v[136:137]
	ds_read_b128 v[0:3], v0
	v_mad_i64_i32 v[6:7], s[0:1], v6, s33, v[4:5]
	s_waitcnt lgkmcnt(0)
	global_store_dwordx4 v[6:7], v[0:3], off
	s_nop 1
	v_add_u32_e32 v0, 0x300, v8
	v_ashrrev_i32_e32 v6, 4, v0
	v_mad_u64_u32 v[0:1], s[0:1], v6, s97, v[136:137]
	ds_read_b128 v[0:3], v0
	v_mad_i64_i32 v[6:7], s[0:1], v6, s33, v[4:5]
	s_waitcnt lgkmcnt(0)
	global_store_dwordx4 v[6:7], v[0:3], off
	s_nop 1
	v_add_u32_e32 v0, 0x400, v8
	v_ashrrev_i32_e32 v6, 4, v0
	v_mad_u64_u32 v[0:1], s[0:1], v6, s97, v[136:137]
	ds_read_b128 v[0:3], v0
	v_mad_i64_i32 v[6:7], s[0:1], v6, s33, v[4:5]
	s_waitcnt lgkmcnt(0)
	global_store_dwordx4 v[6:7], v[0:3], off
	s_nop 1
	v_add_u32_e32 v0, 0x500, v8
	v_ashrrev_i32_e32 v6, 4, v0
	v_mad_u64_u32 v[0:1], s[0:1], v6, s97, v[136:137]
	ds_read_b128 v[0:3], v0
	v_mad_i64_i32 v[6:7], s[0:1], v6, s33, v[4:5]
	s_waitcnt lgkmcnt(0)
	global_store_dwordx4 v[6:7], v[0:3], off
	s_nop 1
	v_add_u32_e32 v0, 0x600, v8
	v_ashrrev_i32_e32 v6, 4, v0
	v_mad_u64_u32 v[0:1], s[0:1], v6, s97, v[136:137]
	ds_read_b128 v[0:3], v0
	v_mad_i64_i32 v[6:7], s[0:1], v6, s33, v[4:5]
	s_waitcnt lgkmcnt(0)
	global_store_dwordx4 v[6:7], v[0:3], off
	s_nop 1
	v_add_u32_e32 v0, 0x700, v8
	v_ashrrev_i32_e32 v6, 4, v0
	v_mad_u64_u32 v[0:1], s[0:1], v6, s97, v[136:137]
	ds_read_b128 v[0:3], v0
	v_mad_i64_i32 v[4:5], s[0:1], v6, s33, v[4:5]
	s_waitcnt lgkmcnt(0)
	global_store_dwordx4 v[4:5], v[0:3], off
	s_barrier
	s_cbranch_scc0 .LBB0_436
